# v4 + K-loop LDS-DMA loads use SGPR-base (saddr) addressing: per-load 64-bit VALU address adds removed in 10 GEMM loops
# speedup vs baseline: 1.0037x; 1.0037x over previous
; #define PG8_STAGE(bufoff, gbase, voff) do { _Pragma("unroll") for (int _i = 0; _i < 2; ++_i) \
;         __builtin_amdgcn_global_load_lds((const unsigned*)((const char*)(gbase) + (voff)[_i]), (PG8_LAS unsigned*)(lds + (bufoff) + ldsw + _i * 8192), 16, 0, 0); } while (0)
; #define PG8_LDA(dst, b, h) do { _Pragma("unroll") for (int m = 0; m < 4; ++m) _Pragma("unroll") for (int k = 0; k < 2; ++k) dst[m][k] = *(const PG8_LAS bf16x8*)(lds + PG8_SA(b, h) + aoff + m * 2048 + k * 1024); } while (0)
; #define PG8_LDB(dst, b, h) do { _Pragma("unroll") for (int n = 0; n < 2; ++n) _Pragma("unroll") for (int k = 0; k < 2; ++k) dst[n][k] = *(const PG8_LAS bf16x8*)(lds + PG8_SB(b, h) + boff + n * 2048 + k * 1024); } while (0)
; #define PG8_MMA(ai, bj, At, Bt) do { __builtin_amdgcn_s_setprio(1); _Pragma("unroll") for (int m = 0; m < 4; ++m) _Pragma("unroll") for (int n = 0; n < 2; ++n) _Pragma("unroll") for (int k = 0; k < 2; ++k) \
;         acc[ai][bj][m][n] = __builtin_amdgcn_mfma_f32_16x16x32_bf16(Bt[n][k], At[m][k], acc[ai][bj][m][n], 0, 0, 0); __builtin_amdgcn_s_setprio(0); } while (0)
; #define PG8_WAIT_V(n) asm volatile("s_waitcnt vmcnt(" #n ")" ::: "memory")
; #define PG8_WAIT_L(n) asm volatile("s_waitcnt lgkmcnt(" #n ")" ::: "memory")
; #define PG8_BAR __builtin_amdgcn_s_barrier()
; #define PG8_SCHED __builtin_amdgcn_sched_barrier(0)
; template <class Epi>
; __device__ __forceinline__ void gemm_phase(PG8_LAS unsigned char* lds, PG8_LAS unsigned char* xl, const Gemm g, const Sched& S, const Epi& E, const int wid) {
;     ...
;             PG8_LDB(B0, 0, 0); PG8_LDB(B1, 0, 1); PG8_SCHED; PG8_LDA(At, 0, 0); PG8_STAGE(PG8_SA(1, 1), a1 + hstepA, voffA);
;             PG8_WAIT_V(8); PG8_WAIT_L(0); PG8_BAR; if (do0) { PG8_MMA(0, 0, At, B0); PG8_MMA(0, 1, At, B1); } PG8_BAR; PG8_SCHED;
;             PG8_LDA(At, 0, 1); PG8_STAGE(PG8_SB(0, 0), b2, voffB); PG8_STAGE(PG8_SB(0, 1), b2 + hstepB, voffB); PG8_STAGE(PG8_SA(0, 0), a2, voffA);
;             PG8_WAIT_V(8); PG8_WAIT_L(0); PG8_BAR; if (do1) { PG8_MMA(1, 0, At, B0); PG8_MMA(1, 1, At, B1); } PG8_BAR; PG8_SCHED;
.Ldefbar_skip_0:
	v_add_u32_e32 v141, s22, v128
	v_add_u32_e32 v226, s22, v130
	v_add_u32_e32 v227, s22, v132
	v_add_u32_e32 v228, s22, v134
.LBB0_220:
	s_add_u32 s52, s50, 0x100
	s_addc_u32 s53, s51, 0
	s_add_i32 s54, 0, 0x10000
	s_cmp_eq_u32 s43, 28
	s_cselect_b32 s59, s8, s53
	s_cselect_b32 s58, s9, s52
	v_add_u32_e32 v140, s54, v142
	s_cselect_b32 s57, s10, s21
	s_cselect_b32 s56, s11, s13
	s_add_i32 s55, 0, 0x14000
	ds_read_b128 v[144:147], v140
	ds_read_b128 v[148:151], v140 offset:1024
	ds_read_b128 v[152:155], v140 offset:2048
	ds_read_b128 v[156:159], v140 offset:3072
	v_add_u32_e32 v140, s55, v142
	ds_read_b128 v[160:163], v140
	ds_read_b128 v[164:167], v140 offset:1024
	ds_read_b128 v[168:171], v140 offset:2048
	ds_read_b128 v[172:175], v140 offset:3072
	s_add_i32 m0, s37, 0xc000
	ds_read_b128 v[176:179], v143
	ds_read_b128 v[180:183], v143 offset:1024
	ds_read_b128 v[184:187], v143 offset:2048
	ds_read_b128 v[188:191], v143 offset:3072
	ds_read_b128 v[210:213], v143 offset:4096
	ds_read_b128 v[214:217], v143 offset:5120
	ds_read_b128 v[218:221], v143 offset:6144
	ds_read_b128 v[222:225], v143 offset:7168
	global_load_lds_dwordx4 v136, s[50:51]
	s_add_i32 m0, s37, 0xe000
	s_nop 0
	global_load_lds_dwordx4 v138, s[50:51]
	s_waitcnt vmcnt(8)
	s_waitcnt lgkmcnt(0)
	s_setprio 1
	s_barrier
	v_mfma_f32_16x16x32_bf16 v[124:127], v[144:147], v[176:179], v[124:127]
	v_mfma_f32_16x16x32_bf16 v[120:123], v[152:155], v[176:179], v[120:123]
	v_mfma_f32_16x16x32_bf16 v[116:119], v[144:147], v[184:187], v[116:119]
	v_mfma_f32_16x16x32_bf16 v[108:111], v[152:155], v[184:187], v[108:111]
	v_mfma_f32_16x16x32_bf16 v[100:103], v[144:147], v[210:213], v[100:103]
	v_mfma_f32_16x16x32_bf16 v[92:95], v[152:155], v[210:213], v[92:95]
	v_mfma_f32_16x16x32_bf16 v[84:87], v[144:147], v[218:221], v[84:87]
	v_mfma_f32_16x16x32_bf16 v[76:79], v[152:155], v[218:221], v[76:79]
	v_mfma_f32_16x16x32_bf16 v[124:127], v[148:151], v[180:183], v[124:127]
	v_mfma_f32_16x16x32_bf16 v[120:123], v[156:159], v[180:183], v[120:123]
	v_mfma_f32_16x16x32_bf16 v[116:119], v[148:151], v[188:191], v[116:119]
	v_mfma_f32_16x16x32_bf16 v[108:111], v[156:159], v[188:191], v[108:111]
	v_mfma_f32_16x16x32_bf16 v[100:103], v[148:151], v[214:217], v[100:103]
	v_mfma_f32_16x16x32_bf16 v[92:95], v[156:159], v[214:217], v[92:95]
	v_mfma_f32_16x16x32_bf16 v[84:87], v[148:151], v[222:225], v[84:87]
	v_mfma_f32_16x16x32_bf16 v[76:79], v[156:159], v[222:225], v[76:79]
	s_setprio 0
	s_setprio 1
	v_mfma_f32_16x16x32_bf16 v[112:115], v[160:163], v[176:179], v[112:115]
	v_mfma_f32_16x16x32_bf16 v[104:107], v[168:171], v[176:179], v[104:107]
	v_mfma_f32_16x16x32_bf16 v[96:99], v[160:163], v[184:187], v[96:99]
	v_mfma_f32_16x16x32_bf16 v[88:91], v[168:171], v[184:187], v[88:91]
	v_mfma_f32_16x16x32_bf16 v[80:83], v[160:163], v[210:213], v[80:83]
	v_mfma_f32_16x16x32_bf16 v[72:75], v[168:171], v[210:213], v[72:75]
	v_mfma_f32_16x16x32_bf16 v[68:71], v[160:163], v[218:221], v[68:71]
	v_mfma_f32_16x16x32_bf16 v[64:67], v[168:171], v[218:221], v[64:67]
	v_mfma_f32_16x16x32_bf16 v[112:115], v[164:167], v[180:183], v[112:115]
	v_mfma_f32_16x16x32_bf16 v[104:107], v[172:175], v[180:183], v[104:107]
	v_mfma_f32_16x16x32_bf16 v[96:99], v[164:167], v[188:191], v[96:99]
	v_mfma_f32_16x16x32_bf16 v[88:91], v[172:175], v[188:191], v[88:91]
	v_mfma_f32_16x16x32_bf16 v[80:83], v[164:167], v[214:217], v[80:83]
	v_mfma_f32_16x16x32_bf16 v[72:75], v[172:175], v[214:217], v[72:75]
	v_mfma_f32_16x16x32_bf16 v[68:71], v[164:167], v[222:225], v[68:71]
	v_mfma_f32_16x16x32_bf16 v[64:67], v[172:175], v[222:225], v[64:67]
	s_barrier
	s_setprio 0
	s_add_i32 s50, s54, s29
	s_mov_b32 m0, s50
	ds_read_b128 v[176:179], v143 offset:16384
	ds_read_b128 v[180:183], v143 offset:17408
	ds_read_b128 v[184:187], v143 offset:18432
	ds_read_b128 v[188:191], v143 offset:19456
	ds_read_b128 v[210:213], v143 offset:20480
	ds_read_b128 v[214:217], v143 offset:21504
	ds_read_b128 v[218:221], v143 offset:22528
	ds_read_b128 v[222:225], v143 offset:23552
	global_load_lds_dwordx4 v132, s[56:57]
	s_add_i32 m0, s50, 0x2000
	s_add_u32 s50, s56, 0x80000
	s_addc_u32 s51, s57, 0
	s_add_i32 s54, s55, s29
	global_load_lds_dwordx4 v128, s[56:57]
	s_mov_b32 m0, s54
	s_nop 0
	global_load_lds_dwordx4 v132, s[50:51]
	s_add_i32 m0, s54, 0x2000
	s_nop 0
	global_load_lds_dwordx4 v128, s[50:51]
	s_mov_b32 m0, s37
	s_nop 0
	global_load_lds_dwordx4 v134, s[58:59]
	s_mov_b32 m0, s68
	s_nop 0
	global_load_lds_dwordx4 v130, s[58:59]
	s_waitcnt vmcnt(8)
	s_waitcnt lgkmcnt(0)
	s_setprio 1
	s_barrier
; #define PG8_STAGE(bufoff, gbase, voff) do { _Pragma("unroll") for (int _i = 0; _i < 2; ++_i) \
;         __builtin_amdgcn_global_load_lds((const unsigned*)((const char*)(gbase) + (voff)[_i]), (PG8_LAS unsigned*)(lds + (bufoff) + ldsw + _i * 8192), 16, 0, 0); } while (0)
; #define PG8_LDA(dst, b, h) do { _Pragma("unroll") for (int m = 0; m < 4; ++m) _Pragma("unroll") for (int k = 0; k < 2; ++k) dst[m][k] = *(const PG8_LAS bf16x8*)(lds + PG8_SA(b, h) + aoff + m * 2048 + k * 1024); } while (0)
; #define PG8_LDB(dst, b, h) do { _Pragma("unroll") for (int n = 0; n < 2; ++n) _Pragma("unroll") for (int k = 0; k < 2; ++k) dst[n][k] = *(const PG8_LAS bf16x8*)(lds + PG8_SB(b, h) + boff + n * 2048 + k * 1024); } while (0)
; #define PG8_MMA(ai, bj, At, Bt) do { __builtin_amdgcn_s_setprio(1); _Pragma("unroll") for (int m = 0; m < 4; ++m) _Pragma("unroll") for (int n = 0; n < 2; ++n) _Pragma("unroll") for (int k = 0; k < 2; ++k) \
;         acc[ai][bj][m][n] = __builtin_amdgcn_mfma_f32_16x16x32_bf16(Bt[n][k], At[m][k], acc[ai][bj][m][n], 0, 0, 0); __builtin_amdgcn_s_setprio(0); } while (0)
; #define PG8_WAIT_V(n) asm volatile("s_waitcnt vmcnt(" #n ")" ::: "memory")
; #define PG8_WAIT_L(n) asm volatile("s_waitcnt lgkmcnt(" #n ")" ::: "memory")
; #define PG8_BAR __builtin_amdgcn_s_barrier()
; #define PG8_SCHED __builtin_amdgcn_sched_barrier(0)
; template <class Epi>
; __device__ __forceinline__ void gemm_phase(PG8_LAS unsigned char* lds, PG8_LAS unsigned char* xl, const Gemm g, const Sched& S, const Epi& E, const int wid) {
;     ...
;             PG8_WAIT_V(8); PG8_WAIT_L(0); PG8_BAR; if (do1) { PG8_MMA(1, 0, At, B0); PG8_MMA(1, 1, At, B1); } PG8_BAR; PG8_SCHED;
;             PG8_LDB(B0, 1, 0); PG8_LDB(B1, 1, 1); PG8_SCHED; PG8_LDA(At, 1, 0); PG8_STAGE(PG8_SA(0, 1), a2 + hstepA, voffA);
;             PG8_WAIT_V(8); PG8_WAIT_L(0); PG8_BAR; if (do0) { PG8_MMA(0, 0, At, B0); PG8_MMA(0, 1, At, B1); } PG8_BAR; PG8_SCHED;
	v_mfma_f32_16x16x32_bf16 v[60:63], v[144:147], v[176:179], v[60:63]
	v_mfma_f32_16x16x32_bf16 v[56:59], v[152:155], v[176:179], v[56:59]
	v_mfma_f32_16x16x32_bf16 v[52:55], v[144:147], v[184:187], v[52:55]
	v_mfma_f32_16x16x32_bf16 v[44:47], v[152:155], v[184:187], v[44:47]
	v_mfma_f32_16x16x32_bf16 v[36:39], v[144:147], v[210:213], v[36:39]
	v_mfma_f32_16x16x32_bf16 v[28:31], v[152:155], v[210:213], v[28:31]
	v_mfma_f32_16x16x32_bf16 v[20:23], v[144:147], v[218:221], v[20:23]
	v_mfma_f32_16x16x32_bf16 v[12:15], v[152:155], v[218:221], v[12:15]
	v_mfma_f32_16x16x32_bf16 v[60:63], v[148:151], v[180:183], v[60:63]
	v_mfma_f32_16x16x32_bf16 v[56:59], v[156:159], v[180:183], v[56:59]
	v_mfma_f32_16x16x32_bf16 v[52:55], v[148:151], v[188:191], v[52:55]
	v_mfma_f32_16x16x32_bf16 v[44:47], v[156:159], v[188:191], v[44:47]
	v_mfma_f32_16x16x32_bf16 v[36:39], v[148:151], v[214:217], v[36:39]
	v_mfma_f32_16x16x32_bf16 v[28:31], v[156:159], v[214:217], v[28:31]
	v_mfma_f32_16x16x32_bf16 v[20:23], v[148:151], v[222:225], v[20:23]
	v_mfma_f32_16x16x32_bf16 v[12:15], v[156:159], v[222:225], v[12:15]
	s_setprio 0
	s_setprio 1
	v_mfma_f32_16x16x32_bf16 v[48:51], v[160:163], v[176:179], v[48:51]
	v_mfma_f32_16x16x32_bf16 v[40:43], v[168:171], v[176:179], v[40:43]
	v_mfma_f32_16x16x32_bf16 v[32:35], v[160:163], v[184:187], v[32:35]
	v_mfma_f32_16x16x32_bf16 v[24:27], v[168:171], v[184:187], v[24:27]
	v_mfma_f32_16x16x32_bf16 v[16:19], v[160:163], v[210:213], v[16:19]
	v_mfma_f32_16x16x32_bf16 v[8:11], v[168:171], v[210:213], v[8:11]
	v_mfma_f32_16x16x32_bf16 v[4:7], v[160:163], v[218:221], v[4:7]
	v_mfma_f32_16x16x32_bf16 v[0:3], v[168:171], v[218:221], v[0:3]
	v_mfma_f32_16x16x32_bf16 v[48:51], v[164:167], v[180:183], v[48:51]
	v_mfma_f32_16x16x32_bf16 v[40:43], v[172:175], v[180:183], v[40:43]
	v_mfma_f32_16x16x32_bf16 v[32:35], v[164:167], v[188:191], v[32:35]
	v_mfma_f32_16x16x32_bf16 v[24:27], v[172:175], v[188:191], v[24:27]
	v_mfma_f32_16x16x32_bf16 v[16:19], v[164:167], v[214:217], v[16:19]
	v_mfma_f32_16x16x32_bf16 v[8:11], v[172:175], v[214:217], v[8:11]
	v_mfma_f32_16x16x32_bf16 v[4:7], v[164:167], v[222:225], v[4:7]
	v_mfma_f32_16x16x32_bf16 v[0:3], v[172:175], v[222:225], v[0:3]
	s_barrier
	s_setprio 0
	s_add_i32 s54, 0, 0x18000
	s_add_i32 s55, 0, 0x1c000
	v_add_u32_e32 v156, s54, v142
	v_add_u32_e32 v172, s55, v142
	ds_read_b128 v[144:147], v156
	ds_read_b128 v[148:151], v156 offset:1024
	ds_read_b128 v[152:155], v156 offset:2048
	ds_read_b128 v[156:159], v156 offset:3072
	ds_read_b128 v[160:163], v172
	ds_read_b128 v[164:167], v172 offset:1024
	ds_read_b128 v[168:171], v172 offset:2048
	ds_read_b128 v[172:175], v172 offset:3072
	s_add_u32 s50, s58, 0x80000
	s_addc_u32 s51, s59, 0
	s_mov_b32 m0, s69
	ds_read_b128 v[176:179], v143 offset:32768
	ds_read_b128 v[180:183], v143 offset:33792
	ds_read_b128 v[184:187], v143 offset:34816
	ds_read_b128 v[188:191], v143 offset:35840
	ds_read_b128 v[210:213], v143 offset:36864
	ds_read_b128 v[214:217], v143 offset:37888
	ds_read_b128 v[218:221], v143 offset:38912
	ds_read_b128 v[222:225], v143 offset:39936
	global_load_lds_dwordx4 v134, s[50:51]
	s_mov_b32 m0, s70
	s_nop 0
	global_load_lds_dwordx4 v130, s[50:51]
	s_waitcnt vmcnt(8)
	s_waitcnt lgkmcnt(0)
	s_setprio 1
	s_barrier
	v_mfma_f32_16x16x32_bf16 v[124:127], v[144:147], v[176:179], v[124:127]
	v_mfma_f32_16x16x32_bf16 v[120:123], v[152:155], v[176:179], v[120:123]
	v_mfma_f32_16x16x32_bf16 v[116:119], v[144:147], v[184:187], v[116:119]
	v_mfma_f32_16x16x32_bf16 v[108:111], v[152:155], v[184:187], v[108:111]
	v_mfma_f32_16x16x32_bf16 v[100:103], v[144:147], v[210:213], v[100:103]
	v_mfma_f32_16x16x32_bf16 v[92:95], v[152:155], v[210:213], v[92:95]
	v_mfma_f32_16x16x32_bf16 v[84:87], v[144:147], v[218:221], v[84:87]
	v_mfma_f32_16x16x32_bf16 v[76:79], v[152:155], v[218:221], v[76:79]
	v_mfma_f32_16x16x32_bf16 v[124:127], v[148:151], v[180:183], v[124:127]
	v_mfma_f32_16x16x32_bf16 v[120:123], v[156:159], v[180:183], v[120:123]
	v_mfma_f32_16x16x32_bf16 v[116:119], v[148:151], v[188:191], v[116:119]
	v_mfma_f32_16x16x32_bf16 v[108:111], v[156:159], v[188:191], v[108:111]
	v_mfma_f32_16x16x32_bf16 v[100:103], v[148:151], v[214:217], v[100:103]
	v_mfma_f32_16x16x32_bf16 v[92:95], v[156:159], v[214:217], v[92:95]
	v_mfma_f32_16x16x32_bf16 v[84:87], v[148:151], v[222:225], v[84:87]
	v_mfma_f32_16x16x32_bf16 v[76:79], v[156:159], v[222:225], v[76:79]
	s_setprio 0
	s_setprio 1
	v_mfma_f32_16x16x32_bf16 v[112:115], v[160:163], v[176:179], v[112:115]
	v_mfma_f32_16x16x32_bf16 v[104:107], v[168:171], v[176:179], v[104:107]
	v_mfma_f32_16x16x32_bf16 v[96:99], v[160:163], v[184:187], v[96:99]
	v_mfma_f32_16x16x32_bf16 v[88:91], v[168:171], v[184:187], v[88:91]
	v_mfma_f32_16x16x32_bf16 v[80:83], v[160:163], v[210:213], v[80:83]
	v_mfma_f32_16x16x32_bf16 v[72:75], v[168:171], v[210:213], v[72:75]
	v_mfma_f32_16x16x32_bf16 v[68:71], v[160:163], v[218:221], v[68:71]
	v_mfma_f32_16x16x32_bf16 v[64:67], v[168:171], v[218:221], v[64:67]
	v_mfma_f32_16x16x32_bf16 v[112:115], v[164:167], v[180:183], v[112:115]
	v_mfma_f32_16x16x32_bf16 v[104:107], v[172:175], v[180:183], v[104:107]
	v_mfma_f32_16x16x32_bf16 v[96:99], v[164:167], v[188:191], v[96:99]
	v_mfma_f32_16x16x32_bf16 v[88:91], v[172:175], v[188:191], v[88:91]
	v_mfma_f32_16x16x32_bf16 v[80:83], v[164:167], v[214:217], v[80:83]
	v_mfma_f32_16x16x32_bf16 v[72:75], v[172:175], v[214:217], v[72:75]
	v_mfma_f32_16x16x32_bf16 v[68:71], v[164:167], v[222:225], v[68:71]
	v_mfma_f32_16x16x32_bf16 v[64:67], v[172:175], v[222:225], v[64:67]
	s_barrier
; #define PG8_STAGE(bufoff, gbase, voff) do { _Pragma("unroll") for (int _i = 0; _i < 2; ++_i) \
;         __builtin_amdgcn_global_load_lds((const unsigned*)((const char*)(gbase) + (voff)[_i]), (PG8_LAS unsigned*)(lds + (bufoff) + ldsw + _i * 8192), 16, 0, 0); } while (0)
; #define PG8_LDA(dst, b, h) do { _Pragma("unroll") for (int m = 0; m < 4; ++m) _Pragma("unroll") for (int k = 0; k < 2; ++k) dst[m][k] = *(const PG8_LAS bf16x8*)(lds + PG8_SA(b, h) + aoff + m * 2048 + k * 1024); } while (0)
; #define PG8_MMA(ai, bj, At, Bt) do { __builtin_amdgcn_s_setprio(1); _Pragma("unroll") for (int m = 0; m < 4; ++m) _Pragma("unroll") for (int n = 0; n < 2; ++n) _Pragma("unroll") for (int k = 0; k < 2; ++k) \
;         acc[ai][bj][m][n] = __builtin_amdgcn_mfma_f32_16x16x32_bf16(Bt[n][k], At[m][k], acc[ai][bj][m][n], 0, 0, 0); __builtin_amdgcn_s_setprio(0); } while (0)
; #define PG8_WAIT_V(n) asm volatile("s_waitcnt vmcnt(" #n ")" ::: "memory")
; #define PG8_WAIT_L(n) asm volatile("s_waitcnt lgkmcnt(" #n ")" ::: "memory")
; #define PG8_BAR __builtin_amdgcn_s_barrier()
; #define PG8_SCHED __builtin_amdgcn_sched_barrier(0)
; template <class Epi>
; __device__ __forceinline__ void gemm_phase(PG8_LAS unsigned char* lds, PG8_LAS unsigned char* xl, const Gemm g, const Sched& S, const Epi& E, const int wid) {
;     ...
;             PG8_LDA(At, 1, 1); PG8_STAGE(PG8_SB(1, 0), b3, voffB); PG8_STAGE(PG8_SB(1, 1), b3 + hstepB, voffB); PG8_STAGE(PG8_SA(1, 0), a3, voffA);
;             PG8_WAIT_V(8); PG8_WAIT_L(0); PG8_BAR; if (do1) { PG8_MMA(1, 0, At, B0); PG8_MMA(1, 1, At, B1); } PG8_BAR; PG8_SCHED;
;         }
	s_setprio 0
	s_add_i32 s50, s54, s29
	s_mov_b32 m0, s50
	ds_read_b128 v[176:179], v143 offset:49152
	ds_read_b128 v[180:183], v143 offset:50176
	ds_read_b128 v[184:187], v143 offset:51200
	ds_read_b128 v[188:191], v143 offset:52224
	ds_read_b128 v[210:213], v143 offset:53248
	ds_read_b128 v[214:217], v143 offset:54272
	ds_read_b128 v[218:221], v143 offset:55296
	ds_read_b128 v[222:225], v143 offset:56320
	global_load_lds_dwordx4 v227, s[56:57]
	s_add_i32 m0, s50, 0x2000
	s_add_u32 s50, s56, 0x80080
	global_load_lds_dwordx4 v141, s[56:57]
	s_addc_u32 s51, s57, 0
	s_add_i32 s54, s55, s29
	s_mov_b32 m0, s54
	s_nop 0
	global_load_lds_dwordx4 v132, s[50:51]
	s_add_i32 m0, s54, 0x2000
	s_nop 0
	global_load_lds_dwordx4 v128, s[50:51]
	s_mov_b32 m0, s77
	s_nop 0
	global_load_lds_dwordx4 v228, s[58:59]
	s_mov_b32 m0, s87
	s_nop 0
	global_load_lds_dwordx4 v226, s[58:59]
	s_waitcnt vmcnt(8)
	s_waitcnt lgkmcnt(0)
	s_setprio 1
	s_barrier
	v_mfma_f32_16x16x32_bf16 v[60:63], v[144:147], v[176:179], v[60:63]
	v_mfma_f32_16x16x32_bf16 v[56:59], v[152:155], v[176:179], v[56:59]
	v_mfma_f32_16x16x32_bf16 v[52:55], v[144:147], v[184:187], v[52:55]
	v_mfma_f32_16x16x32_bf16 v[44:47], v[152:155], v[184:187], v[44:47]
	v_mfma_f32_16x16x32_bf16 v[36:39], v[144:147], v[210:213], v[36:39]
	v_mfma_f32_16x16x32_bf16 v[28:31], v[152:155], v[210:213], v[28:31]
	v_mfma_f32_16x16x32_bf16 v[20:23], v[144:147], v[218:221], v[20:23]
	v_mfma_f32_16x16x32_bf16 v[12:15], v[152:155], v[218:221], v[12:15]
	v_mfma_f32_16x16x32_bf16 v[60:63], v[148:151], v[180:183], v[60:63]
	v_mfma_f32_16x16x32_bf16 v[56:59], v[156:159], v[180:183], v[56:59]
	v_mfma_f32_16x16x32_bf16 v[52:55], v[148:151], v[188:191], v[52:55]
	v_mfma_f32_16x16x32_bf16 v[44:47], v[156:159], v[188:191], v[44:47]
	v_mfma_f32_16x16x32_bf16 v[36:39], v[148:151], v[214:217], v[36:39]
	v_mfma_f32_16x16x32_bf16 v[28:31], v[156:159], v[214:217], v[28:31]
	v_mfma_f32_16x16x32_bf16 v[20:23], v[148:151], v[222:225], v[20:23]
	v_mfma_f32_16x16x32_bf16 v[12:15], v[156:159], v[222:225], v[12:15]
	s_setprio 0
	s_setprio 1
	v_mfma_f32_16x16x32_bf16 v[48:51], v[160:163], v[176:179], v[48:51]
	v_mfma_f32_16x16x32_bf16 v[40:43], v[168:171], v[176:179], v[40:43]
	v_mfma_f32_16x16x32_bf16 v[32:35], v[160:163], v[184:187], v[32:35]
	v_mfma_f32_16x16x32_bf16 v[24:27], v[168:171], v[184:187], v[24:27]
	v_mfma_f32_16x16x32_bf16 v[16:19], v[160:163], v[210:213], v[16:19]
	v_mfma_f32_16x16x32_bf16 v[8:11], v[168:171], v[210:213], v[8:11]
	v_mfma_f32_16x16x32_bf16 v[4:7], v[160:163], v[218:221], v[4:7]
	v_mfma_f32_16x16x32_bf16 v[0:3], v[168:171], v[218:221], v[0:3]
	v_mfma_f32_16x16x32_bf16 v[48:51], v[164:167], v[180:183], v[48:51]
	v_mfma_f32_16x16x32_bf16 v[40:43], v[172:175], v[180:183], v[40:43]
	v_mfma_f32_16x16x32_bf16 v[32:35], v[164:167], v[188:191], v[32:35]
	v_mfma_f32_16x16x32_bf16 v[24:27], v[172:175], v[188:191], v[24:27]
	v_mfma_f32_16x16x32_bf16 v[16:19], v[164:167], v[214:217], v[16:19]
	v_mfma_f32_16x16x32_bf16 v[8:11], v[172:175], v[214:217], v[8:11]
	v_mfma_f32_16x16x32_bf16 v[4:7], v[164:167], v[222:225], v[4:7]
	v_mfma_f32_16x16x32_bf16 v[0:3], v[172:175], v[222:225], v[0:3]
	s_barrier
	s_setprio 0
	s_add_i32 s43, s43, 2
	s_add_u32 s13, s13, 0x100
	s_addc_u32 s21, s21, 0
	s_cmp_gt_u32 s43, 29
	s_mov_b64 s[50:51], s[52:53]
	s_cbranch_scc0 .LBB0_220
	s_and_b64 vcc, exec, s[14:15]
	s_cbranch_vccz .LBB0_223
	s_barrier

; __device__ __forceinline__ const char* a_tile(const Gemm& g, const Unit& u) { return (const char*)(g.A + ((long)u.z1 * g.aS1 + (long)u.z2 * g.aS2 + (long)u.pm * BM * g.lda)); }
; __device__ __forceinline__ const char* b_tile(const Gemm& g, const Unit& u) { return (const char*)(g.Bt + ((long)u.z1 * g.bS1 + (long)u.z2 * g.bS2 + (long)u.pn * BM * g.ldb)); }
; __device__ __forceinline__ int lane_id_opq() { int l; asm volatile("v_mbcnt_lo_u32_b32 %0, -1, 0\n\tv_mbcnt_hi_u32_b32 %0, -1, %0" : "=v"(l)); return l; }
; #define PG8_LDA(dst, b, h) do { _Pragma("unroll") for (int m = 0; m < 4; ++m) _Pragma("unroll") for (int k = 0; k < 2; ++k) dst[m][k] = *(const PG8_LAS bf16x8*)(lds + PG8_SA(b, h) + aoff + m * 2048 + k * 1024); } while (0)
; template <class Epi>
; __device__ __forceinline__ void gemm_phase(PG8_LAS unsigned char* lds, PG8_LAS unsigned char* xl, const Gemm g, const Sched& S, const Epi& E, const int wid) {
;     ...
;         const bool has_next = S.next(ui + 1, nxt);
;         const char* nA = has_next ? a_tile(g, nxt) : cA; const char* nB = has_next ? b_tile(g, nxt) : cB;
;         for (int t = 0; t < nt; t += 2) {
;             const bool last = (t == nt - 2);
;             const bool do0 = !blkdiag_v<Epi> || t == 0, do1 = !blkdiag_v<Epi> || t != 0;
;             long j1 = 0, ja2 = 0, jb2 = 0;
;             if constexpr (Epi::MID) {
;                 if (t == g.tj) { const int lnM = lane_id_opq(); E.mid(acc, cur, wr, wc, lnM & 15, lnM >> 4); }
;                 if (t >= g.tj) j1 = g.jA;
;                 if (t + 2 >= g.tj) { ja2 = g.jA; jb2 = g.jB; } }
;             const char* a1 = cA + (size_t)(t + 1) * kstep + j1;
;             const char* a2 = last ? nA : cA + (size_t)(t + 2) * kstep + ja2; const char* b2 = last ? nB : cB + (size_t)(t + 2) * kstep + jb2;
;             const char* a3 = a2 + kstep; const char* b3 = b2 + kstep;
;             PG8_LDB(B0, 0, 0); PG8_LDB(B1, 0, 1); PG8_SCHED; PG8_LDA(At, 0, 0); PG8_STAGE(PG8_SA(1, 1), a1 + hstepA, voffA);
;             PG8_WAIT_V(8); PG8_WAIT_L(0); PG8_BAR; if (do0) { PG8_MMA(0, 0, At, B0); PG8_MMA(0, 1, At, B1); } PG8_BAR; PG8_SCHED;
;             PG8_LDA(At, 0, 1); PG8_STAGE(PG8_SB(0, 0), b2, voffB); PG8_STAGE(PG8_SB(0, 1), b2 + hstepB, voffB); PG8_STAGE(PG8_SA(0, 0), a2, voffA);
;             PG8_WAIT_V(8); PG8_WAIT_L(0); PG8_BAR; if (do1) { PG8_MMA(1, 0, At, B0); PG8_MMA(1, 1, At, B1); } PG8_BAR; PG8_SCHED;
.Ldefbar_skip_1:
	v_add_u32_e32 v157, s22, v140
	v_add_u32_e32 v234, s22, v142
	v_add_u32_e32 v235, s22, v144
	v_add_u32_e32 v236, s22, v146
.LBB0_238:
	s_add_u32 s30, s20, 0x100
	s_addc_u32 s31, s21, 0
	s_add_i32 s54, 0, 0x10000
	s_cmp_eq_u32 s62, 28
	s_cselect_b32 s47, s8, s31
	s_cselect_b32 s46, s9, s30
	v_add_u32_e32 v156, s54, v158
	s_cselect_b32 s45, s10, s57
	s_cselect_b32 s44, s11, s13
	s_add_i32 s55, 0, 0x14000
	ds_read_b128 v[18:21], v156
	ds_read_b128 v[22:25], v156 offset:1024
	ds_read_b128 v[160:163], v156 offset:2048
	ds_read_b128 v[164:167], v156 offset:3072
	v_add_u32_e32 v156, s55, v158
	ds_read_b128 v[168:171], v156
	ds_read_b128 v[172:175], v156 offset:1024
	ds_read_b128 v[176:179], v156 offset:2048
	ds_read_b128 v[180:183], v156 offset:3072
	s_add_i32 m0, s77, 0xc000
	ds_read_b128 v[184:187], v159
	ds_read_b128 v[188:191], v159 offset:1024
	ds_read_b128 v[210:213], v159 offset:2048
	ds_read_b128 v[214:217], v159 offset:3072
	ds_read_b128 v[218:221], v159 offset:4096
	ds_read_b128 v[222:225], v159 offset:5120
	ds_read_b128 v[226:229], v159 offset:6144
	ds_read_b128 v[230:233], v159 offset:7168
	global_load_lds_dwordx4 v148, s[20:21]
	s_add_i32 m0, s77, 0xe000
	s_nop 0
	global_load_lds_dwordx4 v150, s[20:21]
	s_waitcnt vmcnt(8)
	s_waitcnt lgkmcnt(0)
	s_setprio 1
	s_barrier
	v_mfma_f32_16x16x32_bf16 v[136:139], v[18:21], v[184:187], v[136:139]
	v_mfma_f32_16x16x32_bf16 v[132:135], v[160:163], v[184:187], v[132:135]
	v_mfma_f32_16x16x32_bf16 v[120:123], v[18:21], v[210:213], v[120:123]
	v_mfma_f32_16x16x32_bf16 v[116:119], v[160:163], v[210:213], v[116:119]
	v_mfma_f32_16x16x32_bf16 v[104:107], v[18:21], v[218:221], v[104:107]
	v_mfma_f32_16x16x32_bf16 v[100:103], v[160:163], v[218:221], v[100:103]
	v_mfma_f32_16x16x32_bf16 v[86:89], v[18:21], v[226:229], v[86:89]
	v_mfma_f32_16x16x32_bf16 v[82:85], v[160:163], v[226:229], v[82:85]
	v_mfma_f32_16x16x32_bf16 v[136:139], v[22:25], v[188:191], v[136:139]
	v_mfma_f32_16x16x32_bf16 v[132:135], v[164:167], v[188:191], v[132:135]
	v_mfma_f32_16x16x32_bf16 v[120:123], v[22:25], v[214:217], v[120:123]
	v_mfma_f32_16x16x32_bf16 v[116:119], v[164:167], v[214:217], v[116:119]
	v_mfma_f32_16x16x32_bf16 v[104:107], v[22:25], v[222:225], v[104:107]
	v_mfma_f32_16x16x32_bf16 v[100:103], v[164:167], v[222:225], v[100:103]
	v_mfma_f32_16x16x32_bf16 v[86:89], v[22:25], v[230:233], v[86:89]
	v_mfma_f32_16x16x32_bf16 v[82:85], v[164:167], v[230:233], v[82:85]
	s_setprio 0
	s_setprio 1
	v_mfma_f32_16x16x32_bf16 v[128:131], v[168:171], v[184:187], v[128:131]
	v_mfma_f32_16x16x32_bf16 v[124:127], v[176:179], v[184:187], v[124:127]
	v_mfma_f32_16x16x32_bf16 v[112:115], v[168:171], v[210:213], v[112:115]
	v_mfma_f32_16x16x32_bf16 v[108:111], v[176:179], v[210:213], v[108:111]
	v_mfma_f32_16x16x32_bf16 v[96:99], v[168:171], v[218:221], v[96:99]
	v_mfma_f32_16x16x32_bf16 v[92:95], v[176:179], v[218:221], v[92:95]
	v_mfma_f32_16x16x32_bf16 v[78:81], v[168:171], v[226:229], v[78:81]
	v_mfma_f32_16x16x32_bf16 v[74:77], v[176:179], v[226:229], v[74:77]
	v_mfma_f32_16x16x32_bf16 v[128:131], v[172:175], v[188:191], v[128:131]
	v_mfma_f32_16x16x32_bf16 v[124:127], v[180:183], v[188:191], v[124:127]
	v_mfma_f32_16x16x32_bf16 v[112:115], v[172:175], v[214:217], v[112:115]
	v_mfma_f32_16x16x32_bf16 v[108:111], v[180:183], v[214:217], v[108:111]
	v_mfma_f32_16x16x32_bf16 v[96:99], v[172:175], v[222:225], v[96:99]
	v_mfma_f32_16x16x32_bf16 v[92:95], v[180:183], v[222:225], v[92:95]
	v_mfma_f32_16x16x32_bf16 v[78:81], v[172:175], v[230:233], v[78:81]
	v_mfma_f32_16x16x32_bf16 v[74:77], v[180:183], v[230:233], v[74:77]
	s_barrier
	s_setprio 0
	s_add_i32 s20, s54, s29
	s_mov_b32 m0, s20
	ds_read_b128 v[184:187], v159 offset:16384
	ds_read_b128 v[188:191], v159 offset:17408
	ds_read_b128 v[210:213], v159 offset:18432
	ds_read_b128 v[214:217], v159 offset:19456
	ds_read_b128 v[218:221], v159 offset:20480
	ds_read_b128 v[222:225], v159 offset:21504
	ds_read_b128 v[226:229], v159 offset:22528
	ds_read_b128 v[230:233], v159 offset:23552
	global_load_lds_dwordx4 v142, s[44:45]
	s_add_i32 m0, s20, 0x2000
	s_add_u32 s20, s44, 0x80000
	s_addc_u32 s21, s45, 0
	s_add_i32 s54, s55, s29
	global_load_lds_dwordx4 v146, s[44:45]
	s_mov_b32 m0, s54
	s_nop 0
	global_load_lds_dwordx4 v142, s[20:21]
	s_add_i32 m0, s54, 0x2000
	s_nop 0
	global_load_lds_dwordx4 v146, s[20:21]
	s_mov_b32 m0, s77
	s_nop 0
	global_load_lds_dwordx4 v140, s[46:47]
	s_mov_b32 m0, s49
	s_nop 0
	global_load_lds_dwordx4 v144, s[46:47]
	s_waitcnt vmcnt(8)
	s_waitcnt lgkmcnt(0)
	s_setprio 1
	s_barrier
; #define PG8_STAGE(bufoff, gbase, voff) do { _Pragma("unroll") for (int _i = 0; _i < 2; ++_i) \
;         __builtin_amdgcn_global_load_lds((const unsigned*)((const char*)(gbase) + (voff)[_i]), (PG8_LAS unsigned*)(lds + (bufoff) + ldsw + _i * 8192), 16, 0, 0); } while (0)
; #define PG8_LDA(dst, b, h) do { _Pragma("unroll") for (int m = 0; m < 4; ++m) _Pragma("unroll") for (int k = 0; k < 2; ++k) dst[m][k] = *(const PG8_LAS bf16x8*)(lds + PG8_SA(b, h) + aoff + m * 2048 + k * 1024); } while (0)
; #define PG8_LDB(dst, b, h) do { _Pragma("unroll") for (int n = 0; n < 2; ++n) _Pragma("unroll") for (int k = 0; k < 2; ++k) dst[n][k] = *(const PG8_LAS bf16x8*)(lds + PG8_SB(b, h) + boff + n * 2048 + k * 1024); } while (0)
; #define PG8_MMA(ai, bj, At, Bt) do { __builtin_amdgcn_s_setprio(1); _Pragma("unroll") for (int m = 0; m < 4; ++m) _Pragma("unroll") for (int n = 0; n < 2; ++n) _Pragma("unroll") for (int k = 0; k < 2; ++k) \
;         acc[ai][bj][m][n] = __builtin_amdgcn_mfma_f32_16x16x32_bf16(Bt[n][k], At[m][k], acc[ai][bj][m][n], 0, 0, 0); __builtin_amdgcn_s_setprio(0); } while (0)
; #define PG8_WAIT_V(n) asm volatile("s_waitcnt vmcnt(" #n ")" ::: "memory")
; #define PG8_WAIT_L(n) asm volatile("s_waitcnt lgkmcnt(" #n ")" ::: "memory")
; #define PG8_BAR __builtin_amdgcn_s_barrier()
; #define PG8_SCHED __builtin_amdgcn_sched_barrier(0)
; template <class Epi>
; __device__ __forceinline__ void gemm_phase(PG8_LAS unsigned char* lds, PG8_LAS unsigned char* xl, const Gemm g, const Sched& S, const Epi& E, const int wid) {
;     ...
;             PG8_WAIT_V(8); PG8_WAIT_L(0); PG8_BAR; if (do1) { PG8_MMA(1, 0, At, B0); PG8_MMA(1, 1, At, B1); } PG8_BAR; PG8_SCHED;
;             PG8_LDB(B0, 1, 0); PG8_LDB(B1, 1, 1); PG8_SCHED; PG8_LDA(At, 1, 0); PG8_STAGE(PG8_SA(0, 1), a2 + hstepA, voffA);
;             PG8_WAIT_V(8); PG8_WAIT_L(0); PG8_BAR; if (do0) { PG8_MMA(0, 0, At, B0); PG8_MMA(0, 1, At, B1); } PG8_BAR; PG8_SCHED;
	v_mfma_f32_16x16x32_bf16 v[70:73], v[18:21], v[184:187], v[70:73]
	v_mfma_f32_16x16x32_bf16 v[66:69], v[160:163], v[184:187], v[66:69]
	v_mfma_f32_16x16x32_bf16 v[54:57], v[18:21], v[210:213], v[54:57]
	v_mfma_f32_16x16x32_bf16 v[50:53], v[160:163], v[210:213], v[50:53]
	v_mfma_f32_16x16x32_bf16 v[38:41], v[18:21], v[218:221], v[38:41]
	v_mfma_f32_16x16x32_bf16 v[34:37], v[160:163], v[218:221], v[34:37]
	v_mfma_f32_16x16x32_bf16 v[12:15], v[18:21], v[226:229], v[12:15]
	v_mfma_f32_16x16x32_bf16 v[8:11], v[160:163], v[226:229], v[8:11]
	v_mfma_f32_16x16x32_bf16 v[70:73], v[22:25], v[188:191], v[70:73]
	v_mfma_f32_16x16x32_bf16 v[66:69], v[164:167], v[188:191], v[66:69]
	v_mfma_f32_16x16x32_bf16 v[54:57], v[22:25], v[214:217], v[54:57]
	v_mfma_f32_16x16x32_bf16 v[50:53], v[164:167], v[214:217], v[50:53]
	v_mfma_f32_16x16x32_bf16 v[38:41], v[22:25], v[222:225], v[38:41]
	v_mfma_f32_16x16x32_bf16 v[34:37], v[164:167], v[222:225], v[34:37]
	v_mfma_f32_16x16x32_bf16 v[12:15], v[22:25], v[230:233], v[12:15]
	v_mfma_f32_16x16x32_bf16 v[8:11], v[164:167], v[230:233], v[8:11]
	s_setprio 0
	s_setprio 1
	v_mfma_f32_16x16x32_bf16 v[46:49], v[168:171], v[210:213], v[46:49]
	v_mfma_f32_16x16x32_bf16 v[42:45], v[176:179], v[210:213], v[42:45]
	v_mfma_f32_16x16x32_bf16 v[30:33], v[168:171], v[218:221], v[30:33]
	v_mfma_f32_16x16x32_bf16 v[26:29], v[176:179], v[218:221], v[26:29]
	v_mfma_f32_16x16x32_bf16 v[4:7], v[168:171], v[226:229], v[4:7]
	v_mfma_f32_16x16x32_bf16 v[0:3], v[176:179], v[226:229], v[0:3]
	v_mfma_f32_16x16x32_bf16 v[18:21], v[168:171], v[184:187], v[62:65]
	v_mfma_f32_16x16x32_bf16 v[22:25], v[176:179], v[184:187], v[58:61]
	v_mfma_f32_16x16x32_bf16 v[46:49], v[172:175], v[214:217], v[46:49]
	v_mfma_f32_16x16x32_bf16 v[42:45], v[180:183], v[214:217], v[42:45]
	v_mfma_f32_16x16x32_bf16 v[30:33], v[172:175], v[222:225], v[30:33]
	v_mfma_f32_16x16x32_bf16 v[26:29], v[180:183], v[222:225], v[26:29]
	v_mfma_f32_16x16x32_bf16 v[4:7], v[172:175], v[230:233], v[4:7]
	v_mfma_f32_16x16x32_bf16 v[0:3], v[180:183], v[230:233], v[0:3]
	v_mfma_f32_16x16x32_bf16 v[18:21], v[172:175], v[188:191], v[18:21]
	v_mfma_f32_16x16x32_bf16 v[22:25], v[180:183], v[188:191], v[22:25]
	s_barrier
	s_setprio 0
	s_add_i32 s54, 0, 0x18000
	s_add_i32 s55, 0, 0x1c000
	v_add_u32_e32 v164, s54, v158
	v_add_u32_e32 v180, s55, v158
	ds_read_b128 v[58:61], v164
	ds_read_b128 v[62:65], v164 offset:1024
	ds_read_b128 v[160:163], v164 offset:2048
	ds_read_b128 v[164:167], v164 offset:3072
	ds_read_b128 v[168:171], v180
	ds_read_b128 v[172:175], v180 offset:1024
	ds_read_b128 v[176:179], v180 offset:2048
	ds_read_b128 v[180:183], v180 offset:3072
	s_add_u32 s20, s46, 0x80000
	s_addc_u32 s21, s47, 0
	s_mov_b32 m0, s87
	ds_read_b128 v[184:187], v159 offset:32768
	ds_read_b128 v[188:191], v159 offset:33792
	ds_read_b128 v[210:213], v159 offset:34816
	ds_read_b128 v[214:217], v159 offset:35840
	ds_read_b128 v[218:221], v159 offset:36864
	ds_read_b128 v[222:225], v159 offset:37888
	ds_read_b128 v[226:229], v159 offset:38912
	ds_read_b128 v[230:233], v159 offset:39936
	global_load_lds_dwordx4 v140, s[20:21]
	s_mov_b32 m0, s88
	s_nop 0
	global_load_lds_dwordx4 v144, s[20:21]
	s_waitcnt vmcnt(8)
	s_waitcnt lgkmcnt(0)
	s_setprio 1
	s_barrier
	v_mfma_f32_16x16x32_bf16 v[136:139], v[58:61], v[184:187], v[136:139]
	v_mfma_f32_16x16x32_bf16 v[132:135], v[160:163], v[184:187], v[132:135]
	v_mfma_f32_16x16x32_bf16 v[120:123], v[58:61], v[210:213], v[120:123]
	v_mfma_f32_16x16x32_bf16 v[116:119], v[160:163], v[210:213], v[116:119]
	v_mfma_f32_16x16x32_bf16 v[104:107], v[58:61], v[218:221], v[104:107]
	v_mfma_f32_16x16x32_bf16 v[100:103], v[160:163], v[218:221], v[100:103]
	v_mfma_f32_16x16x32_bf16 v[86:89], v[58:61], v[226:229], v[86:89]
	v_mfma_f32_16x16x32_bf16 v[82:85], v[160:163], v[226:229], v[82:85]
	v_mfma_f32_16x16x32_bf16 v[136:139], v[62:65], v[188:191], v[136:139]
	v_mfma_f32_16x16x32_bf16 v[132:135], v[164:167], v[188:191], v[132:135]
	v_mfma_f32_16x16x32_bf16 v[120:123], v[62:65], v[214:217], v[120:123]
	v_mfma_f32_16x16x32_bf16 v[116:119], v[164:167], v[214:217], v[116:119]
	v_mfma_f32_16x16x32_bf16 v[104:107], v[62:65], v[222:225], v[104:107]
	v_mfma_f32_16x16x32_bf16 v[100:103], v[164:167], v[222:225], v[100:103]
	v_mfma_f32_16x16x32_bf16 v[86:89], v[62:65], v[230:233], v[86:89]
	v_mfma_f32_16x16x32_bf16 v[82:85], v[164:167], v[230:233], v[82:85]
	s_setprio 0
	s_setprio 1
	v_mfma_f32_16x16x32_bf16 v[128:131], v[168:171], v[184:187], v[128:131]
	v_mfma_f32_16x16x32_bf16 v[124:127], v[176:179], v[184:187], v[124:127]
	v_mfma_f32_16x16x32_bf16 v[112:115], v[168:171], v[210:213], v[112:115]
	v_mfma_f32_16x16x32_bf16 v[108:111], v[176:179], v[210:213], v[108:111]
	v_mfma_f32_16x16x32_bf16 v[96:99], v[168:171], v[218:221], v[96:99]
	v_mfma_f32_16x16x32_bf16 v[92:95], v[176:179], v[218:221], v[92:95]
	v_mfma_f32_16x16x32_bf16 v[78:81], v[168:171], v[226:229], v[78:81]
	v_mfma_f32_16x16x32_bf16 v[74:77], v[176:179], v[226:229], v[74:77]
	v_mfma_f32_16x16x32_bf16 v[128:131], v[172:175], v[188:191], v[128:131]
	v_mfma_f32_16x16x32_bf16 v[124:127], v[180:183], v[188:191], v[124:127]
	v_mfma_f32_16x16x32_bf16 v[112:115], v[172:175], v[214:217], v[112:115]
	v_mfma_f32_16x16x32_bf16 v[108:111], v[180:183], v[214:217], v[108:111]
	v_mfma_f32_16x16x32_bf16 v[96:99], v[172:175], v[222:225], v[96:99]
	v_mfma_f32_16x16x32_bf16 v[92:95], v[180:183], v[222:225], v[92:95]
	v_mfma_f32_16x16x32_bf16 v[78:81], v[172:175], v[230:233], v[78:81]
	v_mfma_f32_16x16x32_bf16 v[74:77], v[180:183], v[230:233], v[74:77]
	s_barrier
; #define PG8_STAGE(bufoff, gbase, voff) do { _Pragma("unroll") for (int _i = 0; _i < 2; ++_i) \
;         __builtin_amdgcn_global_load_lds((const unsigned*)((const char*)(gbase) + (voff)[_i]), (PG8_LAS unsigned*)(lds + (bufoff) + ldsw + _i * 8192), 16, 0, 0); } while (0)
; #define PG8_LDA(dst, b, h) do { _Pragma("unroll") for (int m = 0; m < 4; ++m) _Pragma("unroll") for (int k = 0; k < 2; ++k) dst[m][k] = *(const PG8_LAS bf16x8*)(lds + PG8_SA(b, h) + aoff + m * 2048 + k * 1024); } while (0)
; #define PG8_MMA(ai, bj, At, Bt) do { __builtin_amdgcn_s_setprio(1); _Pragma("unroll") for (int m = 0; m < 4; ++m) _Pragma("unroll") for (int n = 0; n < 2; ++n) _Pragma("unroll") for (int k = 0; k < 2; ++k) \
;         acc[ai][bj][m][n] = __builtin_amdgcn_mfma_f32_16x16x32_bf16(Bt[n][k], At[m][k], acc[ai][bj][m][n], 0, 0, 0); __builtin_amdgcn_s_setprio(0); } while (0)
; #define PG8_WAIT_V(n) asm volatile("s_waitcnt vmcnt(" #n ")" ::: "memory")
; #define PG8_WAIT_L(n) asm volatile("s_waitcnt lgkmcnt(" #n ")" ::: "memory")
; #define PG8_BAR __builtin_amdgcn_s_barrier()
; #define PG8_SCHED __builtin_amdgcn_sched_barrier(0)
; template <class Epi>
; __device__ __forceinline__ void gemm_phase(PG8_LAS unsigned char* lds, PG8_LAS unsigned char* xl, const Gemm g, const Sched& S, const Epi& E, const int wid) {
;     ...
;             PG8_LDA(At, 1, 1); PG8_STAGE(PG8_SB(1, 0), b3, voffB); PG8_STAGE(PG8_SB(1, 1), b3 + hstepB, voffB); PG8_STAGE(PG8_SA(1, 0), a3, voffA);
;             PG8_WAIT_V(8); PG8_WAIT_L(0); PG8_BAR; if (do1) { PG8_MMA(1, 0, At, B0); PG8_MMA(1, 1, At, B1); } PG8_BAR; PG8_SCHED;
;         }
	s_setprio 0
	s_add_i32 s20, s54, s29
	s_mov_b32 m0, s20
	ds_read_b128 v[184:187], v159 offset:49152
	ds_read_b128 v[188:191], v159 offset:50176
	ds_read_b128 v[210:213], v159 offset:51200
	ds_read_b128 v[214:217], v159 offset:52224
	ds_read_b128 v[218:221], v159 offset:53248
	ds_read_b128 v[222:225], v159 offset:54272
	ds_read_b128 v[226:229], v159 offset:55296
	ds_read_b128 v[230:233], v159 offset:56320
	global_load_lds_dwordx4 v234, s[44:45]
	s_add_i32 m0, s20, 0x2000
	s_add_u32 s20, s44, 0x80080
	global_load_lds_dwordx4 v236, s[44:45]
	s_addc_u32 s21, s45, 0
	s_add_i32 s44, s55, s29
	s_mov_b32 m0, s44
	s_nop 0
	global_load_lds_dwordx4 v142, s[20:21]
	s_add_i32 m0, s44, 0x2000
	s_nop 0
	global_load_lds_dwordx4 v146, s[20:21]
	s_mov_b32 m0, s91
	s_nop 0
	global_load_lds_dwordx4 v157, s[46:47]
	s_mov_b32 m0, s92
	s_nop 0
	global_load_lds_dwordx4 v235, s[46:47]
	s_waitcnt vmcnt(8)
	s_waitcnt lgkmcnt(0)
	s_setprio 1
	s_barrier
	v_mfma_f32_16x16x32_bf16 v[70:73], v[58:61], v[184:187], v[70:73]
	v_mfma_f32_16x16x32_bf16 v[66:69], v[160:163], v[184:187], v[66:69]
	v_mfma_f32_16x16x32_bf16 v[54:57], v[58:61], v[210:213], v[54:57]
	v_mfma_f32_16x16x32_bf16 v[50:53], v[160:163], v[210:213], v[50:53]
	v_mfma_f32_16x16x32_bf16 v[38:41], v[58:61], v[218:221], v[38:41]
	v_mfma_f32_16x16x32_bf16 v[34:37], v[160:163], v[218:221], v[34:37]
	v_mfma_f32_16x16x32_bf16 v[12:15], v[58:61], v[226:229], v[12:15]
	v_mfma_f32_16x16x32_bf16 v[8:11], v[160:163], v[226:229], v[8:11]
	v_mfma_f32_16x16x32_bf16 v[70:73], v[62:65], v[188:191], v[70:73]
	v_mfma_f32_16x16x32_bf16 v[66:69], v[164:167], v[188:191], v[66:69]
	v_mfma_f32_16x16x32_bf16 v[54:57], v[62:65], v[214:217], v[54:57]
	v_mfma_f32_16x16x32_bf16 v[50:53], v[164:167], v[214:217], v[50:53]
	v_mfma_f32_16x16x32_bf16 v[38:41], v[62:65], v[222:225], v[38:41]
	v_mfma_f32_16x16x32_bf16 v[34:37], v[164:167], v[222:225], v[34:37]
	v_mfma_f32_16x16x32_bf16 v[12:15], v[62:65], v[230:233], v[12:15]
	v_mfma_f32_16x16x32_bf16 v[8:11], v[164:167], v[230:233], v[8:11]
	s_setprio 0
	s_setprio 1
	v_mfma_f32_16x16x32_bf16 v[18:21], v[168:171], v[184:187], v[18:21]
	v_mfma_f32_16x16x32_bf16 v[62:65], v[172:175], v[188:191], v[18:21]
	v_mfma_f32_16x16x32_bf16 v[18:21], v[176:179], v[184:187], v[22:25]
	v_mfma_f32_16x16x32_bf16 v[58:61], v[180:183], v[188:191], v[18:21]
	v_mfma_f32_16x16x32_bf16 v[18:21], v[168:171], v[210:213], v[46:49]
	v_mfma_f32_16x16x32_bf16 v[46:49], v[172:175], v[214:217], v[18:21]
	v_mfma_f32_16x16x32_bf16 v[18:21], v[176:179], v[210:213], v[42:45]
	v_mfma_f32_16x16x32_bf16 v[42:45], v[180:183], v[214:217], v[18:21]
	v_mfma_f32_16x16x32_bf16 v[18:21], v[168:171], v[218:221], v[30:33]
	v_mfma_f32_16x16x32_bf16 v[30:33], v[172:175], v[222:225], v[18:21]
	v_mfma_f32_16x16x32_bf16 v[18:21], v[176:179], v[218:221], v[26:29]
	v_mfma_f32_16x16x32_bf16 v[4:7], v[168:171], v[226:229], v[4:7]
	v_mfma_f32_16x16x32_bf16 v[0:3], v[176:179], v[226:229], v[0:3]
	v_mfma_f32_16x16x32_bf16 v[26:29], v[180:183], v[222:225], v[18:21]
	v_mfma_f32_16x16x32_bf16 v[4:7], v[172:175], v[230:233], v[4:7]
	v_mfma_f32_16x16x32_bf16 v[0:3], v[180:183], v[230:233], v[0:3]
	s_barrier
	s_setprio 0
	s_add_i32 s62, s62, 2
	s_add_u32 s13, s13, 0x100
	s_addc_u32 s57, s57, 0
	s_cmp_gt_u32 s62, 29
	s_mov_b64 s[20:21], s[30:31]
	s_cbranch_scc0 .LBB0_238
	s_and_b64 vcc, exec, s[14:15]
	s_cbranch_vccz .LBB0_241
	s_barrier

; __device__ __forceinline__ const char* a_tile(const Gemm& g, const Unit& u) { return (const char*)(g.A + ((long)u.z1 * g.aS1 + (long)u.z2 * g.aS2 + (long)u.pm * BM * g.lda)); }
; __device__ __forceinline__ const char* b_tile(const Gemm& g, const Unit& u) { return (const char*)(g.Bt + ((long)u.z1 * g.bS1 + (long)u.z2 * g.bS2 + (long)u.pn * BM * g.ldb)); }
; __device__ __forceinline__ int lane_id_opq() { int l; asm volatile("v_mbcnt_lo_u32_b32 %0, -1, 0\n\tv_mbcnt_hi_u32_b32 %0, -1, %0" : "=v"(l)); return l; }
; #define PG8_LDA(dst, b, h) do { _Pragma("unroll") for (int m = 0; m < 4; ++m) _Pragma("unroll") for (int k = 0; k < 2; ++k) dst[m][k] = *(const PG8_LAS bf16x8*)(lds + PG8_SA(b, h) + aoff + m * 2048 + k * 1024); } while (0)
; template <class Epi>
; __device__ __forceinline__ void gemm_phase(PG8_LAS unsigned char* lds, PG8_LAS unsigned char* xl, const Gemm g, const Sched& S, const Epi& E, const int wid) {
;     ...
;         const bool has_next = S.next(ui + 1, nxt);
;         const char* nA = has_next ? a_tile(g, nxt) : cA; const char* nB = has_next ? b_tile(g, nxt) : cB;
;         for (int t = 0; t < nt; t += 2) {
;             const bool last = (t == nt - 2);
;             const bool do0 = !blkdiag_v<Epi> || t == 0, do1 = !blkdiag_v<Epi> || t != 0;
;             long j1 = 0, ja2 = 0, jb2 = 0;
;             if constexpr (Epi::MID) {
;                 if (t == g.tj) { const int lnM = lane_id_opq(); E.mid(acc, cur, wr, wc, lnM & 15, lnM >> 4); }
;                 if (t >= g.tj) j1 = g.jA;
;                 if (t + 2 >= g.tj) { ja2 = g.jA; jb2 = g.jB; } }
;             const char* a1 = cA + (size_t)(t + 1) * kstep + j1;
;             const char* a2 = last ? nA : cA + (size_t)(t + 2) * kstep + ja2; const char* b2 = last ? nB : cB + (size_t)(t + 2) * kstep + jb2;
;             const char* a3 = a2 + kstep; const char* b3 = b2 + kstep;
;             PG8_LDB(B0, 0, 0); PG8_LDB(B1, 0, 1); PG8_SCHED; PG8_LDA(At, 0, 0); PG8_STAGE(PG8_SA(1, 1), a1 + hstepA, voffA);
;             PG8_WAIT_V(8); PG8_WAIT_L(0); PG8_BAR; if (do0) { PG8_MMA(0, 0, At, B0); PG8_MMA(0, 1, At, B1); } PG8_BAR; PG8_SCHED;
;             PG8_LDA(At, 0, 1); PG8_STAGE(PG8_SB(0, 0), b2, voffB); PG8_STAGE(PG8_SB(0, 1), b2 + hstepB, voffB); PG8_STAGE(PG8_SA(0, 0), a2, voffA);
;             PG8_WAIT_V(8); PG8_WAIT_L(0); PG8_BAR; if (do1) { PG8_MMA(1, 0, At, B0); PG8_MMA(1, 1, At, B1); } PG8_BAR; PG8_SCHED;
.Ldefbar_skip_2:
	v_add_u32_e32 v190, s22, v128
	v_add_u32_e32 v191, s22, v130
	v_add_u32_e32 v226, s22, v132
	v_add_u32_e32 v227, s22, v134
.LBB0_408:
	s_add_u32 s76, s60, 0x100
	s_addc_u32 s77, s61, 0
	s_add_i32 s11, 0, 0x10000
	s_cmp_eq_u32 s10, 4
	s_cselect_b32 s41, s47, s77
	s_cselect_b32 s40, s46, s76
	s_cselect_b32 vcc_hi, s59, s9
	s_cselect_b32 vcc_lo, s58, s8
	s_add_i32 s21, 0, 0x14000
	v_add_u32_e32 v154, s11, v140
	v_add_u32_e32 v170, s21, v140
	ds_read_b128 v[142:145], v154
	ds_read_b128 v[146:149], v154 offset:1024
	ds_read_b128 v[150:153], v154 offset:2048
	ds_read_b128 v[154:157], v154 offset:3072
	ds_read_b128 v[158:161], v170
	ds_read_b128 v[162:165], v170 offset:1024
	ds_read_b128 v[166:169], v170 offset:2048
	ds_read_b128 v[170:173], v170 offset:3072
	s_add_i32 m0, s13, 0xc000
	ds_read_b128 v[174:177], v141
	ds_read_b128 v[178:181], v141 offset:1024
	ds_read_b128 v[182:185], v141 offset:2048
	ds_read_b128 v[186:189], v141 offset:3072
	ds_read_b128 v[210:213], v141 offset:4096
	ds_read_b128 v[214:217], v141 offset:5120
	ds_read_b128 v[218:221], v141 offset:6144
	ds_read_b128 v[222:225], v141 offset:7168
	global_load_lds_dwordx4 v136, s[60:61]
	s_add_i32 m0, s13, 0xe000
	s_nop 0
	global_load_lds_dwordx4 v138, s[60:61]
	s_waitcnt vmcnt(8)
	s_waitcnt lgkmcnt(0)
	s_setprio 1
	s_barrier
	v_mfma_f32_16x16x32_bf16 v[124:127], v[142:145], v[174:177], v[124:127]
	v_mfma_f32_16x16x32_bf16 v[120:123], v[150:153], v[174:177], v[120:123]
	v_mfma_f32_16x16x32_bf16 v[116:119], v[142:145], v[182:185], v[116:119]
	v_mfma_f32_16x16x32_bf16 v[108:111], v[150:153], v[182:185], v[108:111]
	v_mfma_f32_16x16x32_bf16 v[100:103], v[142:145], v[210:213], v[100:103]
	v_mfma_f32_16x16x32_bf16 v[92:95], v[150:153], v[210:213], v[92:95]
	v_mfma_f32_16x16x32_bf16 v[84:87], v[142:145], v[218:221], v[84:87]
	v_mfma_f32_16x16x32_bf16 v[76:79], v[150:153], v[218:221], v[76:79]
	v_mfma_f32_16x16x32_bf16 v[124:127], v[146:149], v[178:181], v[124:127]
	v_mfma_f32_16x16x32_bf16 v[120:123], v[154:157], v[178:181], v[120:123]
	v_mfma_f32_16x16x32_bf16 v[116:119], v[146:149], v[186:189], v[116:119]
	v_mfma_f32_16x16x32_bf16 v[108:111], v[154:157], v[186:189], v[108:111]
	v_mfma_f32_16x16x32_bf16 v[100:103], v[146:149], v[214:217], v[100:103]
	v_mfma_f32_16x16x32_bf16 v[92:95], v[154:157], v[214:217], v[92:95]
	v_mfma_f32_16x16x32_bf16 v[84:87], v[146:149], v[222:225], v[84:87]
	v_mfma_f32_16x16x32_bf16 v[76:79], v[154:157], v[222:225], v[76:79]
	s_setprio 0
	s_setprio 1
	v_mfma_f32_16x16x32_bf16 v[112:115], v[158:161], v[174:177], v[112:115]
	v_mfma_f32_16x16x32_bf16 v[104:107], v[166:169], v[174:177], v[104:107]
	v_mfma_f32_16x16x32_bf16 v[96:99], v[158:161], v[182:185], v[96:99]
	v_mfma_f32_16x16x32_bf16 v[88:91], v[166:169], v[182:185], v[88:91]
	v_mfma_f32_16x16x32_bf16 v[80:83], v[158:161], v[210:213], v[80:83]
	v_mfma_f32_16x16x32_bf16 v[72:75], v[166:169], v[210:213], v[72:75]
	v_mfma_f32_16x16x32_bf16 v[68:71], v[158:161], v[218:221], v[68:71]
	v_mfma_f32_16x16x32_bf16 v[64:67], v[166:169], v[218:221], v[64:67]
	v_mfma_f32_16x16x32_bf16 v[112:115], v[162:165], v[178:181], v[112:115]
	v_mfma_f32_16x16x32_bf16 v[104:107], v[170:173], v[178:181], v[104:107]
	v_mfma_f32_16x16x32_bf16 v[96:99], v[162:165], v[186:189], v[96:99]
	v_mfma_f32_16x16x32_bf16 v[88:91], v[170:173], v[186:189], v[88:91]
	v_mfma_f32_16x16x32_bf16 v[80:83], v[162:165], v[214:217], v[80:83]
	v_mfma_f32_16x16x32_bf16 v[72:75], v[170:173], v[214:217], v[72:75]
	v_mfma_f32_16x16x32_bf16 v[68:71], v[162:165], v[222:225], v[68:71]
	v_mfma_f32_16x16x32_bf16 v[64:67], v[170:173], v[222:225], v[64:67]
	s_barrier
	s_setprio 0
	s_add_i32 s11, s11, s29
	s_mov_b32 m0, s11
	ds_read_b128 v[174:177], v141 offset:16384
	ds_read_b128 v[178:181], v141 offset:17408
	ds_read_b128 v[182:185], v141 offset:18432
	ds_read_b128 v[186:189], v141 offset:19456
	ds_read_b128 v[210:213], v141 offset:20480
	ds_read_b128 v[214:217], v141 offset:21504
	ds_read_b128 v[218:221], v141 offset:22528
	ds_read_b128 v[222:225], v141 offset:23552
	global_load_lds_dwordx4 v132, vcc
	s_add_i32 m0, s11, 0x2000
	s_add_u32 s54, vcc_lo, 0x80000
	s_addc_u32 s55, vcc_hi, 0
	s_add_i32 s11, s21, s29
	global_load_lds_dwordx4 v128, vcc
	s_mov_b32 m0, s11
	s_nop 0
	global_load_lds_dwordx4 v132, s[54:55]
	s_add_i32 m0, s11, 0x2000
	s_nop 0
	global_load_lds_dwordx4 v128, s[54:55]
	s_mov_b32 m0, s13
	s_nop 0
	global_load_lds_dwordx4 v134, s[40:41]
	s_mov_b32 m0, s67
	s_nop 0
	global_load_lds_dwordx4 v130, s[40:41]
	s_waitcnt vmcnt(8)
	s_waitcnt lgkmcnt(0)
	s_setprio 1
	s_barrier
; #define PG8_STAGE(bufoff, gbase, voff) do { _Pragma("unroll") for (int _i = 0; _i < 2; ++_i) \
;         __builtin_amdgcn_global_load_lds((const unsigned*)((const char*)(gbase) + (voff)[_i]), (PG8_LAS unsigned*)(lds + (bufoff) + ldsw + _i * 8192), 16, 0, 0); } while (0)
; #define PG8_LDA(dst, b, h) do { _Pragma("unroll") for (int m = 0; m < 4; ++m) _Pragma("unroll") for (int k = 0; k < 2; ++k) dst[m][k] = *(const PG8_LAS bf16x8*)(lds + PG8_SA(b, h) + aoff + m * 2048 + k * 1024); } while (0)
; #define PG8_LDB(dst, b, h) do { _Pragma("unroll") for (int n = 0; n < 2; ++n) _Pragma("unroll") for (int k = 0; k < 2; ++k) dst[n][k] = *(const PG8_LAS bf16x8*)(lds + PG8_SB(b, h) + boff + n * 2048 + k * 1024); } while (0)
; #define PG8_MMA(ai, bj, At, Bt) do { __builtin_amdgcn_s_setprio(1); _Pragma("unroll") for (int m = 0; m < 4; ++m) _Pragma("unroll") for (int n = 0; n < 2; ++n) _Pragma("unroll") for (int k = 0; k < 2; ++k) \
;         acc[ai][bj][m][n] = __builtin_amdgcn_mfma_f32_16x16x32_bf16(Bt[n][k], At[m][k], acc[ai][bj][m][n], 0, 0, 0); __builtin_amdgcn_s_setprio(0); } while (0)
; #define PG8_WAIT_V(n) asm volatile("s_waitcnt vmcnt(" #n ")" ::: "memory")
; #define PG8_WAIT_L(n) asm volatile("s_waitcnt lgkmcnt(" #n ")" ::: "memory")
; #define PG8_BAR __builtin_amdgcn_s_barrier()
; #define PG8_SCHED __builtin_amdgcn_sched_barrier(0)
; template <class Epi>
; __device__ __forceinline__ void gemm_phase(PG8_LAS unsigned char* lds, PG8_LAS unsigned char* xl, const Gemm g, const Sched& S, const Epi& E, const int wid) {
;     ...
;             PG8_WAIT_V(8); PG8_WAIT_L(0); PG8_BAR; if (do1) { PG8_MMA(1, 0, At, B0); PG8_MMA(1, 1, At, B1); } PG8_BAR; PG8_SCHED;
;             PG8_LDB(B0, 1, 0); PG8_LDB(B1, 1, 1); PG8_SCHED; PG8_LDA(At, 1, 0); PG8_STAGE(PG8_SA(0, 1), a2 + hstepA, voffA);
;             PG8_WAIT_V(8); PG8_WAIT_L(0); PG8_BAR; if (do0) { PG8_MMA(0, 0, At, B0); PG8_MMA(0, 1, At, B1); } PG8_BAR; PG8_SCHED;
	v_mfma_f32_16x16x32_bf16 v[60:63], v[142:145], v[174:177], v[60:63]
	v_mfma_f32_16x16x32_bf16 v[56:59], v[150:153], v[174:177], v[56:59]
	v_mfma_f32_16x16x32_bf16 v[52:55], v[142:145], v[182:185], v[52:55]
	v_mfma_f32_16x16x32_bf16 v[44:47], v[150:153], v[182:185], v[44:47]
	v_mfma_f32_16x16x32_bf16 v[36:39], v[142:145], v[210:213], v[36:39]
	v_mfma_f32_16x16x32_bf16 v[28:31], v[150:153], v[210:213], v[28:31]
	v_mfma_f32_16x16x32_bf16 v[20:23], v[142:145], v[218:221], v[20:23]
	v_mfma_f32_16x16x32_bf16 v[12:15], v[150:153], v[218:221], v[12:15]
	v_mfma_f32_16x16x32_bf16 v[60:63], v[146:149], v[178:181], v[60:63]
	v_mfma_f32_16x16x32_bf16 v[56:59], v[154:157], v[178:181], v[56:59]
	v_mfma_f32_16x16x32_bf16 v[52:55], v[146:149], v[186:189], v[52:55]
	v_mfma_f32_16x16x32_bf16 v[44:47], v[154:157], v[186:189], v[44:47]
	v_mfma_f32_16x16x32_bf16 v[36:39], v[146:149], v[214:217], v[36:39]
	v_mfma_f32_16x16x32_bf16 v[28:31], v[154:157], v[214:217], v[28:31]
	v_mfma_f32_16x16x32_bf16 v[20:23], v[146:149], v[222:225], v[20:23]
	v_mfma_f32_16x16x32_bf16 v[12:15], v[154:157], v[222:225], v[12:15]
	s_setprio 0
	s_setprio 1
	v_mfma_f32_16x16x32_bf16 v[48:51], v[158:161], v[174:177], v[48:51]
	v_mfma_f32_16x16x32_bf16 v[40:43], v[166:169], v[174:177], v[40:43]
	v_mfma_f32_16x16x32_bf16 v[32:35], v[158:161], v[182:185], v[32:35]
	v_mfma_f32_16x16x32_bf16 v[24:27], v[166:169], v[182:185], v[24:27]
	v_mfma_f32_16x16x32_bf16 v[16:19], v[158:161], v[210:213], v[16:19]
	v_mfma_f32_16x16x32_bf16 v[8:11], v[166:169], v[210:213], v[8:11]
	v_mfma_f32_16x16x32_bf16 v[4:7], v[158:161], v[218:221], v[4:7]
	v_mfma_f32_16x16x32_bf16 v[0:3], v[166:169], v[218:221], v[0:3]
	v_mfma_f32_16x16x32_bf16 v[48:51], v[162:165], v[178:181], v[48:51]
	v_mfma_f32_16x16x32_bf16 v[40:43], v[170:173], v[178:181], v[40:43]
	v_mfma_f32_16x16x32_bf16 v[32:35], v[162:165], v[186:189], v[32:35]
	v_mfma_f32_16x16x32_bf16 v[24:27], v[170:173], v[186:189], v[24:27]
	v_mfma_f32_16x16x32_bf16 v[16:19], v[162:165], v[214:217], v[16:19]
	v_mfma_f32_16x16x32_bf16 v[8:11], v[170:173], v[214:217], v[8:11]
	v_mfma_f32_16x16x32_bf16 v[4:7], v[162:165], v[222:225], v[4:7]
	v_mfma_f32_16x16x32_bf16 v[0:3], v[170:173], v[222:225], v[0:3]
	s_barrier
	s_setprio 0
	s_add_i32 s11, 0, 0x18000
	s_add_i32 s21, 0, 0x1c000
	v_add_u32_e32 v154, s11, v140
	v_add_u32_e32 v170, s21, v140
	ds_read_b128 v[142:145], v154
	ds_read_b128 v[146:149], v154 offset:1024
	ds_read_b128 v[150:153], v154 offset:2048
	ds_read_b128 v[154:157], v154 offset:3072
	ds_read_b128 v[158:161], v170
	ds_read_b128 v[162:165], v170 offset:1024
	ds_read_b128 v[166:169], v170 offset:2048
	ds_read_b128 v[170:173], v170 offset:3072
	s_add_u32 s100, s40, 0x100000
	s_addc_u32 s101, s41, 0
	s_mov_b32 m0, s68
	ds_read_b128 v[174:177], v141 offset:32768
	ds_read_b128 v[178:181], v141 offset:33792
	ds_read_b128 v[182:185], v141 offset:34816
	ds_read_b128 v[186:189], v141 offset:35840
	ds_read_b128 v[210:213], v141 offset:36864
	ds_read_b128 v[214:217], v141 offset:37888
	ds_read_b128 v[218:221], v141 offset:38912
	ds_read_b128 v[222:225], v141 offset:39936
	global_load_lds_dwordx4 v134, s[100:101]
	s_mov_b32 m0, s69
	s_nop 0
	global_load_lds_dwordx4 v130, s[100:101]
	s_waitcnt vmcnt(8)
	s_waitcnt lgkmcnt(0)
	s_setprio 1
	s_barrier
	v_mfma_f32_16x16x32_bf16 v[124:127], v[142:145], v[174:177], v[124:127]
	v_mfma_f32_16x16x32_bf16 v[120:123], v[150:153], v[174:177], v[120:123]
	v_mfma_f32_16x16x32_bf16 v[116:119], v[142:145], v[182:185], v[116:119]
	v_mfma_f32_16x16x32_bf16 v[108:111], v[150:153], v[182:185], v[108:111]
	v_mfma_f32_16x16x32_bf16 v[100:103], v[142:145], v[210:213], v[100:103]
	v_mfma_f32_16x16x32_bf16 v[92:95], v[150:153], v[210:213], v[92:95]
	v_mfma_f32_16x16x32_bf16 v[84:87], v[142:145], v[218:221], v[84:87]
	v_mfma_f32_16x16x32_bf16 v[76:79], v[150:153], v[218:221], v[76:79]
	v_mfma_f32_16x16x32_bf16 v[124:127], v[146:149], v[178:181], v[124:127]
	v_mfma_f32_16x16x32_bf16 v[120:123], v[154:157], v[178:181], v[120:123]
	v_mfma_f32_16x16x32_bf16 v[116:119], v[146:149], v[186:189], v[116:119]
	v_mfma_f32_16x16x32_bf16 v[108:111], v[154:157], v[186:189], v[108:111]
	v_mfma_f32_16x16x32_bf16 v[100:103], v[146:149], v[214:217], v[100:103]
	v_mfma_f32_16x16x32_bf16 v[92:95], v[154:157], v[214:217], v[92:95]
	v_mfma_f32_16x16x32_bf16 v[84:87], v[146:149], v[222:225], v[84:87]
	v_mfma_f32_16x16x32_bf16 v[76:79], v[154:157], v[222:225], v[76:79]
	s_setprio 0
	s_setprio 1
	v_mfma_f32_16x16x32_bf16 v[112:115], v[158:161], v[174:177], v[112:115]
	v_mfma_f32_16x16x32_bf16 v[104:107], v[166:169], v[174:177], v[104:107]
	v_mfma_f32_16x16x32_bf16 v[96:99], v[158:161], v[182:185], v[96:99]
	v_mfma_f32_16x16x32_bf16 v[88:91], v[166:169], v[182:185], v[88:91]
	v_mfma_f32_16x16x32_bf16 v[80:83], v[158:161], v[210:213], v[80:83]
	v_mfma_f32_16x16x32_bf16 v[72:75], v[166:169], v[210:213], v[72:75]
	v_mfma_f32_16x16x32_bf16 v[68:71], v[158:161], v[218:221], v[68:71]
	v_mfma_f32_16x16x32_bf16 v[64:67], v[166:169], v[218:221], v[64:67]
	v_mfma_f32_16x16x32_bf16 v[112:115], v[162:165], v[178:181], v[112:115]
	v_mfma_f32_16x16x32_bf16 v[104:107], v[170:173], v[178:181], v[104:107]
	v_mfma_f32_16x16x32_bf16 v[96:99], v[162:165], v[186:189], v[96:99]
	v_mfma_f32_16x16x32_bf16 v[88:91], v[170:173], v[186:189], v[88:91]
	v_mfma_f32_16x16x32_bf16 v[80:83], v[162:165], v[214:217], v[80:83]
	v_mfma_f32_16x16x32_bf16 v[72:75], v[170:173], v[214:217], v[72:75]
	v_mfma_f32_16x16x32_bf16 v[68:71], v[162:165], v[222:225], v[68:71]
	v_mfma_f32_16x16x32_bf16 v[64:67], v[170:173], v[222:225], v[64:67]
	s_barrier
; #define PG8_STAGE(bufoff, gbase, voff) do { _Pragma("unroll") for (int _i = 0; _i < 2; ++_i) \
;         __builtin_amdgcn_global_load_lds((const unsigned*)((const char*)(gbase) + (voff)[_i]), (PG8_LAS unsigned*)(lds + (bufoff) + ldsw + _i * 8192), 16, 0, 0); } while (0)
; #define PG8_LDA(dst, b, h) do { _Pragma("unroll") for (int m = 0; m < 4; ++m) _Pragma("unroll") for (int k = 0; k < 2; ++k) dst[m][k] = *(const PG8_LAS bf16x8*)(lds + PG8_SA(b, h) + aoff + m * 2048 + k * 1024); } while (0)
; #define PG8_MMA(ai, bj, At, Bt) do { __builtin_amdgcn_s_setprio(1); _Pragma("unroll") for (int m = 0; m < 4; ++m) _Pragma("unroll") for (int n = 0; n < 2; ++n) _Pragma("unroll") for (int k = 0; k < 2; ++k) \
;         acc[ai][bj][m][n] = __builtin_amdgcn_mfma_f32_16x16x32_bf16(Bt[n][k], At[m][k], acc[ai][bj][m][n], 0, 0, 0); __builtin_amdgcn_s_setprio(0); } while (0)
; #define PG8_WAIT_V(n) asm volatile("s_waitcnt vmcnt(" #n ")" ::: "memory")
; #define PG8_WAIT_L(n) asm volatile("s_waitcnt lgkmcnt(" #n ")" ::: "memory")
; #define PG8_BAR __builtin_amdgcn_s_barrier()
; #define PG8_SCHED __builtin_amdgcn_sched_barrier(0)
; template <class Epi>
; __device__ __forceinline__ void gemm_phase(PG8_LAS unsigned char* lds, PG8_LAS unsigned char* xl, const Gemm g, const Sched& S, const Epi& E, const int wid) {
;     ...
;             PG8_LDA(At, 1, 1); PG8_STAGE(PG8_SB(1, 0), b3, voffB); PG8_STAGE(PG8_SB(1, 1), b3 + hstepB, voffB); PG8_STAGE(PG8_SA(1, 0), a3, voffA);
;             PG8_WAIT_V(8); PG8_WAIT_L(0); PG8_BAR; if (do1) { PG8_MMA(1, 0, At, B0); PG8_MMA(1, 1, At, B1); } PG8_BAR; PG8_SCHED;
;         }
	s_setprio 0
	s_add_i32 s11, s11, s29
	s_mov_b32 m0, s11
	ds_read_b128 v[174:177], v141 offset:49152
	ds_read_b128 v[178:181], v141 offset:50176
	ds_read_b128 v[182:185], v141 offset:51200
	ds_read_b128 v[186:189], v141 offset:52224
	ds_read_b128 v[210:213], v141 offset:53248
	ds_read_b128 v[214:217], v141 offset:54272
	ds_read_b128 v[218:221], v141 offset:55296
	ds_read_b128 v[222:225], v141 offset:56320
	global_load_lds_dwordx4 v226, vcc
	s_add_i32 m0, s11, 0x2000
	s_add_u32 s100, vcc_lo, 0x80080
	global_load_lds_dwordx4 v190, vcc
	s_addc_u32 s101, vcc_hi, 0
	s_add_i32 s11, s21, s29
	s_mov_b32 m0, s11
	s_nop 0
	global_load_lds_dwordx4 v132, s[100:101]
	s_add_i32 m0, s11, 0x2000
	s_nop 0
	global_load_lds_dwordx4 v128, s[100:101]
	s_mov_b32 m0, s88
	s_nop 0
	global_load_lds_dwordx4 v227, s[40:41]
	s_mov_b32 m0, s89
	s_nop 0
	global_load_lds_dwordx4 v191, s[40:41]
	s_waitcnt vmcnt(8)
	s_waitcnt lgkmcnt(0)
	s_setprio 1
	s_barrier
	v_mfma_f32_16x16x32_bf16 v[60:63], v[142:145], v[174:177], v[60:63]
	v_mfma_f32_16x16x32_bf16 v[56:59], v[150:153], v[174:177], v[56:59]
	v_mfma_f32_16x16x32_bf16 v[52:55], v[142:145], v[182:185], v[52:55]
	v_mfma_f32_16x16x32_bf16 v[44:47], v[150:153], v[182:185], v[44:47]
	v_mfma_f32_16x16x32_bf16 v[36:39], v[142:145], v[210:213], v[36:39]
	v_mfma_f32_16x16x32_bf16 v[28:31], v[150:153], v[210:213], v[28:31]
	v_mfma_f32_16x16x32_bf16 v[20:23], v[142:145], v[218:221], v[20:23]
	v_mfma_f32_16x16x32_bf16 v[12:15], v[150:153], v[218:221], v[12:15]
	v_mfma_f32_16x16x32_bf16 v[60:63], v[146:149], v[178:181], v[60:63]
	v_mfma_f32_16x16x32_bf16 v[56:59], v[154:157], v[178:181], v[56:59]
	v_mfma_f32_16x16x32_bf16 v[52:55], v[146:149], v[186:189], v[52:55]
	v_mfma_f32_16x16x32_bf16 v[44:47], v[154:157], v[186:189], v[44:47]
	v_mfma_f32_16x16x32_bf16 v[36:39], v[146:149], v[214:217], v[36:39]
	v_mfma_f32_16x16x32_bf16 v[28:31], v[154:157], v[214:217], v[28:31]
	v_mfma_f32_16x16x32_bf16 v[20:23], v[146:149], v[222:225], v[20:23]
	v_mfma_f32_16x16x32_bf16 v[12:15], v[154:157], v[222:225], v[12:15]
	s_setprio 0
	s_setprio 1
	v_mfma_f32_16x16x32_bf16 v[48:51], v[158:161], v[174:177], v[48:51]
	v_mfma_f32_16x16x32_bf16 v[40:43], v[166:169], v[174:177], v[40:43]
	v_mfma_f32_16x16x32_bf16 v[32:35], v[158:161], v[182:185], v[32:35]
	v_mfma_f32_16x16x32_bf16 v[24:27], v[166:169], v[182:185], v[24:27]
	v_mfma_f32_16x16x32_bf16 v[16:19], v[158:161], v[210:213], v[16:19]
	v_mfma_f32_16x16x32_bf16 v[8:11], v[166:169], v[210:213], v[8:11]
	v_mfma_f32_16x16x32_bf16 v[4:7], v[158:161], v[218:221], v[4:7]
	v_mfma_f32_16x16x32_bf16 v[0:3], v[166:169], v[218:221], v[0:3]
	v_mfma_f32_16x16x32_bf16 v[48:51], v[162:165], v[178:181], v[48:51]
	v_mfma_f32_16x16x32_bf16 v[40:43], v[170:173], v[178:181], v[40:43]
	v_mfma_f32_16x16x32_bf16 v[32:35], v[162:165], v[186:189], v[32:35]
	v_mfma_f32_16x16x32_bf16 v[24:27], v[170:173], v[186:189], v[24:27]
	v_mfma_f32_16x16x32_bf16 v[16:19], v[162:165], v[214:217], v[16:19]
	v_mfma_f32_16x16x32_bf16 v[8:11], v[170:173], v[214:217], v[8:11]
	v_mfma_f32_16x16x32_bf16 v[4:7], v[162:165], v[222:225], v[4:7]
	v_mfma_f32_16x16x32_bf16 v[0:3], v[170:173], v[222:225], v[0:3]
	s_barrier
	s_setprio 0
	s_add_i32 s10, s10, 2
	s_add_u32 s8, s8, 0x100
	s_addc_u32 s9, s9, 0
	s_cmp_gt_u32 s10, 5
	s_mov_b64 s[60:61], s[76:77]
	s_cbranch_scc0 .LBB0_408
	s_mov_b32 s100, 0
	s_and_b64 vcc, exec, s[14:15]
	s_cbranch_vccz .LBB0_411
	s_barrier

; __device__ __forceinline__ const char* a_tile(const Gemm& g, const Unit& u) { return (const char*)(g.A + ((long)u.z1 * g.aS1 + (long)u.z2 * g.aS2 + (long)u.pm * BM * g.lda)); }
; __device__ __forceinline__ const char* b_tile(const Gemm& g, const Unit& u) { return (const char*)(g.Bt + ((long)u.z1 * g.bS1 + (long)u.z2 * g.bS2 + (long)u.pn * BM * g.ldb)); }
; __device__ __forceinline__ int lane_id_opq() { int l; asm volatile("v_mbcnt_lo_u32_b32 %0, -1, 0\n\tv_mbcnt_hi_u32_b32 %0, -1, %0" : "=v"(l)); return l; }
; #define PG8_LDA(dst, b, h) do { _Pragma("unroll") for (int m = 0; m < 4; ++m) _Pragma("unroll") for (int k = 0; k < 2; ++k) dst[m][k] = *(const PG8_LAS bf16x8*)(lds + PG8_SA(b, h) + aoff + m * 2048 + k * 1024); } while (0)
; template <class Epi>
; __device__ __forceinline__ void gemm_phase(PG8_LAS unsigned char* lds, PG8_LAS unsigned char* xl, const Gemm g, const Sched& S, const Epi& E, const int wid) {
;     ...
;         const bool has_next = S.next(ui + 1, nxt);
;         const char* nA = has_next ? a_tile(g, nxt) : cA; const char* nB = has_next ? b_tile(g, nxt) : cB;
;         for (int t = 0; t < nt; t += 2) {
;             const bool last = (t == nt - 2);
;             const bool do0 = !blkdiag_v<Epi> || t == 0, do1 = !blkdiag_v<Epi> || t != 0;
;             long j1 = 0, ja2 = 0, jb2 = 0;
;             if constexpr (Epi::MID) {
;                 if (t == g.tj) { const int lnM = lane_id_opq(); E.mid(acc, cur, wr, wc, lnM & 15, lnM >> 4); }
;                 if (t >= g.tj) j1 = g.jA;
;                 if (t + 2 >= g.tj) { ja2 = g.jA; jb2 = g.jB; } }
;             const char* a1 = cA + (size_t)(t + 1) * kstep + j1;
;             const char* a2 = last ? nA : cA + (size_t)(t + 2) * kstep + ja2; const char* b2 = last ? nB : cB + (size_t)(t + 2) * kstep + jb2;
;             const char* a3 = a2 + kstep; const char* b3 = b2 + kstep;
;             PG8_LDB(B0, 0, 0); PG8_LDB(B1, 0, 1); PG8_SCHED; PG8_LDA(At, 0, 0); PG8_STAGE(PG8_SA(1, 1), a1 + hstepA, voffA);
;             PG8_WAIT_V(8); PG8_WAIT_L(0); PG8_BAR; if (do0) { PG8_MMA(0, 0, At, B0); PG8_MMA(0, 1, At, B1); } PG8_BAR; PG8_SCHED;
;             PG8_LDA(At, 0, 1); PG8_STAGE(PG8_SB(0, 0), b2, voffB); PG8_STAGE(PG8_SB(0, 1), b2 + hstepB, voffB); PG8_STAGE(PG8_SA(0, 0), a2, voffA);
;             PG8_WAIT_V(8); PG8_WAIT_L(0); PG8_BAR; if (do1) { PG8_MMA(1, 0, At, B0); PG8_MMA(1, 1, At, B1); } PG8_BAR; PG8_SCHED;
.LBB0_428:
	s_add_u32 s60, s58, 0x100
	s_addc_u32 s61, s59, 0
	s_add_i32 s11, 0, 0x10000
	s_cmp_eq_u32 s10, 4
	s_cselect_b32 s41, s47, s61
	s_cselect_b32 s40, s46, s60
	s_cselect_b32 s77, s57, s9
	s_cselect_b32 s76, s56, s8
	s_add_i32 s21, 0, 0x14000
	v_add_u32_e32 v154, s11, v140
	v_add_u32_e32 v170, s21, v140
	ds_read_b128 v[142:145], v154
	ds_read_b128 v[146:149], v154 offset:1024
	ds_read_b128 v[150:153], v154 offset:2048
	ds_read_b128 v[154:157], v154 offset:3072
	ds_read_b128 v[158:161], v170
	ds_read_b128 v[162:165], v170 offset:1024
	ds_read_b128 v[166:169], v170 offset:2048
	ds_read_b128 v[170:173], v170 offset:3072
	s_add_i32 m0, s13, 0xc000
	ds_read_b128 v[174:177], v141
	ds_read_b128 v[178:181], v141 offset:1024
	ds_read_b128 v[182:185], v141 offset:2048
	ds_read_b128 v[186:189], v141 offset:3072
	ds_read_b128 v[210:213], v141 offset:4096
	ds_read_b128 v[214:217], v141 offset:5120
	ds_read_b128 v[218:221], v141 offset:6144
	ds_read_b128 v[222:225], v141 offset:7168
	global_load_lds_dwordx4 v136, s[58:59]
	s_add_i32 m0, s13, 0xe000
	s_nop 0
	global_load_lds_dwordx4 v138, s[58:59]
	s_waitcnt vmcnt(8)
	s_waitcnt lgkmcnt(0)
	s_setprio 1
	s_barrier
	v_mfma_f32_16x16x32_bf16 v[124:127], v[142:145], v[174:177], v[124:127]
	v_mfma_f32_16x16x32_bf16 v[120:123], v[150:153], v[174:177], v[120:123]
	v_mfma_f32_16x16x32_bf16 v[116:119], v[142:145], v[182:185], v[116:119]
	v_mfma_f32_16x16x32_bf16 v[108:111], v[150:153], v[182:185], v[108:111]
	v_mfma_f32_16x16x32_bf16 v[100:103], v[142:145], v[210:213], v[100:103]
	v_mfma_f32_16x16x32_bf16 v[92:95], v[150:153], v[210:213], v[92:95]
	v_mfma_f32_16x16x32_bf16 v[84:87], v[142:145], v[218:221], v[84:87]
	v_mfma_f32_16x16x32_bf16 v[76:79], v[150:153], v[218:221], v[76:79]
	v_mfma_f32_16x16x32_bf16 v[124:127], v[146:149], v[178:181], v[124:127]
	v_mfma_f32_16x16x32_bf16 v[120:123], v[154:157], v[178:181], v[120:123]
	v_mfma_f32_16x16x32_bf16 v[116:119], v[146:149], v[186:189], v[116:119]
	v_mfma_f32_16x16x32_bf16 v[108:111], v[154:157], v[186:189], v[108:111]
	v_mfma_f32_16x16x32_bf16 v[100:103], v[146:149], v[214:217], v[100:103]
	v_mfma_f32_16x16x32_bf16 v[92:95], v[154:157], v[214:217], v[92:95]
	v_mfma_f32_16x16x32_bf16 v[84:87], v[146:149], v[222:225], v[84:87]
	v_mfma_f32_16x16x32_bf16 v[76:79], v[154:157], v[222:225], v[76:79]
	s_setprio 0
	s_setprio 1
	v_mfma_f32_16x16x32_bf16 v[112:115], v[158:161], v[174:177], v[112:115]
	v_mfma_f32_16x16x32_bf16 v[104:107], v[166:169], v[174:177], v[104:107]
	v_mfma_f32_16x16x32_bf16 v[96:99], v[158:161], v[182:185], v[96:99]
	v_mfma_f32_16x16x32_bf16 v[88:91], v[166:169], v[182:185], v[88:91]
	v_mfma_f32_16x16x32_bf16 v[80:83], v[158:161], v[210:213], v[80:83]
	v_mfma_f32_16x16x32_bf16 v[72:75], v[166:169], v[210:213], v[72:75]
	v_mfma_f32_16x16x32_bf16 v[68:71], v[158:161], v[218:221], v[68:71]
	v_mfma_f32_16x16x32_bf16 v[64:67], v[166:169], v[218:221], v[64:67]
	v_mfma_f32_16x16x32_bf16 v[112:115], v[162:165], v[178:181], v[112:115]
	v_mfma_f32_16x16x32_bf16 v[104:107], v[170:173], v[178:181], v[104:107]
	v_mfma_f32_16x16x32_bf16 v[96:99], v[162:165], v[186:189], v[96:99]
	v_mfma_f32_16x16x32_bf16 v[88:91], v[170:173], v[186:189], v[88:91]
	v_mfma_f32_16x16x32_bf16 v[80:83], v[162:165], v[214:217], v[80:83]
	v_mfma_f32_16x16x32_bf16 v[72:75], v[170:173], v[214:217], v[72:75]
	v_mfma_f32_16x16x32_bf16 v[68:71], v[162:165], v[222:225], v[68:71]
	v_mfma_f32_16x16x32_bf16 v[64:67], v[170:173], v[222:225], v[64:67]
	s_barrier
	s_setprio 0
	s_add_i32 s11, s11, s29
	s_mov_b32 m0, s11
	ds_read_b128 v[174:177], v141 offset:16384
	ds_read_b128 v[178:181], v141 offset:17408
	ds_read_b128 v[182:185], v141 offset:18432
	ds_read_b128 v[186:189], v141 offset:19456
	ds_read_b128 v[210:213], v141 offset:20480
	ds_read_b128 v[214:217], v141 offset:21504
	ds_read_b128 v[218:221], v141 offset:22528
	ds_read_b128 v[222:225], v141 offset:23552
	global_load_lds_dwordx4 v132, s[76:77]
	s_add_i32 m0, s11, 0x2000
	s_add_u32 s54, s76, 0x100000
	s_addc_u32 s55, s77, 0
	s_add_i32 s11, s21, s29
	global_load_lds_dwordx4 v128, s[76:77]
	s_mov_b32 m0, s11
	s_nop 0
	global_load_lds_dwordx4 v132, s[54:55]
	s_add_i32 m0, s11, 0x2000
	s_nop 0
	global_load_lds_dwordx4 v128, s[54:55]
	s_mov_b32 m0, s13
	s_nop 0
	global_load_lds_dwordx4 v134, s[40:41]
	s_mov_b32 m0, s69
	s_nop 0
	global_load_lds_dwordx4 v130, s[40:41]
	s_waitcnt vmcnt(8)
	s_waitcnt lgkmcnt(0)
	s_setprio 1
	s_barrier
	v_mfma_f32_16x16x32_bf16 v[60:63], v[142:145], v[174:177], v[60:63]
	v_mfma_f32_16x16x32_bf16 v[56:59], v[150:153], v[174:177], v[56:59]
	v_mfma_f32_16x16x32_bf16 v[52:55], v[142:145], v[182:185], v[52:55]
	v_mfma_f32_16x16x32_bf16 v[44:47], v[150:153], v[182:185], v[44:47]
	v_mfma_f32_16x16x32_bf16 v[36:39], v[142:145], v[210:213], v[36:39]
	v_mfma_f32_16x16x32_bf16 v[28:31], v[150:153], v[210:213], v[28:31]
	v_mfma_f32_16x16x32_bf16 v[20:23], v[142:145], v[218:221], v[20:23]
	v_mfma_f32_16x16x32_bf16 v[12:15], v[150:153], v[218:221], v[12:15]
	v_mfma_f32_16x16x32_bf16 v[60:63], v[146:149], v[178:181], v[60:63]
	v_mfma_f32_16x16x32_bf16 v[56:59], v[154:157], v[178:181], v[56:59]
	v_mfma_f32_16x16x32_bf16 v[52:55], v[146:149], v[186:189], v[52:55]
	v_mfma_f32_16x16x32_bf16 v[44:47], v[154:157], v[186:189], v[44:47]
	v_mfma_f32_16x16x32_bf16 v[36:39], v[146:149], v[214:217], v[36:39]
	v_mfma_f32_16x16x32_bf16 v[28:31], v[154:157], v[214:217], v[28:31]
	v_mfma_f32_16x16x32_bf16 v[20:23], v[146:149], v[222:225], v[20:23]
	v_mfma_f32_16x16x32_bf16 v[12:15], v[154:157], v[222:225], v[12:15]
	s_setprio 0
	s_setprio 1
	v_mfma_f32_16x16x32_bf16 v[48:51], v[158:161], v[174:177], v[48:51]
	v_mfma_f32_16x16x32_bf16 v[40:43], v[166:169], v[174:177], v[40:43]
	v_mfma_f32_16x16x32_bf16 v[32:35], v[158:161], v[182:185], v[32:35]
	v_mfma_f32_16x16x32_bf16 v[24:27], v[166:169], v[182:185], v[24:27]
	v_mfma_f32_16x16x32_bf16 v[16:19], v[158:161], v[210:213], v[16:19]
	v_mfma_f32_16x16x32_bf16 v[8:11], v[166:169], v[210:213], v[8:11]
	v_mfma_f32_16x16x32_bf16 v[4:7], v[158:161], v[218:221], v[4:7]
	v_mfma_f32_16x16x32_bf16 v[0:3], v[166:169], v[218:221], v[0:3]
	v_mfma_f32_16x16x32_bf16 v[48:51], v[162:165], v[178:181], v[48:51]
	v_mfma_f32_16x16x32_bf16 v[40:43], v[170:173], v[178:181], v[40:43]
	v_mfma_f32_16x16x32_bf16 v[32:35], v[162:165], v[186:189], v[32:35]
	v_mfma_f32_16x16x32_bf16 v[24:27], v[170:173], v[186:189], v[24:27]
	v_mfma_f32_16x16x32_bf16 v[16:19], v[162:165], v[214:217], v[16:19]
	v_mfma_f32_16x16x32_bf16 v[8:11], v[170:173], v[214:217], v[8:11]
	v_mfma_f32_16x16x32_bf16 v[4:7], v[162:165], v[222:225], v[4:7]
	v_mfma_f32_16x16x32_bf16 v[0:3], v[170:173], v[222:225], v[0:3]
	s_barrier
; #define PG8_STAGE(bufoff, gbase, voff) do { _Pragma("unroll") for (int _i = 0; _i < 2; ++_i) \
;         __builtin_amdgcn_global_load_lds((const unsigned*)((const char*)(gbase) + (voff)[_i]), (PG8_LAS unsigned*)(lds + (bufoff) + ldsw + _i * 8192), 16, 0, 0); } while (0)
; #define PG8_LDA(dst, b, h) do { _Pragma("unroll") for (int m = 0; m < 4; ++m) _Pragma("unroll") for (int k = 0; k < 2; ++k) dst[m][k] = *(const PG8_LAS bf16x8*)(lds + PG8_SA(b, h) + aoff + m * 2048 + k * 1024); } while (0)
; #define PG8_LDB(dst, b, h) do { _Pragma("unroll") for (int n = 0; n < 2; ++n) _Pragma("unroll") for (int k = 0; k < 2; ++k) dst[n][k] = *(const PG8_LAS bf16x8*)(lds + PG8_SB(b, h) + boff + n * 2048 + k * 1024); } while (0)
; #define PG8_MMA(ai, bj, At, Bt) do { __builtin_amdgcn_s_setprio(1); _Pragma("unroll") for (int m = 0; m < 4; ++m) _Pragma("unroll") for (int n = 0; n < 2; ++n) _Pragma("unroll") for (int k = 0; k < 2; ++k) \
;         acc[ai][bj][m][n] = __builtin_amdgcn_mfma_f32_16x16x32_bf16(Bt[n][k], At[m][k], acc[ai][bj][m][n], 0, 0, 0); __builtin_amdgcn_s_setprio(0); } while (0)
; #define PG8_WAIT_V(n) asm volatile("s_waitcnt vmcnt(" #n ")" ::: "memory")
; #define PG8_WAIT_L(n) asm volatile("s_waitcnt lgkmcnt(" #n ")" ::: "memory")
; #define PG8_BAR __builtin_amdgcn_s_barrier()
; #define PG8_SCHED __builtin_amdgcn_sched_barrier(0)
; template <class Epi>
; __device__ __forceinline__ void gemm_phase(PG8_LAS unsigned char* lds, PG8_LAS unsigned char* xl, const Gemm g, const Sched& S, const Epi& E, const int wid) {
;     ...
;             PG8_LDB(B0, 1, 0); PG8_LDB(B1, 1, 1); PG8_SCHED; PG8_LDA(At, 1, 0); PG8_STAGE(PG8_SA(0, 1), a2 + hstepA, voffA);
;             PG8_WAIT_V(8); PG8_WAIT_L(0); PG8_BAR; if (do0) { PG8_MMA(0, 0, At, B0); PG8_MMA(0, 1, At, B1); } PG8_BAR; PG8_SCHED;
;             PG8_LDA(At, 1, 1); PG8_STAGE(PG8_SB(1, 0), b3, voffB); PG8_STAGE(PG8_SB(1, 1), b3 + hstepB, voffB); PG8_STAGE(PG8_SA(1, 0), a3, voffA);
;             PG8_WAIT_V(8); PG8_WAIT_L(0); PG8_BAR; if (do1) { PG8_MMA(1, 0, At, B0); PG8_MMA(1, 1, At, B1); } PG8_BAR; PG8_SCHED;
;         }
	s_setprio 0
	s_add_i32 s11, 0, 0x18000
	s_add_i32 s21, 0, 0x1c000
	v_add_u32_e32 v154, s11, v140
	v_add_u32_e32 v170, s21, v140
	ds_read_b128 v[142:145], v154
	ds_read_b128 v[146:149], v154 offset:1024
	ds_read_b128 v[150:153], v154 offset:2048
	ds_read_b128 v[154:157], v154 offset:3072
	ds_read_b128 v[158:161], v170
	ds_read_b128 v[162:165], v170 offset:1024
	ds_read_b128 v[166:169], v170 offset:2048
	ds_read_b128 v[170:173], v170 offset:3072
	s_add_u32 s100, s40, 0x80000
	s_addc_u32 s101, s41, 0
	s_mov_b32 m0, s70
	ds_read_b128 v[174:177], v141 offset:32768
	ds_read_b128 v[178:181], v141 offset:33792
	ds_read_b128 v[182:185], v141 offset:34816
	ds_read_b128 v[186:189], v141 offset:35840
	ds_read_b128 v[210:213], v141 offset:36864
	ds_read_b128 v[214:217], v141 offset:37888
	ds_read_b128 v[218:221], v141 offset:38912
	ds_read_b128 v[222:225], v141 offset:39936
	global_load_lds_dwordx4 v134, s[100:101]
	s_mov_b32 m0, s71
	s_nop 0
	global_load_lds_dwordx4 v130, s[100:101]
	s_waitcnt vmcnt(8)
	s_waitcnt lgkmcnt(0)
	s_setprio 1
	s_barrier
	v_mfma_f32_16x16x32_bf16 v[124:127], v[142:145], v[174:177], v[124:127]
	v_mfma_f32_16x16x32_bf16 v[120:123], v[150:153], v[174:177], v[120:123]
	v_mfma_f32_16x16x32_bf16 v[116:119], v[142:145], v[182:185], v[116:119]
	v_mfma_f32_16x16x32_bf16 v[108:111], v[150:153], v[182:185], v[108:111]
	v_mfma_f32_16x16x32_bf16 v[100:103], v[142:145], v[210:213], v[100:103]
	v_mfma_f32_16x16x32_bf16 v[92:95], v[150:153], v[210:213], v[92:95]
	v_mfma_f32_16x16x32_bf16 v[84:87], v[142:145], v[218:221], v[84:87]
	v_mfma_f32_16x16x32_bf16 v[76:79], v[150:153], v[218:221], v[76:79]
	v_mfma_f32_16x16x32_bf16 v[124:127], v[146:149], v[178:181], v[124:127]
	v_mfma_f32_16x16x32_bf16 v[120:123], v[154:157], v[178:181], v[120:123]
	v_mfma_f32_16x16x32_bf16 v[116:119], v[146:149], v[186:189], v[116:119]
	v_mfma_f32_16x16x32_bf16 v[108:111], v[154:157], v[186:189], v[108:111]
	v_mfma_f32_16x16x32_bf16 v[100:103], v[146:149], v[214:217], v[100:103]
	v_mfma_f32_16x16x32_bf16 v[92:95], v[154:157], v[214:217], v[92:95]
	v_mfma_f32_16x16x32_bf16 v[84:87], v[146:149], v[222:225], v[84:87]
	v_mfma_f32_16x16x32_bf16 v[76:79], v[154:157], v[222:225], v[76:79]
	s_setprio 0
	s_setprio 1
	v_mfma_f32_16x16x32_bf16 v[112:115], v[158:161], v[174:177], v[112:115]
	v_mfma_f32_16x16x32_bf16 v[104:107], v[166:169], v[174:177], v[104:107]
	v_mfma_f32_16x16x32_bf16 v[96:99], v[158:161], v[182:185], v[96:99]
	v_mfma_f32_16x16x32_bf16 v[88:91], v[166:169], v[182:185], v[88:91]
	v_mfma_f32_16x16x32_bf16 v[80:83], v[158:161], v[210:213], v[80:83]
	v_mfma_f32_16x16x32_bf16 v[72:75], v[166:169], v[210:213], v[72:75]
	v_mfma_f32_16x16x32_bf16 v[68:71], v[158:161], v[218:221], v[68:71]
	v_mfma_f32_16x16x32_bf16 v[64:67], v[166:169], v[218:221], v[64:67]
	v_mfma_f32_16x16x32_bf16 v[112:115], v[162:165], v[178:181], v[112:115]
	v_mfma_f32_16x16x32_bf16 v[104:107], v[170:173], v[178:181], v[104:107]
	v_mfma_f32_16x16x32_bf16 v[96:99], v[162:165], v[186:189], v[96:99]
	v_mfma_f32_16x16x32_bf16 v[88:91], v[170:173], v[186:189], v[88:91]
	v_mfma_f32_16x16x32_bf16 v[80:83], v[162:165], v[214:217], v[80:83]
	v_mfma_f32_16x16x32_bf16 v[72:75], v[170:173], v[214:217], v[72:75]
	v_mfma_f32_16x16x32_bf16 v[68:71], v[162:165], v[222:225], v[68:71]
	v_mfma_f32_16x16x32_bf16 v[64:67], v[170:173], v[222:225], v[64:67]
	s_barrier
	s_setprio 0
	s_add_i32 s11, s11, s29
	s_mov_b32 m0, s11
	ds_read_b128 v[174:177], v141 offset:49152
	ds_read_b128 v[178:181], v141 offset:50176
	ds_read_b128 v[182:185], v141 offset:51200
	ds_read_b128 v[186:189], v141 offset:52224
	ds_read_b128 v[210:213], v141 offset:53248
	ds_read_b128 v[214:217], v141 offset:54272
	ds_read_b128 v[218:221], v141 offset:55296
	ds_read_b128 v[222:225], v141 offset:56320
	global_load_lds_dwordx4 v226, s[76:77]
	s_add_i32 m0, s11, 0x2000
	s_add_u32 s100, s76, 0x100080
	global_load_lds_dwordx4 v190, s[76:77]
	s_addc_u32 s101, s77, 0
	s_add_i32 s11, s21, s29
	s_mov_b32 m0, s11
	s_nop 0
	global_load_lds_dwordx4 v132, s[100:101]
	s_add_i32 m0, s11, 0x2000
	s_nop 0
	global_load_lds_dwordx4 v128, s[100:101]
	s_mov_b32 m0, s90
	s_nop 0
	global_load_lds_dwordx4 v227, s[40:41]
	s_mov_b32 m0, s91
	s_nop 0
	global_load_lds_dwordx4 v191, s[40:41]
	s_waitcnt vmcnt(8)
	s_waitcnt lgkmcnt(0)
	s_setprio 1
	s_barrier
	v_mfma_f32_16x16x32_bf16 v[60:63], v[142:145], v[174:177], v[60:63]
	v_mfma_f32_16x16x32_bf16 v[56:59], v[150:153], v[174:177], v[56:59]
	v_mfma_f32_16x16x32_bf16 v[52:55], v[142:145], v[182:185], v[52:55]
	v_mfma_f32_16x16x32_bf16 v[44:47], v[150:153], v[182:185], v[44:47]
	v_mfma_f32_16x16x32_bf16 v[36:39], v[142:145], v[210:213], v[36:39]
	v_mfma_f32_16x16x32_bf16 v[28:31], v[150:153], v[210:213], v[28:31]
	v_mfma_f32_16x16x32_bf16 v[20:23], v[142:145], v[218:221], v[20:23]
	v_mfma_f32_16x16x32_bf16 v[12:15], v[150:153], v[218:221], v[12:15]
	v_mfma_f32_16x16x32_bf16 v[60:63], v[146:149], v[178:181], v[60:63]
	v_mfma_f32_16x16x32_bf16 v[56:59], v[154:157], v[178:181], v[56:59]
	v_mfma_f32_16x16x32_bf16 v[52:55], v[146:149], v[186:189], v[52:55]
	v_mfma_f32_16x16x32_bf16 v[44:47], v[154:157], v[186:189], v[44:47]
	v_mfma_f32_16x16x32_bf16 v[36:39], v[146:149], v[214:217], v[36:39]
	v_mfma_f32_16x16x32_bf16 v[28:31], v[154:157], v[214:217], v[28:31]
	v_mfma_f32_16x16x32_bf16 v[20:23], v[146:149], v[222:225], v[20:23]
	v_mfma_f32_16x16x32_bf16 v[12:15], v[154:157], v[222:225], v[12:15]
	s_setprio 0
	s_setprio 1
	v_mfma_f32_16x16x32_bf16 v[48:51], v[158:161], v[174:177], v[48:51]
	v_mfma_f32_16x16x32_bf16 v[40:43], v[166:169], v[174:177], v[40:43]
	v_mfma_f32_16x16x32_bf16 v[32:35], v[158:161], v[182:185], v[32:35]
	v_mfma_f32_16x16x32_bf16 v[24:27], v[166:169], v[182:185], v[24:27]
	v_mfma_f32_16x16x32_bf16 v[16:19], v[158:161], v[210:213], v[16:19]
	v_mfma_f32_16x16x32_bf16 v[8:11], v[166:169], v[210:213], v[8:11]
	v_mfma_f32_16x16x32_bf16 v[4:7], v[158:161], v[218:221], v[4:7]
	v_mfma_f32_16x16x32_bf16 v[0:3], v[166:169], v[218:221], v[0:3]
	v_mfma_f32_16x16x32_bf16 v[48:51], v[162:165], v[178:181], v[48:51]
	v_mfma_f32_16x16x32_bf16 v[40:43], v[170:173], v[178:181], v[40:43]
	v_mfma_f32_16x16x32_bf16 v[32:35], v[162:165], v[186:189], v[32:35]
	v_mfma_f32_16x16x32_bf16 v[24:27], v[170:173], v[186:189], v[24:27]
	v_mfma_f32_16x16x32_bf16 v[16:19], v[162:165], v[214:217], v[16:19]
	v_mfma_f32_16x16x32_bf16 v[8:11], v[170:173], v[214:217], v[8:11]
	v_mfma_f32_16x16x32_bf16 v[4:7], v[162:165], v[222:225], v[4:7]
	v_mfma_f32_16x16x32_bf16 v[0:3], v[170:173], v[222:225], v[0:3]
	s_barrier
	s_setprio 0
	s_add_i32 s10, s10, 2
	s_add_u32 s8, s8, 0x100
	s_addc_u32 s9, s9, 0
	s_cmp_gt_u32 s10, 5
	s_mov_b64 s[58:59], s[60:61]
	s_cbranch_scc0 .LBB0_428
	s_mov_b32 s100, 0
	s_and_b64 vcc, exec, s[14:15]
	s_cbranch_vccz .LBB0_431
	s_barrier

; __device__ __forceinline__ const char* a_tile(const Gemm& g, const Unit& u) { return (const char*)(g.A + ((long)u.z1 * g.aS1 + (long)u.z2 * g.aS2 + (long)u.pm * BM * g.lda)); }
; __device__ __forceinline__ const char* b_tile(const Gemm& g, const Unit& u) { return (const char*)(g.Bt + ((long)u.z1 * g.bS1 + (long)u.z2 * g.bS2 + (long)u.pn * BM * g.ldb)); }
; __device__ __forceinline__ int lane_id_opq() { int l; asm volatile("v_mbcnt_lo_u32_b32 %0, -1, 0\n\tv_mbcnt_hi_u32_b32 %0, -1, %0" : "=v"(l)); return l; }
; #define PG8_LDA(dst, b, h) do { _Pragma("unroll") for (int m = 0; m < 4; ++m) _Pragma("unroll") for (int k = 0; k < 2; ++k) dst[m][k] = *(const PG8_LAS bf16x8*)(lds + PG8_SA(b, h) + aoff + m * 2048 + k * 1024); } while (0)
; template <class Epi>
; __device__ __forceinline__ void gemm_phase(PG8_LAS unsigned char* lds, PG8_LAS unsigned char* xl, const Gemm g, const Sched& S, const Epi& E, const int wid) {
;     ...
;         const bool has_next = S.next(ui + 1, nxt);
;         const char* nA = has_next ? a_tile(g, nxt) : cA; const char* nB = has_next ? b_tile(g, nxt) : cB;
;         for (int t = 0; t < nt; t += 2) {
;             const bool last = (t == nt - 2);
;             const bool do0 = !blkdiag_v<Epi> || t == 0, do1 = !blkdiag_v<Epi> || t != 0;
;             long j1 = 0, ja2 = 0, jb2 = 0;
;             if constexpr (Epi::MID) {
;                 if (t == g.tj) { const int lnM = lane_id_opq(); E.mid(acc, cur, wr, wc, lnM & 15, lnM >> 4); }
;                 if (t >= g.tj) j1 = g.jA;
;                 if (t + 2 >= g.tj) { ja2 = g.jA; jb2 = g.jB; } }
;             const char* a1 = cA + (size_t)(t + 1) * kstep + j1;
;             const char* a2 = last ? nA : cA + (size_t)(t + 2) * kstep + ja2; const char* b2 = last ? nB : cB + (size_t)(t + 2) * kstep + jb2;
;             const char* a3 = a2 + kstep; const char* b3 = b2 + kstep;
;             PG8_LDB(B0, 0, 0); PG8_LDB(B1, 0, 1); PG8_SCHED; PG8_LDA(At, 0, 0); PG8_STAGE(PG8_SA(1, 1), a1 + hstepA, voffA);
;             PG8_WAIT_V(8); PG8_WAIT_L(0); PG8_BAR; if (do0) { PG8_MMA(0, 0, At, B0); PG8_MMA(0, 1, At, B1); } PG8_BAR; PG8_SCHED;
;             PG8_LDA(At, 0, 1); PG8_STAGE(PG8_SB(0, 0), b2, voffB); PG8_STAGE(PG8_SB(0, 1), b2 + hstepB, voffB); PG8_STAGE(PG8_SA(0, 0), a2, voffA);
;             PG8_WAIT_V(8); PG8_WAIT_L(0); PG8_BAR; if (do1) { PG8_MMA(1, 0, At, B0); PG8_MMA(1, 1, At, B1); } PG8_BAR; PG8_SCHED;
.Ldefbar_skip_4:
	v_add_u32_e32 v157, s22, v140
	v_add_u32_e32 v204, s22, v142
	v_add_u32_e32 v205, s22, v144
	v_add_u32_e32 v234, s22, v146
.LBB0_527:
	s_add_u32 s20, s12, 0x100
	s_addc_u32 s21, s13, 0
	s_add_i32 s54, 0, 0x10000
	s_cmp_eq_u32 s66, 28
	s_cselect_b32 s53, s8, s21
	s_cselect_b32 s52, s9, s20
	v_add_u32_e32 v156, s54, v158
	s_cselect_b32 s51, s10, s62
	s_cselect_b32 s50, s11, s59
	s_add_i32 s55, 0, 0x14000
	ds_read_b128 v[22:25], v156
	ds_read_b128 v[26:29], v156 offset:1024
	ds_read_b128 v[160:163], v156 offset:2048
	ds_read_b128 v[164:167], v156 offset:3072
	v_add_u32_e32 v156, s55, v158
	ds_read_b128 v[168:171], v156
	ds_read_b128 v[172:175], v156 offset:1024
	ds_read_b128 v[176:179], v156 offset:2048
	ds_read_b128 v[180:183], v156 offset:3072
	s_add_i32 m0, s45, 0xc000
	ds_read_b128 v[184:187], v159
	ds_read_b128 v[188:191], v159 offset:1024
	ds_read_b128 v[210:213], v159 offset:2048
	ds_read_b128 v[214:217], v159 offset:3072
	ds_read_b128 v[218:221], v159 offset:4096
	ds_read_b128 v[222:225], v159 offset:5120
	ds_read_b128 v[226:229], v159 offset:6144
	ds_read_b128 v[230:233], v159 offset:7168
	global_load_lds_dwordx4 v148, s[12:13]
	s_add_i32 m0, s45, 0xe000
	s_nop 0
	global_load_lds_dwordx4 v150, s[12:13]
	s_waitcnt vmcnt(8)
	s_waitcnt lgkmcnt(0)
	s_setprio 1
	s_barrier
	v_mfma_f32_16x16x32_bf16 v[136:139], v[22:25], v[184:187], v[136:139]
	v_mfma_f32_16x16x32_bf16 v[132:135], v[160:163], v[184:187], v[132:135]
	v_mfma_f32_16x16x32_bf16 v[120:123], v[22:25], v[210:213], v[120:123]
	v_mfma_f32_16x16x32_bf16 v[116:119], v[160:163], v[210:213], v[116:119]
	v_mfma_f32_16x16x32_bf16 v[104:107], v[22:25], v[218:221], v[104:107]
	v_mfma_f32_16x16x32_bf16 v[100:103], v[160:163], v[218:221], v[100:103]
	v_mfma_f32_16x16x32_bf16 v[86:89], v[22:25], v[226:229], v[86:89]
	v_mfma_f32_16x16x32_bf16 v[82:85], v[160:163], v[226:229], v[82:85]
	v_mfma_f32_16x16x32_bf16 v[136:139], v[26:29], v[188:191], v[136:139]
	v_mfma_f32_16x16x32_bf16 v[132:135], v[164:167], v[188:191], v[132:135]
	v_mfma_f32_16x16x32_bf16 v[120:123], v[26:29], v[214:217], v[120:123]
	v_mfma_f32_16x16x32_bf16 v[116:119], v[164:167], v[214:217], v[116:119]
	v_mfma_f32_16x16x32_bf16 v[104:107], v[26:29], v[222:225], v[104:107]
	v_mfma_f32_16x16x32_bf16 v[100:103], v[164:167], v[222:225], v[100:103]
	v_mfma_f32_16x16x32_bf16 v[86:89], v[26:29], v[230:233], v[86:89]
	v_mfma_f32_16x16x32_bf16 v[82:85], v[164:167], v[230:233], v[82:85]
	s_setprio 0
	s_setprio 1
	v_mfma_f32_16x16x32_bf16 v[128:131], v[168:171], v[184:187], v[128:131]
	v_mfma_f32_16x16x32_bf16 v[124:127], v[176:179], v[184:187], v[124:127]
	v_mfma_f32_16x16x32_bf16 v[112:115], v[168:171], v[210:213], v[112:115]
	v_mfma_f32_16x16x32_bf16 v[108:111], v[176:179], v[210:213], v[108:111]
	v_mfma_f32_16x16x32_bf16 v[96:99], v[168:171], v[218:221], v[96:99]
	v_mfma_f32_16x16x32_bf16 v[92:95], v[176:179], v[218:221], v[92:95]
	v_mfma_f32_16x16x32_bf16 v[78:81], v[168:171], v[226:229], v[78:81]
	v_mfma_f32_16x16x32_bf16 v[74:77], v[176:179], v[226:229], v[74:77]
	v_mfma_f32_16x16x32_bf16 v[128:131], v[172:175], v[188:191], v[128:131]
	v_mfma_f32_16x16x32_bf16 v[124:127], v[180:183], v[188:191], v[124:127]
	v_mfma_f32_16x16x32_bf16 v[112:115], v[172:175], v[214:217], v[112:115]
	v_mfma_f32_16x16x32_bf16 v[108:111], v[180:183], v[214:217], v[108:111]
	v_mfma_f32_16x16x32_bf16 v[96:99], v[172:175], v[222:225], v[96:99]
	v_mfma_f32_16x16x32_bf16 v[92:95], v[180:183], v[222:225], v[92:95]
	v_mfma_f32_16x16x32_bf16 v[78:81], v[172:175], v[230:233], v[78:81]
	v_mfma_f32_16x16x32_bf16 v[74:77], v[180:183], v[230:233], v[74:77]
	s_barrier
	s_setprio 0
	s_add_i32 s12, s54, s29
	s_mov_b32 m0, s12
	ds_read_b128 v[184:187], v159 offset:16384
	ds_read_b128 v[188:191], v159 offset:17408
	ds_read_b128 v[210:213], v159 offset:18432
	ds_read_b128 v[214:217], v159 offset:19456
	ds_read_b128 v[218:221], v159 offset:20480
	ds_read_b128 v[222:225], v159 offset:21504
	ds_read_b128 v[226:229], v159 offset:22528
	ds_read_b128 v[230:233], v159 offset:23552
	global_load_lds_dwordx4 v142, s[50:51]
	s_add_i32 m0, s12, 0x2000
	s_add_u32 s12, s50, 0x80000
	s_addc_u32 s13, s51, 0
	s_add_i32 s54, s55, s29
	global_load_lds_dwordx4 v146, s[50:51]
	s_mov_b32 m0, s54
	s_nop 0
	global_load_lds_dwordx4 v142, s[12:13]
	s_add_i32 m0, s54, 0x2000
	s_nop 0
	global_load_lds_dwordx4 v146, s[12:13]
	s_mov_b32 m0, s45
	s_nop 0
	global_load_lds_dwordx4 v140, s[52:53]
	s_mov_b32 m0, s41
	s_nop 0
	global_load_lds_dwordx4 v144, s[52:53]
	s_waitcnt vmcnt(8)
	s_waitcnt lgkmcnt(0)
	s_setprio 1
	s_barrier
; #define PG8_STAGE(bufoff, gbase, voff) do { _Pragma("unroll") for (int _i = 0; _i < 2; ++_i) \
;         __builtin_amdgcn_global_load_lds((const unsigned*)((const char*)(gbase) + (voff)[_i]), (PG8_LAS unsigned*)(lds + (bufoff) + ldsw + _i * 8192), 16, 0, 0); } while (0)
; #define PG8_LDA(dst, b, h) do { _Pragma("unroll") for (int m = 0; m < 4; ++m) _Pragma("unroll") for (int k = 0; k < 2; ++k) dst[m][k] = *(const PG8_LAS bf16x8*)(lds + PG8_SA(b, h) + aoff + m * 2048 + k * 1024); } while (0)
; #define PG8_LDB(dst, b, h) do { _Pragma("unroll") for (int n = 0; n < 2; ++n) _Pragma("unroll") for (int k = 0; k < 2; ++k) dst[n][k] = *(const PG8_LAS bf16x8*)(lds + PG8_SB(b, h) + boff + n * 2048 + k * 1024); } while (0)
; #define PG8_MMA(ai, bj, At, Bt) do { __builtin_amdgcn_s_setprio(1); _Pragma("unroll") for (int m = 0; m < 4; ++m) _Pragma("unroll") for (int n = 0; n < 2; ++n) _Pragma("unroll") for (int k = 0; k < 2; ++k) \
;         acc[ai][bj][m][n] = __builtin_amdgcn_mfma_f32_16x16x32_bf16(Bt[n][k], At[m][k], acc[ai][bj][m][n], 0, 0, 0); __builtin_amdgcn_s_setprio(0); } while (0)
; #define PG8_WAIT_V(n) asm volatile("s_waitcnt vmcnt(" #n ")" ::: "memory")
; #define PG8_WAIT_L(n) asm volatile("s_waitcnt lgkmcnt(" #n ")" ::: "memory")
; #define PG8_BAR __builtin_amdgcn_s_barrier()
; #define PG8_SCHED __builtin_amdgcn_sched_barrier(0)
; template <class Epi>
; __device__ __forceinline__ void gemm_phase(PG8_LAS unsigned char* lds, PG8_LAS unsigned char* xl, const Gemm g, const Sched& S, const Epi& E, const int wid) {
;     ...
;             PG8_WAIT_V(8); PG8_WAIT_L(0); PG8_BAR; if (do1) { PG8_MMA(1, 0, At, B0); PG8_MMA(1, 1, At, B1); } PG8_BAR; PG8_SCHED;
;             PG8_LDB(B0, 1, 0); PG8_LDB(B1, 1, 1); PG8_SCHED; PG8_LDA(At, 1, 0); PG8_STAGE(PG8_SA(0, 1), a2 + hstepA, voffA);
;             PG8_WAIT_V(8); PG8_WAIT_L(0); PG8_BAR; if (do0) { PG8_MMA(0, 0, At, B0); PG8_MMA(0, 1, At, B1); } PG8_BAR; PG8_SCHED;
	v_mfma_f32_16x16x32_bf16 v[70:73], v[22:25], v[184:187], v[70:73]
	v_mfma_f32_16x16x32_bf16 v[66:69], v[160:163], v[184:187], v[66:69]
	v_mfma_f32_16x16x32_bf16 v[54:57], v[22:25], v[210:213], v[54:57]
	v_mfma_f32_16x16x32_bf16 v[50:53], v[160:163], v[210:213], v[50:53]
	v_mfma_f32_16x16x32_bf16 v[38:41], v[22:25], v[218:221], v[38:41]
	v_mfma_f32_16x16x32_bf16 v[34:37], v[160:163], v[218:221], v[34:37]
	v_mfma_f32_16x16x32_bf16 v[12:15], v[22:25], v[226:229], v[12:15]
	v_mfma_f32_16x16x32_bf16 v[8:11], v[160:163], v[226:229], v[8:11]
	v_mfma_f32_16x16x32_bf16 v[70:73], v[26:29], v[188:191], v[70:73]
	v_mfma_f32_16x16x32_bf16 v[66:69], v[164:167], v[188:191], v[66:69]
	v_mfma_f32_16x16x32_bf16 v[54:57], v[26:29], v[214:217], v[54:57]
	v_mfma_f32_16x16x32_bf16 v[50:53], v[164:167], v[214:217], v[50:53]
	v_mfma_f32_16x16x32_bf16 v[38:41], v[26:29], v[222:225], v[38:41]
	v_mfma_f32_16x16x32_bf16 v[34:37], v[164:167], v[222:225], v[34:37]
	v_mfma_f32_16x16x32_bf16 v[12:15], v[26:29], v[230:233], v[12:15]
	v_mfma_f32_16x16x32_bf16 v[8:11], v[164:167], v[230:233], v[8:11]
	s_setprio 0
	s_setprio 1
	v_mfma_f32_16x16x32_bf16 v[46:49], v[168:171], v[210:213], v[46:49]
	v_mfma_f32_16x16x32_bf16 v[42:45], v[176:179], v[210:213], v[42:45]
	v_mfma_f32_16x16x32_bf16 v[30:33], v[168:171], v[218:221], v[30:33]
	v_mfma_f32_16x16x32_bf16 v[18:21], v[176:179], v[218:221], v[18:21]
	v_mfma_f32_16x16x32_bf16 v[4:7], v[168:171], v[226:229], v[4:7]
	v_mfma_f32_16x16x32_bf16 v[0:3], v[176:179], v[226:229], v[0:3]
	v_mfma_f32_16x16x32_bf16 v[22:25], v[168:171], v[184:187], v[62:65]
	v_mfma_f32_16x16x32_bf16 v[26:29], v[176:179], v[184:187], v[58:61]
	v_mfma_f32_16x16x32_bf16 v[46:49], v[172:175], v[214:217], v[46:49]
	v_mfma_f32_16x16x32_bf16 v[42:45], v[180:183], v[214:217], v[42:45]
	v_mfma_f32_16x16x32_bf16 v[30:33], v[172:175], v[222:225], v[30:33]
	v_mfma_f32_16x16x32_bf16 v[18:21], v[180:183], v[222:225], v[18:21]
	v_mfma_f32_16x16x32_bf16 v[4:7], v[172:175], v[230:233], v[4:7]
	v_mfma_f32_16x16x32_bf16 v[0:3], v[180:183], v[230:233], v[0:3]
	v_mfma_f32_16x16x32_bf16 v[22:25], v[172:175], v[188:191], v[22:25]
	v_mfma_f32_16x16x32_bf16 v[26:29], v[180:183], v[188:191], v[26:29]
	s_barrier
	s_setprio 0
	s_add_i32 s54, 0, 0x18000
	s_add_i32 s55, 0, 0x1c000
	v_add_u32_e32 v164, s54, v158
	v_add_u32_e32 v180, s55, v158
	ds_read_b128 v[58:61], v164
	ds_read_b128 v[62:65], v164 offset:1024
	ds_read_b128 v[160:163], v164 offset:2048
	ds_read_b128 v[164:167], v164 offset:3072
	ds_read_b128 v[168:171], v180
	ds_read_b128 v[172:175], v180 offset:1024
	ds_read_b128 v[176:179], v180 offset:2048
	ds_read_b128 v[180:183], v180 offset:3072
	s_add_u32 s12, s52, 0x80000
	s_addc_u32 s13, s53, 0
	s_mov_b32 m0, s88
	ds_read_b128 v[184:187], v159 offset:32768
	ds_read_b128 v[188:191], v159 offset:33792
	ds_read_b128 v[210:213], v159 offset:34816
	ds_read_b128 v[214:217], v159 offset:35840
	ds_read_b128 v[218:221], v159 offset:36864
	ds_read_b128 v[222:225], v159 offset:37888
	ds_read_b128 v[226:229], v159 offset:38912
	ds_read_b128 v[230:233], v159 offset:39936
	global_load_lds_dwordx4 v140, s[12:13]
	s_mov_b32 m0, s89
	s_nop 0
	global_load_lds_dwordx4 v144, s[12:13]
	s_waitcnt vmcnt(8)
	s_waitcnt lgkmcnt(0)
	s_setprio 1
	s_barrier
	v_mfma_f32_16x16x32_bf16 v[136:139], v[58:61], v[184:187], v[136:139]
	v_mfma_f32_16x16x32_bf16 v[132:135], v[160:163], v[184:187], v[132:135]
	v_mfma_f32_16x16x32_bf16 v[120:123], v[58:61], v[210:213], v[120:123]
	v_mfma_f32_16x16x32_bf16 v[116:119], v[160:163], v[210:213], v[116:119]
	v_mfma_f32_16x16x32_bf16 v[104:107], v[58:61], v[218:221], v[104:107]
	v_mfma_f32_16x16x32_bf16 v[100:103], v[160:163], v[218:221], v[100:103]
	v_mfma_f32_16x16x32_bf16 v[86:89], v[58:61], v[226:229], v[86:89]
	v_mfma_f32_16x16x32_bf16 v[82:85], v[160:163], v[226:229], v[82:85]
	v_mfma_f32_16x16x32_bf16 v[136:139], v[62:65], v[188:191], v[136:139]
	v_mfma_f32_16x16x32_bf16 v[132:135], v[164:167], v[188:191], v[132:135]
	v_mfma_f32_16x16x32_bf16 v[120:123], v[62:65], v[214:217], v[120:123]
	v_mfma_f32_16x16x32_bf16 v[116:119], v[164:167], v[214:217], v[116:119]
	v_mfma_f32_16x16x32_bf16 v[104:107], v[62:65], v[222:225], v[104:107]
	v_mfma_f32_16x16x32_bf16 v[100:103], v[164:167], v[222:225], v[100:103]
	v_mfma_f32_16x16x32_bf16 v[86:89], v[62:65], v[230:233], v[86:89]
	v_mfma_f32_16x16x32_bf16 v[82:85], v[164:167], v[230:233], v[82:85]
	s_setprio 0
	s_setprio 1
	v_mfma_f32_16x16x32_bf16 v[128:131], v[168:171], v[184:187], v[128:131]
	v_mfma_f32_16x16x32_bf16 v[124:127], v[176:179], v[184:187], v[124:127]
	v_mfma_f32_16x16x32_bf16 v[112:115], v[168:171], v[210:213], v[112:115]
	v_mfma_f32_16x16x32_bf16 v[108:111], v[176:179], v[210:213], v[108:111]
	v_mfma_f32_16x16x32_bf16 v[96:99], v[168:171], v[218:221], v[96:99]
	v_mfma_f32_16x16x32_bf16 v[92:95], v[176:179], v[218:221], v[92:95]
	v_mfma_f32_16x16x32_bf16 v[78:81], v[168:171], v[226:229], v[78:81]
	v_mfma_f32_16x16x32_bf16 v[74:77], v[176:179], v[226:229], v[74:77]
	v_mfma_f32_16x16x32_bf16 v[128:131], v[172:175], v[188:191], v[128:131]
	v_mfma_f32_16x16x32_bf16 v[124:127], v[180:183], v[188:191], v[124:127]
	v_mfma_f32_16x16x32_bf16 v[112:115], v[172:175], v[214:217], v[112:115]
	v_mfma_f32_16x16x32_bf16 v[108:111], v[180:183], v[214:217], v[108:111]
	v_mfma_f32_16x16x32_bf16 v[96:99], v[172:175], v[222:225], v[96:99]
	v_mfma_f32_16x16x32_bf16 v[92:95], v[180:183], v[222:225], v[92:95]
	v_mfma_f32_16x16x32_bf16 v[78:81], v[172:175], v[230:233], v[78:81]
	v_mfma_f32_16x16x32_bf16 v[74:77], v[180:183], v[230:233], v[74:77]
	s_barrier
; #define PG8_STAGE(bufoff, gbase, voff) do { _Pragma("unroll") for (int _i = 0; _i < 2; ++_i) \
;         __builtin_amdgcn_global_load_lds((const unsigned*)((const char*)(gbase) + (voff)[_i]), (PG8_LAS unsigned*)(lds + (bufoff) + ldsw + _i * 8192), 16, 0, 0); } while (0)
; #define PG8_LDA(dst, b, h) do { _Pragma("unroll") for (int m = 0; m < 4; ++m) _Pragma("unroll") for (int k = 0; k < 2; ++k) dst[m][k] = *(const PG8_LAS bf16x8*)(lds + PG8_SA(b, h) + aoff + m * 2048 + k * 1024); } while (0)
; #define PG8_MMA(ai, bj, At, Bt) do { __builtin_amdgcn_s_setprio(1); _Pragma("unroll") for (int m = 0; m < 4; ++m) _Pragma("unroll") for (int n = 0; n < 2; ++n) _Pragma("unroll") for (int k = 0; k < 2; ++k) \
;         acc[ai][bj][m][n] = __builtin_amdgcn_mfma_f32_16x16x32_bf16(Bt[n][k], At[m][k], acc[ai][bj][m][n], 0, 0, 0); __builtin_amdgcn_s_setprio(0); } while (0)
; #define PG8_WAIT_V(n) asm volatile("s_waitcnt vmcnt(" #n ")" ::: "memory")
; #define PG8_WAIT_L(n) asm volatile("s_waitcnt lgkmcnt(" #n ")" ::: "memory")
; #define PG8_BAR __builtin_amdgcn_s_barrier()
; #define PG8_SCHED __builtin_amdgcn_sched_barrier(0)
; template <class Epi>
; __device__ __forceinline__ void gemm_phase(PG8_LAS unsigned char* lds, PG8_LAS unsigned char* xl, const Gemm g, const Sched& S, const Epi& E, const int wid) {
;     ...
;             PG8_LDA(At, 1, 1); PG8_STAGE(PG8_SB(1, 0), b3, voffB); PG8_STAGE(PG8_SB(1, 1), b3 + hstepB, voffB); PG8_STAGE(PG8_SA(1, 0), a3, voffA);
;             PG8_WAIT_V(8); PG8_WAIT_L(0); PG8_BAR; if (do1) { PG8_MMA(1, 0, At, B0); PG8_MMA(1, 1, At, B1); } PG8_BAR; PG8_SCHED;
;         }
	s_setprio 0
	s_add_i32 s12, s54, s29
	s_mov_b32 m0, s12
	ds_read_b128 v[184:187], v159 offset:49152
	ds_read_b128 v[188:191], v159 offset:50176
	ds_read_b128 v[210:213], v159 offset:51200
	ds_read_b128 v[214:217], v159 offset:52224
	ds_read_b128 v[218:221], v159 offset:53248
	ds_read_b128 v[222:225], v159 offset:54272
	ds_read_b128 v[226:229], v159 offset:55296
	ds_read_b128 v[230:233], v159 offset:56320
	global_load_lds_dwordx4 v204, s[50:51]
	s_add_i32 m0, s12, 0x2000
	s_add_u32 s12, s50, 0x80080
	global_load_lds_dwordx4 v234, s[50:51]
	s_addc_u32 s13, s51, 0
	s_add_i32 s50, s55, s29
	s_mov_b32 m0, s50
	s_nop 0
	global_load_lds_dwordx4 v142, s[12:13]
	s_add_i32 m0, s50, 0x2000
	s_nop 0
	global_load_lds_dwordx4 v146, s[12:13]
	s_mov_b32 m0, s90
	s_nop 0
	global_load_lds_dwordx4 v157, s[52:53]
	s_mov_b32 m0, s91
	s_nop 0
	global_load_lds_dwordx4 v205, s[52:53]
	s_waitcnt vmcnt(8)
	s_waitcnt lgkmcnt(0)
	s_setprio 1
	s_barrier
	v_mfma_f32_16x16x32_bf16 v[70:73], v[58:61], v[184:187], v[70:73]
	v_mfma_f32_16x16x32_bf16 v[66:69], v[160:163], v[184:187], v[66:69]
	v_mfma_f32_16x16x32_bf16 v[54:57], v[58:61], v[210:213], v[54:57]
	v_mfma_f32_16x16x32_bf16 v[50:53], v[160:163], v[210:213], v[50:53]
	v_mfma_f32_16x16x32_bf16 v[38:41], v[58:61], v[218:221], v[38:41]
	v_mfma_f32_16x16x32_bf16 v[34:37], v[160:163], v[218:221], v[34:37]
	v_mfma_f32_16x16x32_bf16 v[12:15], v[58:61], v[226:229], v[12:15]
	v_mfma_f32_16x16x32_bf16 v[8:11], v[160:163], v[226:229], v[8:11]
	v_mfma_f32_16x16x32_bf16 v[70:73], v[62:65], v[188:191], v[70:73]
	v_mfma_f32_16x16x32_bf16 v[66:69], v[164:167], v[188:191], v[66:69]
	v_mfma_f32_16x16x32_bf16 v[54:57], v[62:65], v[214:217], v[54:57]
	v_mfma_f32_16x16x32_bf16 v[50:53], v[164:167], v[214:217], v[50:53]
	v_mfma_f32_16x16x32_bf16 v[38:41], v[62:65], v[222:225], v[38:41]
	v_mfma_f32_16x16x32_bf16 v[34:37], v[164:167], v[222:225], v[34:37]
	v_mfma_f32_16x16x32_bf16 v[12:15], v[62:65], v[230:233], v[12:15]
	v_mfma_f32_16x16x32_bf16 v[8:11], v[164:167], v[230:233], v[8:11]
	s_setprio 0
	s_setprio 1
	v_mfma_f32_16x16x32_bf16 v[22:25], v[168:171], v[184:187], v[22:25]
	v_mfma_f32_16x16x32_bf16 v[62:65], v[172:175], v[188:191], v[22:25]
	v_mfma_f32_16x16x32_bf16 v[22:25], v[176:179], v[184:187], v[26:29]
	v_mfma_f32_16x16x32_bf16 v[58:61], v[180:183], v[188:191], v[22:25]
	v_mfma_f32_16x16x32_bf16 v[22:25], v[168:171], v[210:213], v[46:49]
	v_mfma_f32_16x16x32_bf16 v[46:49], v[172:175], v[214:217], v[22:25]
	v_mfma_f32_16x16x32_bf16 v[22:25], v[176:179], v[210:213], v[42:45]
	v_mfma_f32_16x16x32_bf16 v[42:45], v[180:183], v[214:217], v[22:25]
	v_mfma_f32_16x16x32_bf16 v[22:25], v[168:171], v[218:221], v[30:33]
	v_mfma_f32_16x16x32_bf16 v[18:21], v[176:179], v[218:221], v[18:21]
	v_mfma_f32_16x16x32_bf16 v[4:7], v[168:171], v[226:229], v[4:7]
	v_mfma_f32_16x16x32_bf16 v[0:3], v[176:179], v[226:229], v[0:3]
	v_mfma_f32_16x16x32_bf16 v[30:33], v[172:175], v[222:225], v[22:25]
	v_mfma_f32_16x16x32_bf16 v[18:21], v[180:183], v[222:225], v[18:21]
	v_mfma_f32_16x16x32_bf16 v[4:7], v[172:175], v[230:233], v[4:7]
	v_mfma_f32_16x16x32_bf16 v[0:3], v[180:183], v[230:233], v[0:3]
	s_barrier
	s_setprio 0
	s_add_i32 s66, s66, 2
	s_add_u32 s59, s59, 0x100
	s_addc_u32 s62, s62, 0
	s_cmp_gt_u32 s66, 29
	s_mov_b64 s[12:13], s[20:21]
	s_cbranch_scc0 .LBB0_527
	s_and_b64 vcc, exec, s[14:15]
	s_cbranch_vccz .LBB0_530
	s_barrier

; __device__ __forceinline__ const char* a_tile(const Gemm& g, const Unit& u) { return (const char*)(g.A + ((long)u.z1 * g.aS1 + (long)u.z2 * g.aS2 + (long)u.pm * BM * g.lda)); }
; __device__ __forceinline__ const char* b_tile(const Gemm& g, const Unit& u) { return (const char*)(g.Bt + ((long)u.z1 * g.bS1 + (long)u.z2 * g.bS2 + (long)u.pn * BM * g.ldb)); }
; __device__ __forceinline__ int lane_id_opq() { int l; asm volatile("v_mbcnt_lo_u32_b32 %0, -1, 0\n\tv_mbcnt_hi_u32_b32 %0, -1, %0" : "=v"(l)); return l; }
; #define PG8_LDA(dst, b, h) do { _Pragma("unroll") for (int m = 0; m < 4; ++m) _Pragma("unroll") for (int k = 0; k < 2; ++k) dst[m][k] = *(const PG8_LAS bf16x8*)(lds + PG8_SA(b, h) + aoff + m * 2048 + k * 1024); } while (0)
; template <class Epi>
; __device__ __forceinline__ void gemm_phase(PG8_LAS unsigned char* lds, PG8_LAS unsigned char* xl, const Gemm g, const Sched& S, const Epi& E, const int wid) {
;     ...
;         const bool has_next = S.next(ui + 1, nxt);
;         const char* nA = has_next ? a_tile(g, nxt) : cA; const char* nB = has_next ? b_tile(g, nxt) : cB;
;         for (int t = 0; t < nt; t += 2) {
;             const bool last = (t == nt - 2);
;             const bool do0 = !blkdiag_v<Epi> || t == 0, do1 = !blkdiag_v<Epi> || t != 0;
;             long j1 = 0, ja2 = 0, jb2 = 0;
;             if constexpr (Epi::MID) {
;                 if (t == g.tj) { const int lnM = lane_id_opq(); E.mid(acc, cur, wr, wc, lnM & 15, lnM >> 4); }
;                 if (t >= g.tj) j1 = g.jA;
;                 if (t + 2 >= g.tj) { ja2 = g.jA; jb2 = g.jB; } }
;             const char* a1 = cA + (size_t)(t + 1) * kstep + j1;
;             const char* a2 = last ? nA : cA + (size_t)(t + 2) * kstep + ja2; const char* b2 = last ? nB : cB + (size_t)(t + 2) * kstep + jb2;
;             const char* a3 = a2 + kstep; const char* b3 = b2 + kstep;
;             PG8_LDB(B0, 0, 0); PG8_LDB(B1, 0, 1); PG8_SCHED; PG8_LDA(At, 0, 0); PG8_STAGE(PG8_SA(1, 1), a1 + hstepA, voffA);
;             PG8_WAIT_V(8); PG8_WAIT_L(0); PG8_BAR; if (do0) { PG8_MMA(0, 0, At, B0); PG8_MMA(0, 1, At, B1); } PG8_BAR; PG8_SCHED;
;             PG8_LDA(At, 0, 1); PG8_STAGE(PG8_SB(0, 0), b2, voffB); PG8_STAGE(PG8_SB(0, 1), b2 + hstepB, voffB); PG8_STAGE(PG8_SA(0, 0), a2, voffA);
;             PG8_WAIT_V(8); PG8_WAIT_L(0); PG8_BAR; if (do1) { PG8_MMA(1, 0, At, B0); PG8_MMA(1, 1, At, B1); } PG8_BAR; PG8_SCHED;
.Ldefbar_skip_6:
	v_add_u32_e32 v204, s22, v188
	v_add_u32_e32 v205, s22, v190
	v_add_u32_e32 v218, s22, v210
	v_add_u32_e32 v219, s22, v212
.LBB0_765:
	s_add_u32 s21, s42, 0xffd40080
	s_addc_u32 s31, s43, -1
	s_add_i32 s54, 0, 0x10000
	s_cmp_eq_u32 s13, 28
	s_cselect_b32 s49, s37, s31
	s_cselect_b32 s48, s36, s21
	s_cselect_b32 s45, s8, s11
	s_cselect_b32 s44, s9, s10
	s_add_i32 s21, 0, 0x14000
	v_add_u32_e32 v136, s54, v195
	v_add_u32_e32 v156, s21, v195
	ds_read_b128 v[120:123], v136
	ds_read_b128 v[124:127], v136 offset:1024
	ds_read_b128 v[128:131], v136 offset:2048
	ds_read_b128 v[136:139], v136 offset:3072
	ds_read_b128 v[144:147], v156
	ds_read_b128 v[148:151], v156 offset:1024
	ds_read_b128 v[152:155], v156 offset:2048
	ds_read_b128 v[156:159], v156 offset:3072
	s_add_i32 m0, s53, 0xc000
	ds_read_b128 v[160:163], v220
	ds_read_b128 v[164:167], v220 offset:1024
	ds_read_b128 v[168:171], v220 offset:2048
	ds_read_b128 v[172:175], v220 offset:3072
	ds_read_b128 v[176:179], v220 offset:4096
	ds_read_b128 v[180:183], v220 offset:5120
	ds_read_b128 v[184:187], v220 offset:6144
	ds_read_b128 v[222:225], v220 offset:7168
	global_load_lds_dwordx4 v214, s[42:43]
	s_add_i32 m0, s53, 0xe000
	s_nop 0
	global_load_lds_dwordx4 v216, s[42:43]
	s_waitcnt vmcnt(8)
	s_waitcnt lgkmcnt(0)
	s_setprio 1
	s_barrier
	v_mfma_f32_16x16x32_bf16 v[140:143], v[120:123], v[160:163], v[140:143]
	v_mfma_f32_16x16x32_bf16 v[132:135], v[128:131], v[160:163], v[132:135]
	v_mfma_f32_16x16x32_bf16 v[108:111], v[120:123], v[168:171], v[108:111]
	v_mfma_f32_16x16x32_bf16 v[104:107], v[128:131], v[168:171], v[104:107]
	v_mfma_f32_16x16x32_bf16 v[92:95], v[120:123], v[176:179], v[92:95]
	v_mfma_f32_16x16x32_bf16 v[88:91], v[128:131], v[176:179], v[88:91]
	v_mfma_f32_16x16x32_bf16 v[76:79], v[120:123], v[184:187], v[76:79]
	v_mfma_f32_16x16x32_bf16 v[72:75], v[128:131], v[184:187], v[72:75]
	v_mfma_f32_16x16x32_bf16 v[140:143], v[124:127], v[164:167], v[140:143]
	v_mfma_f32_16x16x32_bf16 v[132:135], v[136:139], v[164:167], v[132:135]
	v_mfma_f32_16x16x32_bf16 v[108:111], v[124:127], v[172:175], v[108:111]
	v_mfma_f32_16x16x32_bf16 v[104:107], v[136:139], v[172:175], v[104:107]
	v_mfma_f32_16x16x32_bf16 v[92:95], v[124:127], v[180:183], v[92:95]
	v_mfma_f32_16x16x32_bf16 v[88:91], v[136:139], v[180:183], v[88:91]
	v_mfma_f32_16x16x32_bf16 v[76:79], v[124:127], v[222:225], v[76:79]
	v_mfma_f32_16x16x32_bf16 v[72:75], v[136:139], v[222:225], v[72:75]
	s_setprio 0
	s_setprio 1
	v_mfma_f32_16x16x32_bf16 v[116:119], v[144:147], v[160:163], v[116:119]
	v_mfma_f32_16x16x32_bf16 v[112:115], v[152:155], v[160:163], v[112:115]
	v_mfma_f32_16x16x32_bf16 v[100:103], v[144:147], v[168:171], v[100:103]
	v_mfma_f32_16x16x32_bf16 v[96:99], v[152:155], v[168:171], v[96:99]
	v_mfma_f32_16x16x32_bf16 v[84:87], v[144:147], v[176:179], v[84:87]
	v_mfma_f32_16x16x32_bf16 v[80:83], v[152:155], v[176:179], v[80:83]
	v_mfma_f32_16x16x32_bf16 v[68:71], v[144:147], v[184:187], v[68:71]
	v_mfma_f32_16x16x32_bf16 v[64:67], v[152:155], v[184:187], v[64:67]
	v_mfma_f32_16x16x32_bf16 v[116:119], v[148:151], v[164:167], v[116:119]
	v_mfma_f32_16x16x32_bf16 v[112:115], v[156:159], v[164:167], v[112:115]
	v_mfma_f32_16x16x32_bf16 v[100:103], v[148:151], v[172:175], v[100:103]
	v_mfma_f32_16x16x32_bf16 v[96:99], v[156:159], v[172:175], v[96:99]
	v_mfma_f32_16x16x32_bf16 v[84:87], v[148:151], v[180:183], v[84:87]
	v_mfma_f32_16x16x32_bf16 v[80:83], v[156:159], v[180:183], v[80:83]
	v_mfma_f32_16x16x32_bf16 v[68:71], v[148:151], v[222:225], v[68:71]
	v_mfma_f32_16x16x32_bf16 v[64:67], v[156:159], v[222:225], v[64:67]
	s_barrier
	s_setprio 0
	s_add_i32 s31, s54, s29
	s_mov_b32 m0, s31
	ds_read_b128 v[160:163], v220 offset:16384
	ds_read_b128 v[164:167], v220 offset:17408
	ds_read_b128 v[168:171], v220 offset:18432
	ds_read_b128 v[172:175], v220 offset:19456
	ds_read_b128 v[176:179], v220 offset:20480
	ds_read_b128 v[180:183], v220 offset:21504
	ds_read_b128 v[184:187], v220 offset:22528
	ds_read_b128 v[222:225], v220 offset:23552
	global_load_lds_dwordx4 v190, s[44:45]
	s_add_i32 m0, s31, 0x2000
	s_add_u32 s54, s44, 0x80000
	s_addc_u32 s55, s45, 0
	s_add_i32 s21, s21, s29
	global_load_lds_dwordx4 v212, s[44:45]
	s_mov_b32 m0, s21
	s_nop 0
	global_load_lds_dwordx4 v190, s[54:55]
	s_add_i32 m0, s21, 0x2000
	s_nop 0
	global_load_lds_dwordx4 v212, s[54:55]
	s_mov_b32 m0, s53
	s_nop 0
	global_load_lds_dwordx4 v188, s[48:49]
	s_mov_b32 m0, s56
	s_nop 0
	global_load_lds_dwordx4 v210, s[48:49]
	s_waitcnt vmcnt(8)
	s_waitcnt lgkmcnt(0)
	s_setprio 1
	s_barrier
; #define PG8_STAGE(bufoff, gbase, voff) do { _Pragma("unroll") for (int _i = 0; _i < 2; ++_i) \
;         __builtin_amdgcn_global_load_lds((const unsigned*)((const char*)(gbase) + (voff)[_i]), (PG8_LAS unsigned*)(lds + (bufoff) + ldsw + _i * 8192), 16, 0, 0); } while (0)
; #define PG8_LDA(dst, b, h) do { _Pragma("unroll") for (int m = 0; m < 4; ++m) _Pragma("unroll") for (int k = 0; k < 2; ++k) dst[m][k] = *(const PG8_LAS bf16x8*)(lds + PG8_SA(b, h) + aoff + m * 2048 + k * 1024); } while (0)
; #define PG8_LDB(dst, b, h) do { _Pragma("unroll") for (int n = 0; n < 2; ++n) _Pragma("unroll") for (int k = 0; k < 2; ++k) dst[n][k] = *(const PG8_LAS bf16x8*)(lds + PG8_SB(b, h) + boff + n * 2048 + k * 1024); } while (0)
; #define PG8_MMA(ai, bj, At, Bt) do { __builtin_amdgcn_s_setprio(1); _Pragma("unroll") for (int m = 0; m < 4; ++m) _Pragma("unroll") for (int n = 0; n < 2; ++n) _Pragma("unroll") for (int k = 0; k < 2; ++k) \
;         acc[ai][bj][m][n] = __builtin_amdgcn_mfma_f32_16x16x32_bf16(Bt[n][k], At[m][k], acc[ai][bj][m][n], 0, 0, 0); __builtin_amdgcn_s_setprio(0); } while (0)
; #define PG8_WAIT_V(n) asm volatile("s_waitcnt vmcnt(" #n ")" ::: "memory")
; #define PG8_WAIT_L(n) asm volatile("s_waitcnt lgkmcnt(" #n ")" ::: "memory")
; #define PG8_BAR __builtin_amdgcn_s_barrier()
; #define PG8_SCHED __builtin_amdgcn_sched_barrier(0)
; template <class Epi>
; __device__ __forceinline__ void gemm_phase(PG8_LAS unsigned char* lds, PG8_LAS unsigned char* xl, const Gemm g, const Sched& S, const Epi& E, const int wid) {
;     ...
;             PG8_WAIT_V(8); PG8_WAIT_L(0); PG8_BAR; if (do1) { PG8_MMA(1, 0, At, B0); PG8_MMA(1, 1, At, B1); } PG8_BAR; PG8_SCHED;
;             PG8_LDB(B0, 1, 0); PG8_LDB(B1, 1, 1); PG8_SCHED; PG8_LDA(At, 1, 0); PG8_STAGE(PG8_SA(0, 1), a2 + hstepA, voffA);
;             PG8_WAIT_V(8); PG8_WAIT_L(0); PG8_BAR; if (do0) { PG8_MMA(0, 0, At, B0); PG8_MMA(0, 1, At, B1); } PG8_BAR; PG8_SCHED;
	v_mfma_f32_16x16x32_bf16 v[60:63], v[120:123], v[160:163], v[60:63]
	v_mfma_f32_16x16x32_bf16 v[56:59], v[128:131], v[160:163], v[56:59]
	v_mfma_f32_16x16x32_bf16 v[44:47], v[120:123], v[168:171], v[44:47]
	v_mfma_f32_16x16x32_bf16 v[40:43], v[128:131], v[168:171], v[40:43]
	v_mfma_f32_16x16x32_bf16 v[28:31], v[120:123], v[176:179], v[28:31]
	v_mfma_f32_16x16x32_bf16 v[24:27], v[128:131], v[176:179], v[24:27]
	v_mfma_f32_16x16x32_bf16 v[12:15], v[120:123], v[184:187], v[12:15]
	v_mfma_f32_16x16x32_bf16 v[8:11], v[128:131], v[184:187], v[8:11]
	v_mfma_f32_16x16x32_bf16 v[60:63], v[124:127], v[164:167], v[60:63]
	v_mfma_f32_16x16x32_bf16 v[56:59], v[136:139], v[164:167], v[56:59]
	v_mfma_f32_16x16x32_bf16 v[44:47], v[124:127], v[172:175], v[44:47]
	v_mfma_f32_16x16x32_bf16 v[40:43], v[136:139], v[172:175], v[40:43]
	v_mfma_f32_16x16x32_bf16 v[28:31], v[124:127], v[180:183], v[28:31]
	v_mfma_f32_16x16x32_bf16 v[24:27], v[136:139], v[180:183], v[24:27]
	v_mfma_f32_16x16x32_bf16 v[12:15], v[124:127], v[222:225], v[12:15]
	v_mfma_f32_16x16x32_bf16 v[8:11], v[136:139], v[222:225], v[8:11]
	s_setprio 0
	s_setprio 1
	v_mfma_f32_16x16x32_bf16 v[52:55], v[144:147], v[160:163], v[52:55]
	v_mfma_f32_16x16x32_bf16 v[48:51], v[152:155], v[160:163], v[48:51]
	v_mfma_f32_16x16x32_bf16 v[36:39], v[144:147], v[168:171], v[36:39]
	v_mfma_f32_16x16x32_bf16 v[32:35], v[152:155], v[168:171], v[32:35]
	v_mfma_f32_16x16x32_bf16 v[20:23], v[144:147], v[176:179], v[20:23]
	v_mfma_f32_16x16x32_bf16 v[16:19], v[152:155], v[176:179], v[16:19]
	v_mfma_f32_16x16x32_bf16 v[4:7], v[144:147], v[184:187], v[4:7]
	v_mfma_f32_16x16x32_bf16 v[0:3], v[152:155], v[184:187], v[0:3]
	v_mfma_f32_16x16x32_bf16 v[52:55], v[148:151], v[164:167], v[52:55]
	v_mfma_f32_16x16x32_bf16 v[48:51], v[156:159], v[164:167], v[48:51]
	v_mfma_f32_16x16x32_bf16 v[36:39], v[148:151], v[172:175], v[36:39]
	v_mfma_f32_16x16x32_bf16 v[32:35], v[156:159], v[172:175], v[32:35]
	v_mfma_f32_16x16x32_bf16 v[20:23], v[148:151], v[180:183], v[20:23]
	v_mfma_f32_16x16x32_bf16 v[16:19], v[156:159], v[180:183], v[16:19]
	v_mfma_f32_16x16x32_bf16 v[4:7], v[148:151], v[222:225], v[4:7]
	v_mfma_f32_16x16x32_bf16 v[0:3], v[156:159], v[222:225], v[0:3]
	s_barrier
	s_setprio 0
	s_add_i32 s21, 0, 0x18000
	s_add_i32 s31, 0, 0x1c000
	v_add_u32_e32 v136, s21, v195
	v_add_u32_e32 v156, s31, v195
	ds_read_b128 v[120:123], v136
	ds_read_b128 v[124:127], v136 offset:1024
	ds_read_b128 v[128:131], v136 offset:2048
	ds_read_b128 v[136:139], v136 offset:3072
	ds_read_b128 v[144:147], v156
	ds_read_b128 v[148:151], v156 offset:1024
	ds_read_b128 v[152:155], v156 offset:2048
	ds_read_b128 v[156:159], v156 offset:3072
	s_add_u32 s100, s48, 0x2c0000
	s_addc_u32 s101, s49, 0
	s_mov_b32 m0, s57
	ds_read_b128 v[160:163], v220 offset:32768
	ds_read_b128 v[164:167], v220 offset:33792
	ds_read_b128 v[168:171], v220 offset:34816
	ds_read_b128 v[172:175], v220 offset:35840
	ds_read_b128 v[176:179], v220 offset:36864
	ds_read_b128 v[180:183], v220 offset:37888
	ds_read_b128 v[184:187], v220 offset:38912
	ds_read_b128 v[222:225], v220 offset:39936
	global_load_lds_dwordx4 v188, s[100:101]
	s_mov_b32 m0, s58
	s_nop 0
	global_load_lds_dwordx4 v210, s[100:101]
	s_waitcnt vmcnt(8)
	s_waitcnt lgkmcnt(0)
	s_setprio 1
	s_barrier
	v_mfma_f32_16x16x32_bf16 v[140:143], v[120:123], v[160:163], v[140:143]
	v_mfma_f32_16x16x32_bf16 v[132:135], v[128:131], v[160:163], v[132:135]
	v_mfma_f32_16x16x32_bf16 v[108:111], v[120:123], v[168:171], v[108:111]
	v_mfma_f32_16x16x32_bf16 v[104:107], v[128:131], v[168:171], v[104:107]
	v_mfma_f32_16x16x32_bf16 v[92:95], v[120:123], v[176:179], v[92:95]
	v_mfma_f32_16x16x32_bf16 v[88:91], v[128:131], v[176:179], v[88:91]
	v_mfma_f32_16x16x32_bf16 v[76:79], v[120:123], v[184:187], v[76:79]
	v_mfma_f32_16x16x32_bf16 v[72:75], v[128:131], v[184:187], v[72:75]
	v_mfma_f32_16x16x32_bf16 v[140:143], v[124:127], v[164:167], v[140:143]
	v_mfma_f32_16x16x32_bf16 v[132:135], v[136:139], v[164:167], v[132:135]
	v_mfma_f32_16x16x32_bf16 v[108:111], v[124:127], v[172:175], v[108:111]
	v_mfma_f32_16x16x32_bf16 v[104:107], v[136:139], v[172:175], v[104:107]
	v_mfma_f32_16x16x32_bf16 v[92:95], v[124:127], v[180:183], v[92:95]
	v_mfma_f32_16x16x32_bf16 v[88:91], v[136:139], v[180:183], v[88:91]
	v_mfma_f32_16x16x32_bf16 v[76:79], v[124:127], v[222:225], v[76:79]
	v_mfma_f32_16x16x32_bf16 v[72:75], v[136:139], v[222:225], v[72:75]
	s_setprio 0
	s_setprio 1
	v_mfma_f32_16x16x32_bf16 v[116:119], v[144:147], v[160:163], v[116:119]
	v_mfma_f32_16x16x32_bf16 v[112:115], v[152:155], v[160:163], v[112:115]
	v_mfma_f32_16x16x32_bf16 v[100:103], v[144:147], v[168:171], v[100:103]
	v_mfma_f32_16x16x32_bf16 v[96:99], v[152:155], v[168:171], v[96:99]
	v_mfma_f32_16x16x32_bf16 v[84:87], v[144:147], v[176:179], v[84:87]
	v_mfma_f32_16x16x32_bf16 v[80:83], v[152:155], v[176:179], v[80:83]
	v_mfma_f32_16x16x32_bf16 v[68:71], v[144:147], v[184:187], v[68:71]
	v_mfma_f32_16x16x32_bf16 v[64:67], v[152:155], v[184:187], v[64:67]
	v_mfma_f32_16x16x32_bf16 v[116:119], v[148:151], v[164:167], v[116:119]
	v_mfma_f32_16x16x32_bf16 v[112:115], v[156:159], v[164:167], v[112:115]
	v_mfma_f32_16x16x32_bf16 v[100:103], v[148:151], v[172:175], v[100:103]
	v_mfma_f32_16x16x32_bf16 v[96:99], v[156:159], v[172:175], v[96:99]
	v_mfma_f32_16x16x32_bf16 v[84:87], v[148:151], v[180:183], v[84:87]
	v_mfma_f32_16x16x32_bf16 v[80:83], v[156:159], v[180:183], v[80:83]
	v_mfma_f32_16x16x32_bf16 v[68:71], v[148:151], v[222:225], v[68:71]
	v_mfma_f32_16x16x32_bf16 v[64:67], v[156:159], v[222:225], v[64:67]
	s_barrier
; #define PG8_STAGE(bufoff, gbase, voff) do { _Pragma("unroll") for (int _i = 0; _i < 2; ++_i) \
;         __builtin_amdgcn_global_load_lds((const unsigned*)((const char*)(gbase) + (voff)[_i]), (PG8_LAS unsigned*)(lds + (bufoff) + ldsw + _i * 8192), 16, 0, 0); } while (0)
; #define PG8_LDA(dst, b, h) do { _Pragma("unroll") for (int m = 0; m < 4; ++m) _Pragma("unroll") for (int k = 0; k < 2; ++k) dst[m][k] = *(const PG8_LAS bf16x8*)(lds + PG8_SA(b, h) + aoff + m * 2048 + k * 1024); } while (0)
; #define PG8_MMA(ai, bj, At, Bt) do { __builtin_amdgcn_s_setprio(1); _Pragma("unroll") for (int m = 0; m < 4; ++m) _Pragma("unroll") for (int n = 0; n < 2; ++n) _Pragma("unroll") for (int k = 0; k < 2; ++k) \
;         acc[ai][bj][m][n] = __builtin_amdgcn_mfma_f32_16x16x32_bf16(Bt[n][k], At[m][k], acc[ai][bj][m][n], 0, 0, 0); __builtin_amdgcn_s_setprio(0); } while (0)
; #define PG8_WAIT_V(n) asm volatile("s_waitcnt vmcnt(" #n ")" ::: "memory")
; #define PG8_WAIT_L(n) asm volatile("s_waitcnt lgkmcnt(" #n ")" ::: "memory")
; #define PG8_BAR __builtin_amdgcn_s_barrier()
; #define PG8_SCHED __builtin_amdgcn_sched_barrier(0)
; template <class Epi>
; __device__ __forceinline__ void gemm_phase(PG8_LAS unsigned char* lds, PG8_LAS unsigned char* xl, const Gemm g, const Sched& S, const Epi& E, const int wid) {
;     ...
;             PG8_LDA(At, 1, 1); PG8_STAGE(PG8_SB(1, 0), b3, voffB); PG8_STAGE(PG8_SB(1, 1), b3 + hstepB, voffB); PG8_STAGE(PG8_SA(1, 0), a3, voffA);
;             PG8_WAIT_V(8); PG8_WAIT_L(0); PG8_BAR; if (do1) { PG8_MMA(1, 0, At, B0); PG8_MMA(1, 1, At, B1); } PG8_BAR; PG8_SCHED;
;         }
	s_setprio 0
	s_add_i32 s21, s21, s29
	s_mov_b32 m0, s21
	ds_read_b128 v[160:163], v220 offset:49152
	ds_read_b128 v[164:167], v220 offset:50176
	ds_read_b128 v[168:171], v220 offset:51200
	ds_read_b128 v[172:175], v220 offset:52224
	ds_read_b128 v[176:179], v220 offset:53248
	ds_read_b128 v[180:183], v220 offset:54272
	ds_read_b128 v[184:187], v220 offset:55296
	ds_read_b128 v[222:225], v220 offset:56320
	global_load_lds_dwordx4 v205, s[44:45]
	s_add_i32 m0, s21, 0x2000
	s_add_u32 s100, s44, 0x80080
	global_load_lds_dwordx4 v219, s[44:45]
	s_addc_u32 s101, s45, 0
	s_add_i32 s21, s31, s29
	s_mov_b32 m0, s21
	s_nop 0
	global_load_lds_dwordx4 v190, s[100:101]
	s_add_i32 m0, s21, 0x2000
	s_nop 0
	global_load_lds_dwordx4 v212, s[100:101]
	s_mov_b32 m0, s66
	s_nop 0
	global_load_lds_dwordx4 v204, s[48:49]
	s_mov_b32 m0, s67
	s_nop 0
	global_load_lds_dwordx4 v218, s[48:49]
	s_waitcnt vmcnt(8)
	s_waitcnt lgkmcnt(0)
	s_setprio 1
	s_barrier
	v_mfma_f32_16x16x32_bf16 v[60:63], v[120:123], v[160:163], v[60:63]
	v_mfma_f32_16x16x32_bf16 v[56:59], v[128:131], v[160:163], v[56:59]
	v_mfma_f32_16x16x32_bf16 v[44:47], v[120:123], v[168:171], v[44:47]
	v_mfma_f32_16x16x32_bf16 v[40:43], v[128:131], v[168:171], v[40:43]
	v_mfma_f32_16x16x32_bf16 v[28:31], v[120:123], v[176:179], v[28:31]
	v_mfma_f32_16x16x32_bf16 v[24:27], v[128:131], v[176:179], v[24:27]
	v_mfma_f32_16x16x32_bf16 v[12:15], v[120:123], v[184:187], v[12:15]
	v_mfma_f32_16x16x32_bf16 v[8:11], v[128:131], v[184:187], v[8:11]
	v_mfma_f32_16x16x32_bf16 v[60:63], v[124:127], v[164:167], v[60:63]
	v_mfma_f32_16x16x32_bf16 v[56:59], v[136:139], v[164:167], v[56:59]
	v_mfma_f32_16x16x32_bf16 v[44:47], v[124:127], v[172:175], v[44:47]
	v_mfma_f32_16x16x32_bf16 v[40:43], v[136:139], v[172:175], v[40:43]
	v_mfma_f32_16x16x32_bf16 v[28:31], v[124:127], v[180:183], v[28:31]
	v_mfma_f32_16x16x32_bf16 v[24:27], v[136:139], v[180:183], v[24:27]
	v_mfma_f32_16x16x32_bf16 v[12:15], v[124:127], v[222:225], v[12:15]
	v_mfma_f32_16x16x32_bf16 v[8:11], v[136:139], v[222:225], v[8:11]
	s_setprio 0
	s_setprio 1
	v_mfma_f32_16x16x32_bf16 v[52:55], v[144:147], v[160:163], v[52:55]
	v_mfma_f32_16x16x32_bf16 v[48:51], v[152:155], v[160:163], v[48:51]
	v_mfma_f32_16x16x32_bf16 v[36:39], v[144:147], v[168:171], v[36:39]
	v_mfma_f32_16x16x32_bf16 v[32:35], v[152:155], v[168:171], v[32:35]
	v_mfma_f32_16x16x32_bf16 v[20:23], v[144:147], v[176:179], v[20:23]
	v_mfma_f32_16x16x32_bf16 v[16:19], v[152:155], v[176:179], v[16:19]
	v_mfma_f32_16x16x32_bf16 v[4:7], v[144:147], v[184:187], v[4:7]
	v_mfma_f32_16x16x32_bf16 v[0:3], v[152:155], v[184:187], v[0:3]
	v_mfma_f32_16x16x32_bf16 v[52:55], v[148:151], v[164:167], v[52:55]
	v_mfma_f32_16x16x32_bf16 v[48:51], v[156:159], v[164:167], v[48:51]
	v_mfma_f32_16x16x32_bf16 v[36:39], v[148:151], v[172:175], v[36:39]
	v_mfma_f32_16x16x32_bf16 v[32:35], v[156:159], v[172:175], v[32:35]
	v_mfma_f32_16x16x32_bf16 v[20:23], v[148:151], v[180:183], v[20:23]
	v_mfma_f32_16x16x32_bf16 v[16:19], v[156:159], v[180:183], v[16:19]
	v_mfma_f32_16x16x32_bf16 v[4:7], v[148:151], v[222:225], v[4:7]
	v_mfma_f32_16x16x32_bf16 v[0:3], v[156:159], v[222:225], v[0:3]
	s_barrier
	s_setprio 0
	s_add_i32 s13, s13, 2
	s_add_u32 s42, s42, 0x100
	s_addc_u32 s43, s43, 0
	s_add_u32 s10, s10, 0x100
	s_addc_u32 s11, s11, 0
	s_cmp_gt_u32 s13, 29
	s_cbranch_scc0 .LBB0_765
	s_mov_b32 s100, 0
	s_and_b64 vcc, exec, s[14:15]
	s_cbranch_vccz .LBB0_768
	s_barrier

; __device__ __forceinline__ const char* a_tile(const Gemm& g, const Unit& u) { return (const char*)(g.A + ((long)u.z1 * g.aS1 + (long)u.z2 * g.aS2 + (long)u.pm * BM * g.lda)); }
; __device__ __forceinline__ const char* b_tile(const Gemm& g, const Unit& u) { return (const char*)(g.Bt + ((long)u.z1 * g.bS1 + (long)u.z2 * g.bS2 + (long)u.pn * BM * g.ldb)); }
; __device__ __forceinline__ int lane_id_opq() { int l; asm volatile("v_mbcnt_lo_u32_b32 %0, -1, 0\n\tv_mbcnt_hi_u32_b32 %0, -1, %0" : "=v"(l)); return l; }
; #define PG8_LDA(dst, b, h) do { _Pragma("unroll") for (int m = 0; m < 4; ++m) _Pragma("unroll") for (int k = 0; k < 2; ++k) dst[m][k] = *(const PG8_LAS bf16x8*)(lds + PG8_SA(b, h) + aoff + m * 2048 + k * 1024); } while (0)
; template <class Epi>
; __device__ __forceinline__ void gemm_phase(PG8_LAS unsigned char* lds, PG8_LAS unsigned char* xl, const Gemm g, const Sched& S, const Epi& E, const int wid) {
;     ...
;         const bool has_next = S.next(ui + 1, nxt);
;         const char* nA = has_next ? a_tile(g, nxt) : cA; const char* nB = has_next ? b_tile(g, nxt) : cB;
;         for (int t = 0; t < nt; t += 2) {
;             const bool last = (t == nt - 2);
;             const bool do0 = !blkdiag_v<Epi> || t == 0, do1 = !blkdiag_v<Epi> || t != 0;
;             long j1 = 0, ja2 = 0, jb2 = 0;
;             if constexpr (Epi::MID) {
;                 if (t == g.tj) { const int lnM = lane_id_opq(); E.mid(acc, cur, wr, wc, lnM & 15, lnM >> 4); }
;                 if (t >= g.tj) j1 = g.jA;
;                 if (t + 2 >= g.tj) { ja2 = g.jA; jb2 = g.jB; } }
;             const char* a1 = cA + (size_t)(t + 1) * kstep + j1;
;             const char* a2 = last ? nA : cA + (size_t)(t + 2) * kstep + ja2; const char* b2 = last ? nB : cB + (size_t)(t + 2) * kstep + jb2;
;             const char* a3 = a2 + kstep; const char* b3 = b2 + kstep;
;             PG8_LDB(B0, 0, 0); PG8_LDB(B1, 0, 1); PG8_SCHED; PG8_LDA(At, 0, 0); PG8_STAGE(PG8_SA(1, 1), a1 + hstepA, voffA);
;             PG8_WAIT_V(8); PG8_WAIT_L(0); PG8_BAR; if (do0) { PG8_MMA(0, 0, At, B0); PG8_MMA(0, 1, At, B1); } PG8_BAR; PG8_SCHED;
;             PG8_LDA(At, 0, 1); PG8_STAGE(PG8_SB(0, 0), b2, voffB); PG8_STAGE(PG8_SB(0, 1), b2 + hstepB, voffB); PG8_STAGE(PG8_SA(0, 0), a2, voffA);
;             PG8_WAIT_V(8); PG8_WAIT_L(0); PG8_BAR; if (do1) { PG8_MMA(1, 0, At, B0); PG8_MMA(1, 1, At, B1); } PG8_BAR; PG8_SCHED;
.Ldefbar_skip_7:
	v_add_u32_e32 v204, s22, v184
	v_add_u32_e32 v205, s22, v186
	v_add_u32_e32 v214, s22, v188
	v_add_u32_e32 v215, s22, v190
.LBB0_859:
	s_add_u32 s46, s48, 0x100
	s_addc_u32 s47, s49, 0
	s_add_i32 s11, 0, 0x10000
	s_cmp_eq_u32 s10, 28
	s_cselect_b32 vcc_hi, s59, s47
	s_cselect_b32 vcc_lo, s58, s46
	s_cselect_b32 s51, s21, s9
	s_cselect_b32 s50, s20, s8
	s_add_i32 s13, 0, 0x14000
	v_add_u32_e32 v140, s11, v195
	v_add_u32_e32 v156, s13, v195
	ds_read_b128 v[120:123], v140
	ds_read_b128 v[124:127], v140 offset:1024
	ds_read_b128 v[136:139], v140 offset:2048
	ds_read_b128 v[140:143], v140 offset:3072
	ds_read_b128 v[144:147], v156
	ds_read_b128 v[148:151], v156 offset:1024
	ds_read_b128 v[152:155], v156 offset:2048
	ds_read_b128 v[156:159], v156 offset:3072
	s_add_i32 m0, s89, 0xc000
	ds_read_b128 v[160:163], v216
	ds_read_b128 v[164:167], v216 offset:1024
	ds_read_b128 v[168:171], v216 offset:2048
	ds_read_b128 v[172:175], v216 offset:3072
	ds_read_b128 v[176:179], v216 offset:4096
	ds_read_b128 v[180:183], v216 offset:5120
	ds_read_b128 v[218:221], v216 offset:6144
	ds_read_b128 v[222:225], v216 offset:7168
	global_load_lds_dwordx4 v210, s[48:49]
	s_add_i32 m0, s89, 0xe000
	s_nop 0
	global_load_lds_dwordx4 v212, s[48:49]
	s_waitcnt vmcnt(8)
	s_waitcnt lgkmcnt(0)
	s_setprio 1
	s_barrier
	v_mfma_f32_16x16x32_bf16 v[132:135], v[120:123], v[160:163], v[132:135]
	v_mfma_f32_16x16x32_bf16 v[128:131], v[136:139], v[160:163], v[128:131]
	v_mfma_f32_16x16x32_bf16 v[108:111], v[120:123], v[168:171], v[108:111]
	v_mfma_f32_16x16x32_bf16 v[104:107], v[136:139], v[168:171], v[104:107]
	v_mfma_f32_16x16x32_bf16 v[92:95], v[120:123], v[176:179], v[92:95]
	v_mfma_f32_16x16x32_bf16 v[88:91], v[136:139], v[176:179], v[88:91]
	v_mfma_f32_16x16x32_bf16 v[76:79], v[120:123], v[218:221], v[76:79]
	v_mfma_f32_16x16x32_bf16 v[72:75], v[136:139], v[218:221], v[72:75]
	v_mfma_f32_16x16x32_bf16 v[132:135], v[124:127], v[164:167], v[132:135]
	v_mfma_f32_16x16x32_bf16 v[128:131], v[140:143], v[164:167], v[128:131]
	v_mfma_f32_16x16x32_bf16 v[108:111], v[124:127], v[172:175], v[108:111]
	v_mfma_f32_16x16x32_bf16 v[104:107], v[140:143], v[172:175], v[104:107]
	v_mfma_f32_16x16x32_bf16 v[92:95], v[124:127], v[180:183], v[92:95]
	v_mfma_f32_16x16x32_bf16 v[88:91], v[140:143], v[180:183], v[88:91]
	v_mfma_f32_16x16x32_bf16 v[76:79], v[124:127], v[222:225], v[76:79]
	v_mfma_f32_16x16x32_bf16 v[72:75], v[140:143], v[222:225], v[72:75]
	s_setprio 0
	s_setprio 1
	v_mfma_f32_16x16x32_bf16 v[116:119], v[144:147], v[160:163], v[116:119]
	v_mfma_f32_16x16x32_bf16 v[112:115], v[152:155], v[160:163], v[112:115]
	v_mfma_f32_16x16x32_bf16 v[100:103], v[144:147], v[168:171], v[100:103]
	v_mfma_f32_16x16x32_bf16 v[96:99], v[152:155], v[168:171], v[96:99]
	v_mfma_f32_16x16x32_bf16 v[84:87], v[144:147], v[176:179], v[84:87]
	v_mfma_f32_16x16x32_bf16 v[80:83], v[152:155], v[176:179], v[80:83]
	v_mfma_f32_16x16x32_bf16 v[68:71], v[144:147], v[218:221], v[68:71]
	v_mfma_f32_16x16x32_bf16 v[64:67], v[152:155], v[218:221], v[64:67]
	v_mfma_f32_16x16x32_bf16 v[116:119], v[148:151], v[164:167], v[116:119]
	v_mfma_f32_16x16x32_bf16 v[112:115], v[156:159], v[164:167], v[112:115]
	v_mfma_f32_16x16x32_bf16 v[100:103], v[148:151], v[172:175], v[100:103]
	v_mfma_f32_16x16x32_bf16 v[96:99], v[156:159], v[172:175], v[96:99]
	v_mfma_f32_16x16x32_bf16 v[84:87], v[148:151], v[180:183], v[84:87]
	v_mfma_f32_16x16x32_bf16 v[80:83], v[156:159], v[180:183], v[80:83]
	v_mfma_f32_16x16x32_bf16 v[68:71], v[148:151], v[222:225], v[68:71]
	v_mfma_f32_16x16x32_bf16 v[64:67], v[156:159], v[222:225], v[64:67]
	s_barrier
	s_setprio 0
	s_add_i32 s11, s11, s29
	s_mov_b32 m0, s11
	ds_read_b128 v[160:163], v216 offset:16384
	ds_read_b128 v[164:167], v216 offset:17408
	ds_read_b128 v[168:171], v216 offset:18432
	ds_read_b128 v[172:175], v216 offset:19456
	ds_read_b128 v[176:179], v216 offset:20480
	ds_read_b128 v[180:183], v216 offset:21504
	ds_read_b128 v[218:221], v216 offset:22528
	ds_read_b128 v[222:225], v216 offset:23552
	global_load_lds_dwordx4 v186, s[50:51]
	s_add_i32 m0, s11, 0x2000
	s_add_u32 s48, s50, 0x80000
	s_addc_u32 s49, s51, 0
	s_add_i32 s11, s13, s29
	global_load_lds_dwordx4 v190, s[50:51]
	s_mov_b32 m0, s11
	s_nop 0
	global_load_lds_dwordx4 v186, s[48:49]
	s_add_i32 m0, s11, 0x2000
	s_nop 0
	global_load_lds_dwordx4 v190, s[48:49]
	s_mov_b32 m0, s89
	s_nop 0
	global_load_lds_dwordx4 v184, vcc
	s_mov_b32 m0, s90
	s_nop 0
	global_load_lds_dwordx4 v188, vcc
	s_waitcnt vmcnt(8)
	s_waitcnt lgkmcnt(0)
	s_setprio 1
	s_barrier
; #define PG8_STAGE(bufoff, gbase, voff) do { _Pragma("unroll") for (int _i = 0; _i < 2; ++_i) \
;         __builtin_amdgcn_global_load_lds((const unsigned*)((const char*)(gbase) + (voff)[_i]), (PG8_LAS unsigned*)(lds + (bufoff) + ldsw + _i * 8192), 16, 0, 0); } while (0)
; #define PG8_LDA(dst, b, h) do { _Pragma("unroll") for (int m = 0; m < 4; ++m) _Pragma("unroll") for (int k = 0; k < 2; ++k) dst[m][k] = *(const PG8_LAS bf16x8*)(lds + PG8_SA(b, h) + aoff + m * 2048 + k * 1024); } while (0)
; #define PG8_LDB(dst, b, h) do { _Pragma("unroll") for (int n = 0; n < 2; ++n) _Pragma("unroll") for (int k = 0; k < 2; ++k) dst[n][k] = *(const PG8_LAS bf16x8*)(lds + PG8_SB(b, h) + boff + n * 2048 + k * 1024); } while (0)
; #define PG8_MMA(ai, bj, At, Bt) do { __builtin_amdgcn_s_setprio(1); _Pragma("unroll") for (int m = 0; m < 4; ++m) _Pragma("unroll") for (int n = 0; n < 2; ++n) _Pragma("unroll") for (int k = 0; k < 2; ++k) \
;         acc[ai][bj][m][n] = __builtin_amdgcn_mfma_f32_16x16x32_bf16(Bt[n][k], At[m][k], acc[ai][bj][m][n], 0, 0, 0); __builtin_amdgcn_s_setprio(0); } while (0)
; #define PG8_WAIT_V(n) asm volatile("s_waitcnt vmcnt(" #n ")" ::: "memory")
; #define PG8_WAIT_L(n) asm volatile("s_waitcnt lgkmcnt(" #n ")" ::: "memory")
; #define PG8_BAR __builtin_amdgcn_s_barrier()
; #define PG8_SCHED __builtin_amdgcn_sched_barrier(0)
; template <class Epi>
; __device__ __forceinline__ void gemm_phase(PG8_LAS unsigned char* lds, PG8_LAS unsigned char* xl, const Gemm g, const Sched& S, const Epi& E, const int wid) {
;     ...
;             PG8_WAIT_V(8); PG8_WAIT_L(0); PG8_BAR; if (do1) { PG8_MMA(1, 0, At, B0); PG8_MMA(1, 1, At, B1); } PG8_BAR; PG8_SCHED;
;             PG8_LDB(B0, 1, 0); PG8_LDB(B1, 1, 1); PG8_SCHED; PG8_LDA(At, 1, 0); PG8_STAGE(PG8_SA(0, 1), a2 + hstepA, voffA);
;             PG8_WAIT_V(8); PG8_WAIT_L(0); PG8_BAR; if (do0) { PG8_MMA(0, 0, At, B0); PG8_MMA(0, 1, At, B1); } PG8_BAR; PG8_SCHED;
	v_mfma_f32_16x16x32_bf16 v[60:63], v[120:123], v[160:163], v[60:63]
	v_mfma_f32_16x16x32_bf16 v[56:59], v[136:139], v[160:163], v[56:59]
	v_mfma_f32_16x16x32_bf16 v[44:47], v[120:123], v[168:171], v[44:47]
	v_mfma_f32_16x16x32_bf16 v[40:43], v[136:139], v[168:171], v[40:43]
	v_mfma_f32_16x16x32_bf16 v[28:31], v[120:123], v[176:179], v[28:31]
	v_mfma_f32_16x16x32_bf16 v[24:27], v[136:139], v[176:179], v[24:27]
	v_mfma_f32_16x16x32_bf16 v[12:15], v[120:123], v[218:221], v[12:15]
	v_mfma_f32_16x16x32_bf16 v[8:11], v[136:139], v[218:221], v[8:11]
	v_mfma_f32_16x16x32_bf16 v[60:63], v[124:127], v[164:167], v[60:63]
	v_mfma_f32_16x16x32_bf16 v[56:59], v[140:143], v[164:167], v[56:59]
	v_mfma_f32_16x16x32_bf16 v[44:47], v[124:127], v[172:175], v[44:47]
	v_mfma_f32_16x16x32_bf16 v[40:43], v[140:143], v[172:175], v[40:43]
	v_mfma_f32_16x16x32_bf16 v[28:31], v[124:127], v[180:183], v[28:31]
	v_mfma_f32_16x16x32_bf16 v[24:27], v[140:143], v[180:183], v[24:27]
	v_mfma_f32_16x16x32_bf16 v[12:15], v[124:127], v[222:225], v[12:15]
	v_mfma_f32_16x16x32_bf16 v[8:11], v[140:143], v[222:225], v[8:11]
	s_setprio 0
	s_setprio 1
	v_mfma_f32_16x16x32_bf16 v[52:55], v[144:147], v[160:163], v[52:55]
	v_mfma_f32_16x16x32_bf16 v[48:51], v[152:155], v[160:163], v[48:51]
	v_mfma_f32_16x16x32_bf16 v[36:39], v[144:147], v[168:171], v[36:39]
	v_mfma_f32_16x16x32_bf16 v[32:35], v[152:155], v[168:171], v[32:35]
	v_mfma_f32_16x16x32_bf16 v[20:23], v[144:147], v[176:179], v[20:23]
	v_mfma_f32_16x16x32_bf16 v[16:19], v[152:155], v[176:179], v[16:19]
	v_mfma_f32_16x16x32_bf16 v[4:7], v[144:147], v[218:221], v[4:7]
	v_mfma_f32_16x16x32_bf16 v[0:3], v[152:155], v[218:221], v[0:3]
	v_mfma_f32_16x16x32_bf16 v[52:55], v[148:151], v[164:167], v[52:55]
	v_mfma_f32_16x16x32_bf16 v[48:51], v[156:159], v[164:167], v[48:51]
	v_mfma_f32_16x16x32_bf16 v[36:39], v[148:151], v[172:175], v[36:39]
	v_mfma_f32_16x16x32_bf16 v[32:35], v[156:159], v[172:175], v[32:35]
	v_mfma_f32_16x16x32_bf16 v[20:23], v[148:151], v[180:183], v[20:23]
	v_mfma_f32_16x16x32_bf16 v[16:19], v[156:159], v[180:183], v[16:19]
	v_mfma_f32_16x16x32_bf16 v[4:7], v[148:151], v[222:225], v[4:7]
	v_mfma_f32_16x16x32_bf16 v[0:3], v[156:159], v[222:225], v[0:3]
	s_barrier
	s_setprio 0
	s_add_i32 s11, 0, 0x18000
	s_add_i32 s13, 0, 0x1c000
	v_add_u32_e32 v140, s11, v195
	v_add_u32_e32 v156, s13, v195
	ds_read_b128 v[120:123], v140
	ds_read_b128 v[124:127], v140 offset:1024
	ds_read_b128 v[136:139], v140 offset:2048
	ds_read_b128 v[140:143], v140 offset:3072
	ds_read_b128 v[144:147], v156
	ds_read_b128 v[148:151], v156 offset:1024
	ds_read_b128 v[152:155], v156 offset:2048
	ds_read_b128 v[156:159], v156 offset:3072
	s_add_u32 s48, vcc_lo, 0x80000
	s_addc_u32 s49, vcc_hi, 0
	s_mov_b32 m0, s91
	ds_read_b128 v[160:163], v216 offset:32768
	ds_read_b128 v[164:167], v216 offset:33792
	ds_read_b128 v[168:171], v216 offset:34816
	ds_read_b128 v[172:175], v216 offset:35840
	ds_read_b128 v[176:179], v216 offset:36864
	ds_read_b128 v[180:183], v216 offset:37888
	ds_read_b128 v[218:221], v216 offset:38912
	ds_read_b128 v[222:225], v216 offset:39936
	global_load_lds_dwordx4 v184, s[48:49]
	s_mov_b32 m0, s92
	s_nop 0
	global_load_lds_dwordx4 v188, s[48:49]
	s_waitcnt vmcnt(8)
	s_waitcnt lgkmcnt(0)
	s_setprio 1
	s_barrier
	v_mfma_f32_16x16x32_bf16 v[132:135], v[120:123], v[160:163], v[132:135]
	v_mfma_f32_16x16x32_bf16 v[128:131], v[136:139], v[160:163], v[128:131]
	v_mfma_f32_16x16x32_bf16 v[108:111], v[120:123], v[168:171], v[108:111]
	v_mfma_f32_16x16x32_bf16 v[104:107], v[136:139], v[168:171], v[104:107]
	v_mfma_f32_16x16x32_bf16 v[92:95], v[120:123], v[176:179], v[92:95]
	v_mfma_f32_16x16x32_bf16 v[88:91], v[136:139], v[176:179], v[88:91]
	v_mfma_f32_16x16x32_bf16 v[76:79], v[120:123], v[218:221], v[76:79]
	v_mfma_f32_16x16x32_bf16 v[72:75], v[136:139], v[218:221], v[72:75]
	v_mfma_f32_16x16x32_bf16 v[132:135], v[124:127], v[164:167], v[132:135]
	v_mfma_f32_16x16x32_bf16 v[128:131], v[140:143], v[164:167], v[128:131]
	v_mfma_f32_16x16x32_bf16 v[108:111], v[124:127], v[172:175], v[108:111]
	v_mfma_f32_16x16x32_bf16 v[104:107], v[140:143], v[172:175], v[104:107]
	v_mfma_f32_16x16x32_bf16 v[92:95], v[124:127], v[180:183], v[92:95]
	v_mfma_f32_16x16x32_bf16 v[88:91], v[140:143], v[180:183], v[88:91]
	v_mfma_f32_16x16x32_bf16 v[76:79], v[124:127], v[222:225], v[76:79]
	v_mfma_f32_16x16x32_bf16 v[72:75], v[140:143], v[222:225], v[72:75]
	s_setprio 0
	s_setprio 1
	v_mfma_f32_16x16x32_bf16 v[116:119], v[144:147], v[160:163], v[116:119]
	v_mfma_f32_16x16x32_bf16 v[112:115], v[152:155], v[160:163], v[112:115]
	v_mfma_f32_16x16x32_bf16 v[100:103], v[144:147], v[168:171], v[100:103]
	v_mfma_f32_16x16x32_bf16 v[96:99], v[152:155], v[168:171], v[96:99]
	v_mfma_f32_16x16x32_bf16 v[84:87], v[144:147], v[176:179], v[84:87]
	v_mfma_f32_16x16x32_bf16 v[80:83], v[152:155], v[176:179], v[80:83]
	v_mfma_f32_16x16x32_bf16 v[68:71], v[144:147], v[218:221], v[68:71]
	v_mfma_f32_16x16x32_bf16 v[64:67], v[152:155], v[218:221], v[64:67]
	v_mfma_f32_16x16x32_bf16 v[116:119], v[148:151], v[164:167], v[116:119]
	v_mfma_f32_16x16x32_bf16 v[112:115], v[156:159], v[164:167], v[112:115]
	v_mfma_f32_16x16x32_bf16 v[100:103], v[148:151], v[172:175], v[100:103]
	v_mfma_f32_16x16x32_bf16 v[96:99], v[156:159], v[172:175], v[96:99]
	v_mfma_f32_16x16x32_bf16 v[84:87], v[148:151], v[180:183], v[84:87]
	v_mfma_f32_16x16x32_bf16 v[80:83], v[156:159], v[180:183], v[80:83]
	v_mfma_f32_16x16x32_bf16 v[68:71], v[148:151], v[222:225], v[68:71]
	v_mfma_f32_16x16x32_bf16 v[64:67], v[156:159], v[222:225], v[64:67]
	s_barrier
; #define PG8_STAGE(bufoff, gbase, voff) do { _Pragma("unroll") for (int _i = 0; _i < 2; ++_i) \
;         __builtin_amdgcn_global_load_lds((const unsigned*)((const char*)(gbase) + (voff)[_i]), (PG8_LAS unsigned*)(lds + (bufoff) + ldsw + _i * 8192), 16, 0, 0); } while (0)
; #define PG8_LDA(dst, b, h) do { _Pragma("unroll") for (int m = 0; m < 4; ++m) _Pragma("unroll") for (int k = 0; k < 2; ++k) dst[m][k] = *(const PG8_LAS bf16x8*)(lds + PG8_SA(b, h) + aoff + m * 2048 + k * 1024); } while (0)
; #define PG8_MMA(ai, bj, At, Bt) do { __builtin_amdgcn_s_setprio(1); _Pragma("unroll") for (int m = 0; m < 4; ++m) _Pragma("unroll") for (int n = 0; n < 2; ++n) _Pragma("unroll") for (int k = 0; k < 2; ++k) \
;         acc[ai][bj][m][n] = __builtin_amdgcn_mfma_f32_16x16x32_bf16(Bt[n][k], At[m][k], acc[ai][bj][m][n], 0, 0, 0); __builtin_amdgcn_s_setprio(0); } while (0)
; #define PG8_WAIT_V(n) asm volatile("s_waitcnt vmcnt(" #n ")" ::: "memory")
; #define PG8_WAIT_L(n) asm volatile("s_waitcnt lgkmcnt(" #n ")" ::: "memory")
; #define PG8_BAR __builtin_amdgcn_s_barrier()
; #define PG8_SCHED __builtin_amdgcn_sched_barrier(0)
; template <class Epi>
; __device__ __forceinline__ void gemm_phase(PG8_LAS unsigned char* lds, PG8_LAS unsigned char* xl, const Gemm g, const Sched& S, const Epi& E, const int wid) {
;     ...
;             PG8_LDA(At, 1, 1); PG8_STAGE(PG8_SB(1, 0), b3, voffB); PG8_STAGE(PG8_SB(1, 1), b3 + hstepB, voffB); PG8_STAGE(PG8_SA(1, 0), a3, voffA);
;             PG8_WAIT_V(8); PG8_WAIT_L(0); PG8_BAR; if (do1) { PG8_MMA(1, 0, At, B0); PG8_MMA(1, 1, At, B1); } PG8_BAR; PG8_SCHED;
;         }
	s_setprio 0
	s_add_i32 s11, s11, s29
	s_mov_b32 m0, s11
	ds_read_b128 v[160:163], v216 offset:49152
	ds_read_b128 v[164:167], v216 offset:50176
	ds_read_b128 v[168:171], v216 offset:51200
	ds_read_b128 v[172:175], v216 offset:52224
	ds_read_b128 v[176:179], v216 offset:53248
	ds_read_b128 v[180:183], v216 offset:54272
	ds_read_b128 v[218:221], v216 offset:55296
	ds_read_b128 v[222:225], v216 offset:56320
	global_load_lds_dwordx4 v205, s[50:51]
	s_add_i32 m0, s11, 0x2000
	s_add_u32 s48, s50, 0x80080
	global_load_lds_dwordx4 v215, s[50:51]
	s_addc_u32 s49, s51, 0
	s_add_i32 s11, s13, s29
	s_mov_b32 m0, s11
	s_nop 0
	global_load_lds_dwordx4 v186, s[48:49]
	s_add_i32 m0, s11, 0x2000
	s_nop 0
	global_load_lds_dwordx4 v190, s[48:49]
	s_mov_b32 m0, s95
	s_nop 0
	global_load_lds_dwordx4 v204, vcc
	s_mov_b32 m0, s96
	s_nop 0
	global_load_lds_dwordx4 v214, vcc
	s_waitcnt vmcnt(8)
	s_waitcnt lgkmcnt(0)
	s_setprio 1
	s_barrier
	v_mfma_f32_16x16x32_bf16 v[60:63], v[120:123], v[160:163], v[60:63]
	v_mfma_f32_16x16x32_bf16 v[56:59], v[136:139], v[160:163], v[56:59]
	v_mfma_f32_16x16x32_bf16 v[44:47], v[120:123], v[168:171], v[44:47]
	v_mfma_f32_16x16x32_bf16 v[40:43], v[136:139], v[168:171], v[40:43]
	v_mfma_f32_16x16x32_bf16 v[28:31], v[120:123], v[176:179], v[28:31]
	v_mfma_f32_16x16x32_bf16 v[24:27], v[136:139], v[176:179], v[24:27]
	v_mfma_f32_16x16x32_bf16 v[12:15], v[120:123], v[218:221], v[12:15]
	v_mfma_f32_16x16x32_bf16 v[8:11], v[136:139], v[218:221], v[8:11]
	v_mfma_f32_16x16x32_bf16 v[60:63], v[124:127], v[164:167], v[60:63]
	v_mfma_f32_16x16x32_bf16 v[56:59], v[140:143], v[164:167], v[56:59]
	v_mfma_f32_16x16x32_bf16 v[44:47], v[124:127], v[172:175], v[44:47]
	v_mfma_f32_16x16x32_bf16 v[40:43], v[140:143], v[172:175], v[40:43]
	v_mfma_f32_16x16x32_bf16 v[28:31], v[124:127], v[180:183], v[28:31]
	v_mfma_f32_16x16x32_bf16 v[24:27], v[140:143], v[180:183], v[24:27]
	v_mfma_f32_16x16x32_bf16 v[12:15], v[124:127], v[222:225], v[12:15]
	v_mfma_f32_16x16x32_bf16 v[8:11], v[140:143], v[222:225], v[8:11]
	s_setprio 0
	s_setprio 1
	v_mfma_f32_16x16x32_bf16 v[52:55], v[144:147], v[160:163], v[52:55]
	v_mfma_f32_16x16x32_bf16 v[48:51], v[152:155], v[160:163], v[48:51]
	v_mfma_f32_16x16x32_bf16 v[36:39], v[144:147], v[168:171], v[36:39]
	v_mfma_f32_16x16x32_bf16 v[32:35], v[152:155], v[168:171], v[32:35]
	v_mfma_f32_16x16x32_bf16 v[20:23], v[144:147], v[176:179], v[20:23]
	v_mfma_f32_16x16x32_bf16 v[16:19], v[152:155], v[176:179], v[16:19]
	v_mfma_f32_16x16x32_bf16 v[4:7], v[144:147], v[218:221], v[4:7]
	v_mfma_f32_16x16x32_bf16 v[0:3], v[152:155], v[218:221], v[0:3]
	v_mfma_f32_16x16x32_bf16 v[52:55], v[148:151], v[164:167], v[52:55]
	v_mfma_f32_16x16x32_bf16 v[48:51], v[156:159], v[164:167], v[48:51]
	v_mfma_f32_16x16x32_bf16 v[36:39], v[148:151], v[172:175], v[36:39]
	v_mfma_f32_16x16x32_bf16 v[32:35], v[156:159], v[172:175], v[32:35]
	v_mfma_f32_16x16x32_bf16 v[20:23], v[148:151], v[180:183], v[20:23]
	v_mfma_f32_16x16x32_bf16 v[16:19], v[156:159], v[180:183], v[16:19]
	v_mfma_f32_16x16x32_bf16 v[4:7], v[148:151], v[222:225], v[4:7]
	v_mfma_f32_16x16x32_bf16 v[0:3], v[156:159], v[222:225], v[0:3]
	s_barrier
	s_setprio 0
	s_add_i32 s10, s10, 2
	s_add_u32 s8, s8, 0x100
	s_addc_u32 s9, s9, 0
	s_cmp_gt_u32 s10, 29
	s_mov_b64 s[48:49], s[46:47]
	s_cbranch_scc0 .LBB0_859
	s_and_b64 vcc, exec, s[14:15]
	s_cbranch_vccz .LBB0_862
	s_barrier

; __device__ __forceinline__ const char* a_tile(const Gemm& g, const Unit& u) { return (const char*)(g.A + ((long)u.z1 * g.aS1 + (long)u.z2 * g.aS2 + (long)u.pm * BM * g.lda)); }
; __device__ __forceinline__ const char* b_tile(const Gemm& g, const Unit& u) { return (const char*)(g.Bt + ((long)u.z1 * g.bS1 + (long)u.z2 * g.bS2 + (long)u.pn * BM * g.ldb)); }
; __device__ __forceinline__ int lane_id_opq() { int l; asm volatile("v_mbcnt_lo_u32_b32 %0, -1, 0\n\tv_mbcnt_hi_u32_b32 %0, -1, %0" : "=v"(l)); return l; }
; #define PG8_LDA(dst, b, h) do { _Pragma("unroll") for (int m = 0; m < 4; ++m) _Pragma("unroll") for (int k = 0; k < 2; ++k) dst[m][k] = *(const PG8_LAS bf16x8*)(lds + PG8_SA(b, h) + aoff + m * 2048 + k * 1024); } while (0)
; template <class Epi>
; __device__ __forceinline__ void gemm_phase(PG8_LAS unsigned char* lds, PG8_LAS unsigned char* xl, const Gemm g, const Sched& S, const Epi& E, const int wid) {
;     ...
;         const bool has_next = S.next(ui + 1, nxt);
;         const char* nA = has_next ? a_tile(g, nxt) : cA; const char* nB = has_next ? b_tile(g, nxt) : cB;
;         for (int t = 0; t < nt; t += 2) {
;             const bool last = (t == nt - 2);
;             const bool do0 = !blkdiag_v<Epi> || t == 0, do1 = !blkdiag_v<Epi> || t != 0;
;             long j1 = 0, ja2 = 0, jb2 = 0;
;             if constexpr (Epi::MID) {
;                 if (t == g.tj) { const int lnM = lane_id_opq(); E.mid(acc, cur, wr, wc, lnM & 15, lnM >> 4); }
;                 if (t >= g.tj) j1 = g.jA;
;                 if (t + 2 >= g.tj) { ja2 = g.jA; jb2 = g.jB; } }
;             const char* a1 = cA + (size_t)(t + 1) * kstep + j1;
;             const char* a2 = last ? nA : cA + (size_t)(t + 2) * kstep + ja2; const char* b2 = last ? nB : cB + (size_t)(t + 2) * kstep + jb2;
;             const char* a3 = a2 + kstep; const char* b3 = b2 + kstep;
;             PG8_LDB(B0, 0, 0); PG8_LDB(B1, 0, 1); PG8_SCHED; PG8_LDA(At, 0, 0); PG8_STAGE(PG8_SA(1, 1), a1 + hstepA, voffA);
;             PG8_WAIT_V(8); PG8_WAIT_L(0); PG8_BAR; if (do0) { PG8_MMA(0, 0, At, B0); PG8_MMA(0, 1, At, B1); } PG8_BAR; PG8_SCHED;
;             PG8_LDA(At, 0, 1); PG8_STAGE(PG8_SB(0, 0), b2, voffB); PG8_STAGE(PG8_SB(0, 1), b2 + hstepB, voffB); PG8_STAGE(PG8_SA(0, 0), a2, voffA);
;             PG8_WAIT_V(8); PG8_WAIT_L(0); PG8_BAR; if (do1) { PG8_MMA(1, 0, At, B0); PG8_MMA(1, 1, At, B1); } PG8_BAR; PG8_SCHED;
.LBB0_959:
	s_add_u32 s56, s52, 0x100
	s_addc_u32 s57, s53, 0
	s_add_i32 s11, 0, 0x10000
	s_cmp_eq_u32 s10, 12
	s_cselect_b32 s61, s47, s57
	s_cselect_b32 s60, s46, s56
	s_cselect_b32 s59, s51, s9
	s_cselect_b32 s58, s50, s8
	s_add_i32 s13, 0, 0x14000
	v_add_u32_e32 v140, s11, v195
	v_add_u32_e32 v156, s13, v195
	ds_read_b128 v[124:127], v140
	ds_read_b128 v[128:131], v140 offset:1024
	ds_read_b128 v[136:139], v140 offset:2048
	ds_read_b128 v[140:143], v140 offset:3072
	ds_read_b128 v[144:147], v156
	ds_read_b128 v[148:151], v156 offset:1024
	ds_read_b128 v[152:155], v156 offset:2048
	ds_read_b128 v[156:159], v156 offset:3072
	s_add_i32 m0, s66, 0xc000
	ds_read_b128 v[160:163], v220
	ds_read_b128 v[164:167], v220 offset:1024
	ds_read_b128 v[168:171], v220 offset:2048
	ds_read_b128 v[172:175], v220 offset:3072
	ds_read_b128 v[176:179], v220 offset:4096
	ds_read_b128 v[180:183], v220 offset:5120
	ds_read_b128 v[184:187], v220 offset:6144
	ds_read_b128 v[222:225], v220 offset:7168
	global_load_lds_dwordx4 v214, s[52:53]
	s_add_i32 m0, s66, 0xe000
	s_nop 0
	global_load_lds_dwordx4 v216, s[52:53]
	s_waitcnt vmcnt(8)
	s_waitcnt lgkmcnt(0)
	s_setprio 1
	s_barrier
	v_mfma_f32_16x16x32_bf16 v[132:135], v[124:127], v[160:163], v[132:135]
	v_mfma_f32_16x16x32_bf16 v[120:123], v[136:139], v[160:163], v[120:123]
	v_mfma_f32_16x16x32_bf16 v[108:111], v[124:127], v[168:171], v[108:111]
	v_mfma_f32_16x16x32_bf16 v[104:107], v[136:139], v[168:171], v[104:107]
	v_mfma_f32_16x16x32_bf16 v[92:95], v[124:127], v[176:179], v[92:95]
	v_mfma_f32_16x16x32_bf16 v[88:91], v[136:139], v[176:179], v[88:91]
	v_mfma_f32_16x16x32_bf16 v[76:79], v[124:127], v[184:187], v[76:79]
	v_mfma_f32_16x16x32_bf16 v[72:75], v[136:139], v[184:187], v[72:75]
	v_mfma_f32_16x16x32_bf16 v[132:135], v[128:131], v[164:167], v[132:135]
	v_mfma_f32_16x16x32_bf16 v[120:123], v[140:143], v[164:167], v[120:123]
	v_mfma_f32_16x16x32_bf16 v[108:111], v[128:131], v[172:175], v[108:111]
	v_mfma_f32_16x16x32_bf16 v[104:107], v[140:143], v[172:175], v[104:107]
	v_mfma_f32_16x16x32_bf16 v[92:95], v[128:131], v[180:183], v[92:95]
	v_mfma_f32_16x16x32_bf16 v[88:91], v[140:143], v[180:183], v[88:91]
	v_mfma_f32_16x16x32_bf16 v[76:79], v[128:131], v[222:225], v[76:79]
	v_mfma_f32_16x16x32_bf16 v[72:75], v[140:143], v[222:225], v[72:75]
	s_setprio 0
	s_setprio 1
	v_mfma_f32_16x16x32_bf16 v[116:119], v[144:147], v[160:163], v[116:119]
	v_mfma_f32_16x16x32_bf16 v[112:115], v[152:155], v[160:163], v[112:115]
	v_mfma_f32_16x16x32_bf16 v[100:103], v[144:147], v[168:171], v[100:103]
	v_mfma_f32_16x16x32_bf16 v[96:99], v[152:155], v[168:171], v[96:99]
	v_mfma_f32_16x16x32_bf16 v[84:87], v[144:147], v[176:179], v[84:87]
	v_mfma_f32_16x16x32_bf16 v[80:83], v[152:155], v[176:179], v[80:83]
	v_mfma_f32_16x16x32_bf16 v[68:71], v[144:147], v[184:187], v[68:71]
	v_mfma_f32_16x16x32_bf16 v[64:67], v[152:155], v[184:187], v[64:67]
	v_mfma_f32_16x16x32_bf16 v[116:119], v[148:151], v[164:167], v[116:119]
	v_mfma_f32_16x16x32_bf16 v[112:115], v[156:159], v[164:167], v[112:115]
	v_mfma_f32_16x16x32_bf16 v[100:103], v[148:151], v[172:175], v[100:103]
	v_mfma_f32_16x16x32_bf16 v[96:99], v[156:159], v[172:175], v[96:99]
	v_mfma_f32_16x16x32_bf16 v[84:87], v[148:151], v[180:183], v[84:87]
	v_mfma_f32_16x16x32_bf16 v[80:83], v[156:159], v[180:183], v[80:83]
	v_mfma_f32_16x16x32_bf16 v[68:71], v[148:151], v[222:225], v[68:71]
	v_mfma_f32_16x16x32_bf16 v[64:67], v[156:159], v[222:225], v[64:67]
	s_barrier
	s_setprio 0
	s_add_i32 s11, s11, s29
	s_mov_b32 m0, s11
	ds_read_b128 v[160:163], v220 offset:16384
	ds_read_b128 v[164:167], v220 offset:17408
	ds_read_b128 v[168:171], v220 offset:18432
	ds_read_b128 v[172:175], v220 offset:19456
	ds_read_b128 v[176:179], v220 offset:20480
	ds_read_b128 v[180:183], v220 offset:21504
	ds_read_b128 v[184:187], v220 offset:22528
	ds_read_b128 v[222:225], v220 offset:23552
	global_load_lds_dwordx4 v190, s[58:59]
	s_add_i32 m0, s11, 0x2000
	s_add_u32 s52, s58, 0x40000
	s_addc_u32 s53, s59, 0
	s_add_i32 s11, s13, s29
	global_load_lds_dwordx4 v212, s[58:59]
	s_mov_b32 m0, s11
	s_nop 0
	global_load_lds_dwordx4 v190, s[52:53]
	s_add_i32 m0, s11, 0x2000
	s_nop 0
	global_load_lds_dwordx4 v212, s[52:53]
	s_mov_b32 m0, s66
	s_nop 0
	global_load_lds_dwordx4 v188, s[60:61]
	s_mov_b32 m0, s67
	s_nop 0
	global_load_lds_dwordx4 v210, s[60:61]
	s_waitcnt vmcnt(8)
	s_waitcnt lgkmcnt(0)
	s_setprio 1
	s_barrier
	v_mfma_f32_16x16x32_bf16 v[60:63], v[124:127], v[160:163], v[60:63]
	v_mfma_f32_16x16x32_bf16 v[56:59], v[136:139], v[160:163], v[56:59]
	v_mfma_f32_16x16x32_bf16 v[44:47], v[124:127], v[168:171], v[44:47]
	v_mfma_f32_16x16x32_bf16 v[40:43], v[136:139], v[168:171], v[40:43]
	v_mfma_f32_16x16x32_bf16 v[28:31], v[124:127], v[176:179], v[28:31]
	v_mfma_f32_16x16x32_bf16 v[24:27], v[136:139], v[176:179], v[24:27]
	v_mfma_f32_16x16x32_bf16 v[12:15], v[124:127], v[184:187], v[12:15]
	v_mfma_f32_16x16x32_bf16 v[8:11], v[136:139], v[184:187], v[8:11]
	v_mfma_f32_16x16x32_bf16 v[60:63], v[128:131], v[164:167], v[60:63]
	v_mfma_f32_16x16x32_bf16 v[56:59], v[140:143], v[164:167], v[56:59]
	v_mfma_f32_16x16x32_bf16 v[44:47], v[128:131], v[172:175], v[44:47]
	v_mfma_f32_16x16x32_bf16 v[40:43], v[140:143], v[172:175], v[40:43]
	v_mfma_f32_16x16x32_bf16 v[28:31], v[128:131], v[180:183], v[28:31]
	v_mfma_f32_16x16x32_bf16 v[24:27], v[140:143], v[180:183], v[24:27]
	v_mfma_f32_16x16x32_bf16 v[12:15], v[128:131], v[222:225], v[12:15]
	v_mfma_f32_16x16x32_bf16 v[8:11], v[140:143], v[222:225], v[8:11]
	s_setprio 0
	s_setprio 1
	v_mfma_f32_16x16x32_bf16 v[52:55], v[144:147], v[160:163], v[52:55]
	v_mfma_f32_16x16x32_bf16 v[48:51], v[152:155], v[160:163], v[48:51]
	v_mfma_f32_16x16x32_bf16 v[36:39], v[144:147], v[168:171], v[36:39]
	v_mfma_f32_16x16x32_bf16 v[32:35], v[152:155], v[168:171], v[32:35]
	v_mfma_f32_16x16x32_bf16 v[20:23], v[144:147], v[176:179], v[20:23]
	v_mfma_f32_16x16x32_bf16 v[16:19], v[152:155], v[176:179], v[16:19]
	v_mfma_f32_16x16x32_bf16 v[4:7], v[144:147], v[184:187], v[4:7]
	v_mfma_f32_16x16x32_bf16 v[0:3], v[152:155], v[184:187], v[0:3]
	v_mfma_f32_16x16x32_bf16 v[52:55], v[148:151], v[164:167], v[52:55]
	v_mfma_f32_16x16x32_bf16 v[48:51], v[156:159], v[164:167], v[48:51]
	v_mfma_f32_16x16x32_bf16 v[36:39], v[148:151], v[172:175], v[36:39]
	v_mfma_f32_16x16x32_bf16 v[32:35], v[156:159], v[172:175], v[32:35]
	v_mfma_f32_16x16x32_bf16 v[20:23], v[148:151], v[180:183], v[20:23]
	v_mfma_f32_16x16x32_bf16 v[16:19], v[156:159], v[180:183], v[16:19]
	v_mfma_f32_16x16x32_bf16 v[4:7], v[148:151], v[222:225], v[4:7]
	v_mfma_f32_16x16x32_bf16 v[0:3], v[156:159], v[222:225], v[0:3]
	s_barrier
; #define PG8_STAGE(bufoff, gbase, voff) do { _Pragma("unroll") for (int _i = 0; _i < 2; ++_i) \
;         __builtin_amdgcn_global_load_lds((const unsigned*)((const char*)(gbase) + (voff)[_i]), (PG8_LAS unsigned*)(lds + (bufoff) + ldsw + _i * 8192), 16, 0, 0); } while (0)
; #define PG8_LDA(dst, b, h) do { _Pragma("unroll") for (int m = 0; m < 4; ++m) _Pragma("unroll") for (int k = 0; k < 2; ++k) dst[m][k] = *(const PG8_LAS bf16x8*)(lds + PG8_SA(b, h) + aoff + m * 2048 + k * 1024); } while (0)
; #define PG8_LDB(dst, b, h) do { _Pragma("unroll") for (int n = 0; n < 2; ++n) _Pragma("unroll") for (int k = 0; k < 2; ++k) dst[n][k] = *(const PG8_LAS bf16x8*)(lds + PG8_SB(b, h) + boff + n * 2048 + k * 1024); } while (0)
; #define PG8_MMA(ai, bj, At, Bt) do { __builtin_amdgcn_s_setprio(1); _Pragma("unroll") for (int m = 0; m < 4; ++m) _Pragma("unroll") for (int n = 0; n < 2; ++n) _Pragma("unroll") for (int k = 0; k < 2; ++k) \
;         acc[ai][bj][m][n] = __builtin_amdgcn_mfma_f32_16x16x32_bf16(Bt[n][k], At[m][k], acc[ai][bj][m][n], 0, 0, 0); __builtin_amdgcn_s_setprio(0); } while (0)
; #define PG8_WAIT_V(n) asm volatile("s_waitcnt vmcnt(" #n ")" ::: "memory")
; #define PG8_WAIT_L(n) asm volatile("s_waitcnt lgkmcnt(" #n ")" ::: "memory")
; #define PG8_BAR __builtin_amdgcn_s_barrier()
; #define PG8_SCHED __builtin_amdgcn_sched_barrier(0)
; template <class Epi>
; __device__ __forceinline__ void gemm_phase(PG8_LAS unsigned char* lds, PG8_LAS unsigned char* xl, const Gemm g, const Sched& S, const Epi& E, const int wid) {
;     ...
;             PG8_LDB(B0, 1, 0); PG8_LDB(B1, 1, 1); PG8_SCHED; PG8_LDA(At, 1, 0); PG8_STAGE(PG8_SA(0, 1), a2 + hstepA, voffA);
;             PG8_WAIT_V(8); PG8_WAIT_L(0); PG8_BAR; if (do0) { PG8_MMA(0, 0, At, B0); PG8_MMA(0, 1, At, B1); } PG8_BAR; PG8_SCHED;
;             PG8_LDA(At, 1, 1); PG8_STAGE(PG8_SB(1, 0), b3, voffB); PG8_STAGE(PG8_SB(1, 1), b3 + hstepB, voffB); PG8_STAGE(PG8_SA(1, 0), a3, voffA);
;             PG8_WAIT_V(8); PG8_WAIT_L(0); PG8_BAR; if (do1) { PG8_MMA(1, 0, At, B0); PG8_MMA(1, 1, At, B1); } PG8_BAR; PG8_SCHED;
;         }
	s_setprio 0
	s_add_i32 s11, 0, 0x18000
	s_add_i32 s13, 0, 0x1c000
	v_add_u32_e32 v140, s11, v195
	v_add_u32_e32 v156, s13, v195
	ds_read_b128 v[124:127], v140
	ds_read_b128 v[128:131], v140 offset:1024
	ds_read_b128 v[136:139], v140 offset:2048
	ds_read_b128 v[140:143], v140 offset:3072
	ds_read_b128 v[144:147], v156
	ds_read_b128 v[148:151], v156 offset:1024
	ds_read_b128 v[152:155], v156 offset:2048
	ds_read_b128 v[156:159], v156 offset:3072
	s_add_u32 s52, s60, 0x40000
	s_addc_u32 s53, s61, 0
	s_mov_b32 m0, s68
	ds_read_b128 v[160:163], v220 offset:32768
	ds_read_b128 v[164:167], v220 offset:33792
	ds_read_b128 v[168:171], v220 offset:34816
	ds_read_b128 v[172:175], v220 offset:35840
	ds_read_b128 v[176:179], v220 offset:36864
	ds_read_b128 v[180:183], v220 offset:37888
	ds_read_b128 v[184:187], v220 offset:38912
	ds_read_b128 v[222:225], v220 offset:39936
	global_load_lds_dwordx4 v188, s[52:53]
	s_mov_b32 m0, s69
	s_nop 0
	global_load_lds_dwordx4 v210, s[52:53]
	s_waitcnt vmcnt(8)
	s_waitcnt lgkmcnt(0)
	s_setprio 1
	s_barrier
	v_mfma_f32_16x16x32_bf16 v[132:135], v[124:127], v[160:163], v[132:135]
	v_mfma_f32_16x16x32_bf16 v[120:123], v[136:139], v[160:163], v[120:123]
	v_mfma_f32_16x16x32_bf16 v[108:111], v[124:127], v[168:171], v[108:111]
	v_mfma_f32_16x16x32_bf16 v[104:107], v[136:139], v[168:171], v[104:107]
	v_mfma_f32_16x16x32_bf16 v[92:95], v[124:127], v[176:179], v[92:95]
	v_mfma_f32_16x16x32_bf16 v[88:91], v[136:139], v[176:179], v[88:91]
	v_mfma_f32_16x16x32_bf16 v[76:79], v[124:127], v[184:187], v[76:79]
	v_mfma_f32_16x16x32_bf16 v[72:75], v[136:139], v[184:187], v[72:75]
	v_mfma_f32_16x16x32_bf16 v[132:135], v[128:131], v[164:167], v[132:135]
	v_mfma_f32_16x16x32_bf16 v[120:123], v[140:143], v[164:167], v[120:123]
	v_mfma_f32_16x16x32_bf16 v[108:111], v[128:131], v[172:175], v[108:111]
	v_mfma_f32_16x16x32_bf16 v[104:107], v[140:143], v[172:175], v[104:107]
	v_mfma_f32_16x16x32_bf16 v[92:95], v[128:131], v[180:183], v[92:95]
	v_mfma_f32_16x16x32_bf16 v[88:91], v[140:143], v[180:183], v[88:91]
	v_mfma_f32_16x16x32_bf16 v[76:79], v[128:131], v[222:225], v[76:79]
	v_mfma_f32_16x16x32_bf16 v[72:75], v[140:143], v[222:225], v[72:75]
	s_setprio 0
	s_setprio 1
	v_mfma_f32_16x16x32_bf16 v[116:119], v[144:147], v[160:163], v[116:119]
	v_mfma_f32_16x16x32_bf16 v[112:115], v[152:155], v[160:163], v[112:115]
	v_mfma_f32_16x16x32_bf16 v[100:103], v[144:147], v[168:171], v[100:103]
	v_mfma_f32_16x16x32_bf16 v[96:99], v[152:155], v[168:171], v[96:99]
	v_mfma_f32_16x16x32_bf16 v[84:87], v[144:147], v[176:179], v[84:87]
	v_mfma_f32_16x16x32_bf16 v[80:83], v[152:155], v[176:179], v[80:83]
	v_mfma_f32_16x16x32_bf16 v[68:71], v[144:147], v[184:187], v[68:71]
	v_mfma_f32_16x16x32_bf16 v[64:67], v[152:155], v[184:187], v[64:67]
	v_mfma_f32_16x16x32_bf16 v[116:119], v[148:151], v[164:167], v[116:119]
	v_mfma_f32_16x16x32_bf16 v[112:115], v[156:159], v[164:167], v[112:115]
	v_mfma_f32_16x16x32_bf16 v[100:103], v[148:151], v[172:175], v[100:103]
	v_mfma_f32_16x16x32_bf16 v[96:99], v[156:159], v[172:175], v[96:99]
	v_mfma_f32_16x16x32_bf16 v[84:87], v[148:151], v[180:183], v[84:87]
	v_mfma_f32_16x16x32_bf16 v[80:83], v[156:159], v[180:183], v[80:83]
	v_mfma_f32_16x16x32_bf16 v[68:71], v[148:151], v[222:225], v[68:71]
	v_mfma_f32_16x16x32_bf16 v[64:67], v[156:159], v[222:225], v[64:67]
	s_barrier
	s_setprio 0
	s_add_i32 s11, s11, s29
	s_mov_b32 m0, s11
	ds_read_b128 v[160:163], v220 offset:49152
	ds_read_b128 v[164:167], v220 offset:50176
	ds_read_b128 v[168:171], v220 offset:51200
	ds_read_b128 v[172:175], v220 offset:52224
	ds_read_b128 v[176:179], v220 offset:53248
	ds_read_b128 v[180:183], v220 offset:54272
	ds_read_b128 v[184:187], v220 offset:55296
	ds_read_b128 v[222:225], v220 offset:56320
	global_load_lds_dwordx4 v205, s[58:59]
	s_add_i32 m0, s11, 0x2000
	s_add_u32 s52, s58, 0x40080
	global_load_lds_dwordx4 v219, s[58:59]
	s_addc_u32 s53, s59, 0
	s_add_i32 s11, s13, s29
	s_mov_b32 m0, s11
	s_nop 0
	global_load_lds_dwordx4 v190, s[52:53]
	s_add_i32 m0, s11, 0x2000
	s_nop 0
	global_load_lds_dwordx4 v212, s[52:53]
	s_mov_b32 m0, s87
	s_nop 0
	global_load_lds_dwordx4 v204, s[60:61]
	s_mov_b32 m0, s88
	s_nop 0
	global_load_lds_dwordx4 v218, s[60:61]
	s_waitcnt vmcnt(8)
	s_waitcnt lgkmcnt(0)
	s_setprio 1
	s_barrier
	v_mfma_f32_16x16x32_bf16 v[60:63], v[124:127], v[160:163], v[60:63]
	v_mfma_f32_16x16x32_bf16 v[56:59], v[136:139], v[160:163], v[56:59]
	v_mfma_f32_16x16x32_bf16 v[44:47], v[124:127], v[168:171], v[44:47]
	v_mfma_f32_16x16x32_bf16 v[40:43], v[136:139], v[168:171], v[40:43]
	v_mfma_f32_16x16x32_bf16 v[28:31], v[124:127], v[176:179], v[28:31]
	v_mfma_f32_16x16x32_bf16 v[24:27], v[136:139], v[176:179], v[24:27]
	v_mfma_f32_16x16x32_bf16 v[12:15], v[124:127], v[184:187], v[12:15]
	v_mfma_f32_16x16x32_bf16 v[8:11], v[136:139], v[184:187], v[8:11]
	v_mfma_f32_16x16x32_bf16 v[60:63], v[128:131], v[164:167], v[60:63]
	v_mfma_f32_16x16x32_bf16 v[56:59], v[140:143], v[164:167], v[56:59]
	v_mfma_f32_16x16x32_bf16 v[44:47], v[128:131], v[172:175], v[44:47]
	v_mfma_f32_16x16x32_bf16 v[40:43], v[140:143], v[172:175], v[40:43]
	v_mfma_f32_16x16x32_bf16 v[28:31], v[128:131], v[180:183], v[28:31]
	v_mfma_f32_16x16x32_bf16 v[24:27], v[140:143], v[180:183], v[24:27]
	v_mfma_f32_16x16x32_bf16 v[12:15], v[128:131], v[222:225], v[12:15]
	v_mfma_f32_16x16x32_bf16 v[8:11], v[140:143], v[222:225], v[8:11]
	s_setprio 0
	s_setprio 1
	v_mfma_f32_16x16x32_bf16 v[52:55], v[144:147], v[160:163], v[52:55]
	v_mfma_f32_16x16x32_bf16 v[48:51], v[152:155], v[160:163], v[48:51]
	v_mfma_f32_16x16x32_bf16 v[36:39], v[144:147], v[168:171], v[36:39]
	v_mfma_f32_16x16x32_bf16 v[32:35], v[152:155], v[168:171], v[32:35]
	v_mfma_f32_16x16x32_bf16 v[20:23], v[144:147], v[176:179], v[20:23]
	v_mfma_f32_16x16x32_bf16 v[16:19], v[152:155], v[176:179], v[16:19]
	v_mfma_f32_16x16x32_bf16 v[4:7], v[144:147], v[184:187], v[4:7]
	v_mfma_f32_16x16x32_bf16 v[0:3], v[152:155], v[184:187], v[0:3]
	v_mfma_f32_16x16x32_bf16 v[52:55], v[148:151], v[164:167], v[52:55]
	v_mfma_f32_16x16x32_bf16 v[48:51], v[156:159], v[164:167], v[48:51]
	v_mfma_f32_16x16x32_bf16 v[36:39], v[148:151], v[172:175], v[36:39]
	v_mfma_f32_16x16x32_bf16 v[32:35], v[156:159], v[172:175], v[32:35]
	v_mfma_f32_16x16x32_bf16 v[20:23], v[148:151], v[180:183], v[20:23]
	v_mfma_f32_16x16x32_bf16 v[16:19], v[156:159], v[180:183], v[16:19]
	v_mfma_f32_16x16x32_bf16 v[4:7], v[148:151], v[222:225], v[4:7]
	v_mfma_f32_16x16x32_bf16 v[0:3], v[156:159], v[222:225], v[0:3]
	s_barrier
	s_setprio 0
	s_add_i32 s10, s10, 2
	s_add_u32 s8, s8, 0x100
	s_addc_u32 s9, s9, 0
	s_cmp_gt_u32 s10, 13
	s_mov_b64 s[52:53], s[56:57]
	s_cbranch_scc0 .LBB0_959
	s_and_b64 vcc, exec, s[14:15]
	s_cbranch_vccz .LBB0_962
	s_barrier

; __device__ __forceinline__ const char* a_tile(const Gemm& g, const Unit& u) { return (const char*)(g.A + ((long)u.z1 * g.aS1 + (long)u.z2 * g.aS2 + (long)u.pm * BM * g.lda)); }
; __device__ __forceinline__ const char* b_tile(const Gemm& g, const Unit& u) { return (const char*)(g.Bt + ((long)u.z1 * g.bS1 + (long)u.z2 * g.bS2 + (long)u.pn * BM * g.ldb)); }
; __device__ __forceinline__ int lane_id_opq() { int l; asm volatile("v_mbcnt_lo_u32_b32 %0, -1, 0\n\tv_mbcnt_hi_u32_b32 %0, -1, %0" : "=v"(l)); return l; }
; #define PG8_LDA(dst, b, h) do { _Pragma("unroll") for (int m = 0; m < 4; ++m) _Pragma("unroll") for (int k = 0; k < 2; ++k) dst[m][k] = *(const PG8_LAS bf16x8*)(lds + PG8_SA(b, h) + aoff + m * 2048 + k * 1024); } while (0)
; template <class Epi>
; __device__ __forceinline__ void gemm_phase(PG8_LAS unsigned char* lds, PG8_LAS unsigned char* xl, const Gemm g, const Sched& S, const Epi& E, const int wid) {
;     ...
;         const bool has_next = S.next(ui + 1, nxt);
;         const char* nA = has_next ? a_tile(g, nxt) : cA; const char* nB = has_next ? b_tile(g, nxt) : cB;
;         for (int t = 0; t < nt; t += 2) {
;             const bool last = (t == nt - 2);
;             const bool do0 = !blkdiag_v<Epi> || t == 0, do1 = !blkdiag_v<Epi> || t != 0;
;             long j1 = 0, ja2 = 0, jb2 = 0;
;             if constexpr (Epi::MID) {
;                 if (t == g.tj) { const int lnM = lane_id_opq(); E.mid(acc, cur, wr, wc, lnM & 15, lnM >> 4); }
;                 if (t >= g.tj) j1 = g.jA;
;                 if (t + 2 >= g.tj) { ja2 = g.jA; jb2 = g.jB; } }
;             const char* a1 = cA + (size_t)(t + 1) * kstep + j1;
;             const char* a2 = last ? nA : cA + (size_t)(t + 2) * kstep + ja2; const char* b2 = last ? nB : cB + (size_t)(t + 2) * kstep + jb2;
;             const char* a3 = a2 + kstep; const char* b3 = b2 + kstep;
;             PG8_LDB(B0, 0, 0); PG8_LDB(B1, 0, 1); PG8_SCHED; PG8_LDA(At, 0, 0); PG8_STAGE(PG8_SA(1, 1), a1 + hstepA, voffA);
;             PG8_WAIT_V(8); PG8_WAIT_L(0); PG8_BAR; if (do0) { PG8_MMA(0, 0, At, B0); PG8_MMA(0, 1, At, B1); } PG8_BAR; PG8_SCHED;
;             PG8_LDA(At, 0, 1); PG8_STAGE(PG8_SB(0, 0), b2, voffB); PG8_STAGE(PG8_SB(0, 1), b2 + hstepB, voffB); PG8_STAGE(PG8_SA(0, 0), a2, voffA);
;             PG8_WAIT_V(8); PG8_WAIT_L(0); PG8_BAR; if (do1) { PG8_MMA(1, 0, At, B0); PG8_MMA(1, 1, At, B1); } PG8_BAR; PG8_SCHED;
.Ldefbar_skip_9:
	v_add_u32_e32 v204, s22, v210
	v_add_u32_e32 v205, s22, v212
	v_add_u32_e32 v226, s22, v214
	v_add_u32_e32 v227, s22, v216
.LBB0_1106:
	s_add_u32 s76, s44, 0x100
	s_addc_u32 s77, s45, 0
	s_add_i32 s55, 0, 0x10000
	s_cmp_eq_u32 s54, 28
	s_cselect_b32 s11, s8, s77
	s_cselect_b32 s10, s9, s76
	v_add_u32_e32 v1, s55, v195
	s_cselect_b32 vcc_hi, s49, s73
	s_cselect_b32 vcc_lo, s61, s72
	s_add_i32 s4, 0, 0x14000
	ds_read_b128 v[4:7], v1
	ds_read_b128 v[8:11], v1 offset:1024
	ds_read_b128 v[84:87], v1 offset:2048
	ds_read_b128 v[88:91], v1 offset:3072
	v_add_u32_e32 v1, s4, v195
	ds_read_b128 v[92:95], v1
	ds_read_b128 v[96:99], v1 offset:1024
	ds_read_b128 v[100:103], v1 offset:2048
	ds_read_b128 v[104:107], v1 offset:3072
	s_add_i32 m0, s90, 0xc000
	ds_read_b128 v[108:111], v225
	ds_read_b128 v[172:175], v225 offset:1024
	ds_read_b128 v[176:179], v225 offset:2048
	ds_read_b128 v[180:183], v225 offset:3072
	ds_read_b128 v[184:187], v225 offset:4096
	ds_read_b128 v[188:191], v225 offset:5120
	ds_read_b128 v[230:233], v225 offset:6144
	ds_read_b128 v[234:237], v225 offset:7168
	global_load_lds_dwordx4 v218, s[44:45]
	s_add_i32 m0, s90, 0xe000
	s_nop 0
	global_load_lds_dwordx4 v220, s[44:45]
	s_waitcnt vmcnt(8)
	s_waitcnt lgkmcnt(0)
	s_setprio 1
	s_barrier
	v_mfma_f32_16x16x32_bf16 v[60:63], v[4:7], v[108:111], v[60:63]
	v_mfma_f32_16x16x32_bf16 v[64:67], v[84:87], v[108:111], v[64:67]
	v_mfma_f32_16x16x32_bf16 v[120:123], v[4:7], v[176:179], v[120:123]
	v_mfma_f32_16x16x32_bf16 v[124:127], v[84:87], v[176:179], v[124:127]
	v_mfma_f32_16x16x32_bf16 v[164:167], v[4:7], v[184:187], v[164:167]
	v_mfma_f32_16x16x32_bf16 v[160:163], v[84:87], v[184:187], v[160:163]
	v_mfma_f32_16x16x32_bf16 v[80:83], v[4:7], v[230:233], v[80:83]
	v_mfma_f32_16x16x32_bf16 v[128:131], v[84:87], v[230:233], v[128:131]
	v_mfma_f32_16x16x32_bf16 v[60:63], v[8:11], v[172:175], v[60:63]
	v_mfma_f32_16x16x32_bf16 v[64:67], v[88:91], v[172:175], v[64:67]
	v_mfma_f32_16x16x32_bf16 v[120:123], v[8:11], v[180:183], v[120:123]
	v_mfma_f32_16x16x32_bf16 v[124:127], v[88:91], v[180:183], v[124:127]
	v_mfma_f32_16x16x32_bf16 v[164:167], v[8:11], v[188:191], v[164:167]
	v_mfma_f32_16x16x32_bf16 v[160:163], v[88:91], v[188:191], v[160:163]
	v_mfma_f32_16x16x32_bf16 v[80:83], v[8:11], v[234:237], v[80:83]
	v_mfma_f32_16x16x32_bf16 v[128:131], v[88:91], v[234:237], v[128:131]
	s_setprio 0
	s_setprio 1
	v_mfma_f32_16x16x32_bf16 v[112:115], v[92:95], v[108:111], v[112:115]
	v_mfma_f32_16x16x32_bf16 v[108:111], v[100:103], v[108:111], v[116:119]
	v_mfma_f32_16x16x32_bf16 v[116:119], v[92:95], v[176:179], v[156:159]
	v_mfma_f32_16x16x32_bf16 v[156:159], v[96:99], v[180:183], v[116:119]
	v_mfma_f32_16x16x32_bf16 v[116:119], v[100:103], v[176:179], v[152:155]
	v_mfma_f32_16x16x32_bf16 v[152:155], v[104:107], v[180:183], v[116:119]
	v_mfma_f32_16x16x32_bf16 v[116:119], v[92:95], v[184:187], v[148:151]
	v_mfma_f32_16x16x32_bf16 v[148:151], v[96:99], v[188:191], v[116:119]
	v_mfma_f32_16x16x32_bf16 v[116:119], v[100:103], v[184:187], v[144:147]
	v_mfma_f32_16x16x32_bf16 v[144:147], v[104:107], v[188:191], v[116:119]
	v_mfma_f32_16x16x32_bf16 v[116:119], v[92:95], v[230:233], v[140:143]
	v_mfma_f32_16x16x32_bf16 v[140:143], v[96:99], v[234:237], v[116:119]
	v_mfma_f32_16x16x32_bf16 v[116:119], v[100:103], v[230:233], v[136:139]
	v_mfma_f32_16x16x32_bf16 v[112:115], v[96:99], v[172:175], v[112:115]
	v_mfma_f32_16x16x32_bf16 v[136:139], v[104:107], v[234:237], v[116:119]
	v_mfma_f32_16x16x32_bf16 v[108:111], v[104:107], v[172:175], v[108:111]
	s_barrier
	s_setprio 0
	s_add_i32 s5, s55, s29
	s_mov_b32 m0, s5
	ds_read_b128 v[116:119], v225 offset:16384
	ds_read_b128 v[172:175], v225 offset:17408
	ds_read_b128 v[176:179], v225 offset:18432
	ds_read_b128 v[180:183], v225 offset:19456
	ds_read_b128 v[184:187], v225 offset:20480
	ds_read_b128 v[188:191], v225 offset:21504
	ds_read_b128 v[230:233], v225 offset:22528
	ds_read_b128 v[234:237], v225 offset:23552
	global_load_lds_dwordx4 v212, vcc
	s_add_i32 m0, s5, 0x2000
	s_add_u32 s44, vcc_lo, 0x80000
	s_addc_u32 s45, vcc_hi, 0
	s_add_i32 s4, s4, s29
	global_load_lds_dwordx4 v216, vcc
	s_mov_b32 m0, s4
	s_nop 0
	global_load_lds_dwordx4 v212, s[44:45]
	s_add_i32 m0, s4, 0x2000
	s_nop 0
	global_load_lds_dwordx4 v216, s[44:45]
	s_mov_b32 m0, s90
	s_nop 0
	global_load_lds_dwordx4 v210, s[10:11]
	s_mov_b32 m0, s13
	s_nop 0
	global_load_lds_dwordx4 v214, s[10:11]
	s_waitcnt vmcnt(8)
	s_waitcnt lgkmcnt(0)
	s_setprio 1
	s_barrier
	v_mfma_f32_16x16x32_bf16 v[132:135], v[4:7], v[116:119], v[132:135]
	v_mfma_f32_16x16x32_bf16 v[68:71], v[84:87], v[116:119], v[68:71]
	v_mfma_f32_16x16x32_bf16 v[56:59], v[4:7], v[176:179], v[56:59]
	v_mfma_f32_16x16x32_bf16 v[52:55], v[84:87], v[176:179], v[52:55]
	v_mfma_f32_16x16x32_bf16 v[40:43], v[4:7], v[184:187], v[40:43]
	v_mfma_f32_16x16x32_bf16 v[36:39], v[84:87], v[184:187], v[36:39]
	v_mfma_f32_16x16x32_bf16 v[4:7], v[4:7], v[230:233], v[168:171]
	v_mfma_f32_16x16x32_bf16 v[132:135], v[8:11], v[172:175], v[132:135]
	v_mfma_f32_16x16x32_bf16 v[68:71], v[88:91], v[172:175], v[68:71]
	v_mfma_f32_16x16x32_bf16 v[56:59], v[8:11], v[180:183], v[56:59]
	v_mfma_f32_16x16x32_bf16 v[52:55], v[88:91], v[180:183], v[52:55]
	v_mfma_f32_16x16x32_bf16 v[40:43], v[8:11], v[188:191], v[40:43]
	v_mfma_f32_16x16x32_bf16 v[36:39], v[88:91], v[188:191], v[36:39]
	v_mfma_f32_16x16x32_bf16 v[4:7], v[8:11], v[234:237], v[4:7]
	v_mfma_f32_16x16x32_bf16 v[8:11], v[84:87], v[230:233], v[72:75]
	v_mfma_f32_16x16x32_bf16 v[8:11], v[88:91], v[234:237], v[8:11]
	s_setprio 0
	s_setprio 1
	v_mfma_f32_16x16x32_bf16 v[48:51], v[92:95], v[116:119], v[48:51]
	v_mfma_f32_16x16x32_bf16 v[44:47], v[100:103], v[116:119], v[44:47]
	v_mfma_f32_16x16x32_bf16 v[32:35], v[92:95], v[176:179], v[32:35]
	v_mfma_f32_16x16x32_bf16 v[28:31], v[100:103], v[176:179], v[28:31]
	v_mfma_f32_16x16x32_bf16 v[24:27], v[92:95], v[184:187], v[24:27]
	v_mfma_f32_16x16x32_bf16 v[20:23], v[100:103], v[184:187], v[20:23]
	v_mfma_f32_16x16x32_bf16 v[16:19], v[92:95], v[230:233], v[16:19]
	v_mfma_f32_16x16x32_bf16 v[12:15], v[100:103], v[230:233], v[12:15]
	v_mfma_f32_16x16x32_bf16 v[48:51], v[96:99], v[172:175], v[48:51]
	v_mfma_f32_16x16x32_bf16 v[44:47], v[104:107], v[172:175], v[44:47]
	v_mfma_f32_16x16x32_bf16 v[32:35], v[96:99], v[180:183], v[32:35]
	v_mfma_f32_16x16x32_bf16 v[28:31], v[104:107], v[180:183], v[28:31]
	v_mfma_f32_16x16x32_bf16 v[24:27], v[96:99], v[188:191], v[24:27]
	v_mfma_f32_16x16x32_bf16 v[20:23], v[104:107], v[188:191], v[20:23]
	v_mfma_f32_16x16x32_bf16 v[16:19], v[96:99], v[234:237], v[16:19]
	v_mfma_f32_16x16x32_bf16 v[12:15], v[104:107], v[234:237], v[12:15]
	s_barrier
; #define PG8_STAGE(bufoff, gbase, voff) do { _Pragma("unroll") for (int _i = 0; _i < 2; ++_i) \
;         __builtin_amdgcn_global_load_lds((const unsigned*)((const char*)(gbase) + (voff)[_i]), (PG8_LAS unsigned*)(lds + (bufoff) + ldsw + _i * 8192), 16, 0, 0); } while (0)
; #define PG8_LDA(dst, b, h) do { _Pragma("unroll") for (int m = 0; m < 4; ++m) _Pragma("unroll") for (int k = 0; k < 2; ++k) dst[m][k] = *(const PG8_LAS bf16x8*)(lds + PG8_SA(b, h) + aoff + m * 2048 + k * 1024); } while (0)
; #define PG8_LDB(dst, b, h) do { _Pragma("unroll") for (int n = 0; n < 2; ++n) _Pragma("unroll") for (int k = 0; k < 2; ++k) dst[n][k] = *(const PG8_LAS bf16x8*)(lds + PG8_SB(b, h) + boff + n * 2048 + k * 1024); } while (0)
; #define PG8_MMA(ai, bj, At, Bt) do { __builtin_amdgcn_s_setprio(1); _Pragma("unroll") for (int m = 0; m < 4; ++m) _Pragma("unroll") for (int n = 0; n < 2; ++n) _Pragma("unroll") for (int k = 0; k < 2; ++k) \
;         acc[ai][bj][m][n] = __builtin_amdgcn_mfma_f32_16x16x32_bf16(Bt[n][k], At[m][k], acc[ai][bj][m][n], 0, 0, 0); __builtin_amdgcn_s_setprio(0); } while (0)
; #define PG8_WAIT_V(n) asm volatile("s_waitcnt vmcnt(" #n ")" ::: "memory")
; #define PG8_WAIT_L(n) asm volatile("s_waitcnt lgkmcnt(" #n ")" ::: "memory")
; #define PG8_BAR __builtin_amdgcn_s_barrier()
; #define PG8_SCHED __builtin_amdgcn_sched_barrier(0)
; template <class Epi>
; __device__ __forceinline__ void gemm_phase(PG8_LAS unsigned char* lds, PG8_LAS unsigned char* xl, const Gemm g, const Sched& S, const Epi& E, const int wid) {
;     ...
;             PG8_LDB(B0, 1, 0); PG8_LDB(B1, 1, 1); PG8_SCHED; PG8_LDA(At, 1, 0); PG8_STAGE(PG8_SA(0, 1), a2 + hstepA, voffA);
;             PG8_WAIT_V(8); PG8_WAIT_L(0); PG8_BAR; if (do0) { PG8_MMA(0, 0, At, B0); PG8_MMA(0, 1, At, B1); } PG8_BAR; PG8_SCHED;
;             PG8_LDA(At, 1, 1); PG8_STAGE(PG8_SB(1, 0), b3, voffB); PG8_STAGE(PG8_SB(1, 1), b3 + hstepB, voffB); PG8_STAGE(PG8_SA(1, 0), a3, voffA);
;             PG8_WAIT_V(8); PG8_WAIT_L(0); PG8_BAR; if (do1) { PG8_MMA(1, 0, At, B0); PG8_MMA(1, 1, At, B1); } PG8_BAR; PG8_SCHED;
;         }
	s_setprio 0
	s_add_i32 s4, 0, 0x18000
	v_add_u32_e32 v1, s4, v195
	s_add_i32 s5, 0, 0x1c000
	ds_read_b128 v[72:75], v1
	ds_read_b128 v[84:87], v1 offset:1024
	ds_read_b128 v[88:91], v1 offset:2048
	ds_read_b128 v[92:95], v1 offset:3072
	v_add_u32_e32 v1, s5, v195
	ds_read_b128 v[96:99], v1
	ds_read_b128 v[100:103], v1 offset:1024
	ds_read_b128 v[104:107], v1 offset:2048
	ds_read_b128 v[172:175], v1 offset:3072
	s_add_u32 s100, s10, 0x80000
	s_addc_u32 s101, s11, 0
	s_mov_b32 m0, s91
	ds_read_b128 v[116:119], v225 offset:32768
	ds_read_b128 v[168:171], v225 offset:33792
	ds_read_b128 v[176:179], v225 offset:34816
	ds_read_b128 v[180:183], v225 offset:35840
	ds_read_b128 v[184:187], v225 offset:36864
	ds_read_b128 v[188:191], v225 offset:37888
	ds_read_b128 v[230:233], v225 offset:38912
	ds_read_b128 v[234:237], v225 offset:39936
	global_load_lds_dwordx4 v210, s[100:101]
	s_mov_b32 m0, s92
	s_nop 0
	global_load_lds_dwordx4 v214, s[100:101]
	s_waitcnt vmcnt(8)
	s_waitcnt lgkmcnt(0)
	s_setprio 1
	s_barrier
	v_mfma_f32_16x16x32_bf16 v[60:63], v[72:75], v[116:119], v[60:63]
	v_mfma_f32_16x16x32_bf16 v[64:67], v[88:91], v[116:119], v[64:67]
	v_mfma_f32_16x16x32_bf16 v[120:123], v[72:75], v[176:179], v[120:123]
	v_mfma_f32_16x16x32_bf16 v[124:127], v[88:91], v[176:179], v[124:127]
	v_mfma_f32_16x16x32_bf16 v[164:167], v[72:75], v[184:187], v[164:167]
	v_mfma_f32_16x16x32_bf16 v[160:163], v[88:91], v[184:187], v[160:163]
	v_mfma_f32_16x16x32_bf16 v[80:83], v[72:75], v[230:233], v[80:83]
	v_mfma_f32_16x16x32_bf16 v[128:131], v[88:91], v[230:233], v[128:131]
	v_mfma_f32_16x16x32_bf16 v[60:63], v[84:87], v[168:171], v[60:63]
	v_mfma_f32_16x16x32_bf16 v[64:67], v[92:95], v[168:171], v[64:67]
	v_mfma_f32_16x16x32_bf16 v[120:123], v[84:87], v[180:183], v[120:123]
	v_mfma_f32_16x16x32_bf16 v[124:127], v[92:95], v[180:183], v[124:127]
	v_mfma_f32_16x16x32_bf16 v[164:167], v[84:87], v[188:191], v[164:167]
	v_mfma_f32_16x16x32_bf16 v[160:163], v[92:95], v[188:191], v[160:163]
	v_mfma_f32_16x16x32_bf16 v[80:83], v[84:87], v[234:237], v[80:83]
	v_mfma_f32_16x16x32_bf16 v[128:131], v[92:95], v[234:237], v[128:131]
	s_setprio 0
	s_setprio 1
	v_mfma_f32_16x16x32_bf16 v[108:111], v[104:107], v[116:119], v[108:111]
	v_mfma_f32_16x16x32_bf16 v[112:115], v[96:99], v[116:119], v[112:115]
	v_mfma_f32_16x16x32_bf16 v[116:119], v[172:175], v[168:171], v[108:111]
	v_mfma_f32_16x16x32_bf16 v[108:111], v[96:99], v[176:179], v[156:159]
	v_mfma_f32_16x16x32_bf16 v[156:159], v[100:103], v[180:183], v[108:111]
	v_mfma_f32_16x16x32_bf16 v[108:111], v[104:107], v[176:179], v[152:155]
	v_mfma_f32_16x16x32_bf16 v[152:155], v[172:175], v[180:183], v[108:111]
	v_mfma_f32_16x16x32_bf16 v[108:111], v[96:99], v[184:187], v[148:151]
	v_mfma_f32_16x16x32_bf16 v[148:151], v[100:103], v[188:191], v[108:111]
	v_mfma_f32_16x16x32_bf16 v[108:111], v[104:107], v[184:187], v[144:147]
	v_mfma_f32_16x16x32_bf16 v[144:147], v[172:175], v[188:191], v[108:111]
	v_mfma_f32_16x16x32_bf16 v[108:111], v[96:99], v[230:233], v[140:143]
	v_mfma_f32_16x16x32_bf16 v[140:143], v[100:103], v[234:237], v[108:111]
	v_mfma_f32_16x16x32_bf16 v[108:111], v[104:107], v[230:233], v[136:139]
	v_mfma_f32_16x16x32_bf16 v[112:115], v[100:103], v[168:171], v[112:115]
	v_mfma_f32_16x16x32_bf16 v[136:139], v[172:175], v[234:237], v[108:111]
	s_barrier
	s_setprio 0
	s_add_i32 s4, s4, s29
	s_mov_b32 m0, s4
	s_nop 0
	ds_read_b128 v[108:111], v225 offset:49152
	ds_read_b128 v[176:179], v225 offset:50176
	ds_read_b128 v[180:183], v225 offset:51200
	ds_read_b128 v[184:187], v225 offset:52224
	ds_read_b128 v[188:191], v225 offset:53248
	ds_read_b128 v[230:233], v225 offset:54272
	ds_read_b128 v[234:237], v225 offset:55296
	ds_read_b128 v[238:241], v225 offset:56320
	global_load_lds_dwordx4 v205, vcc
	s_add_i32 m0, s4, 0x2000
	s_add_u32 s100, vcc_lo, 0x80080
	global_load_lds_dwordx4 v227, vcc
	s_addc_u32 s101, vcc_hi, 0
	s_add_i32 s4, s5, s29
	s_mov_b32 m0, s4
	s_nop 0
	global_load_lds_dwordx4 v212, s[100:101]
	s_add_i32 m0, s4, 0x2000
	s_nop 0
	global_load_lds_dwordx4 v216, s[100:101]
	s_mov_b32 m0, s40
	s_nop 0
	global_load_lds_dwordx4 v204, s[10:11]
	s_mov_b32 m0, s41
	s_nop 0
	global_load_lds_dwordx4 v226, s[10:11]
	s_waitcnt vmcnt(8)
	s_waitcnt lgkmcnt(0)
	s_setprio 1
	s_barrier
	v_mfma_f32_16x16x32_bf16 v[4:7], v[72:75], v[234:237], v[4:7]
	v_mfma_f32_16x16x32_bf16 v[132:135], v[72:75], v[108:111], v[132:135]
	v_mfma_f32_16x16x32_bf16 v[68:71], v[88:91], v[108:111], v[68:71]
	v_mfma_f32_16x16x32_bf16 v[56:59], v[72:75], v[180:183], v[56:59]
	v_mfma_f32_16x16x32_bf16 v[52:55], v[88:91], v[180:183], v[52:55]
	v_mfma_f32_16x16x32_bf16 v[40:43], v[72:75], v[188:191], v[40:43]
	v_mfma_f32_16x16x32_bf16 v[36:39], v[88:91], v[188:191], v[36:39]
	v_mfma_f32_16x16x32_bf16 v[168:171], v[84:87], v[238:241], v[4:7]
	v_mfma_f32_16x16x32_bf16 v[4:7], v[88:91], v[234:237], v[8:11]
	v_mfma_f32_16x16x32_bf16 v[132:135], v[84:87], v[176:179], v[132:135]
	v_mfma_f32_16x16x32_bf16 v[68:71], v[92:95], v[176:179], v[68:71]
	v_mfma_f32_16x16x32_bf16 v[56:59], v[84:87], v[184:187], v[56:59]
	v_mfma_f32_16x16x32_bf16 v[52:55], v[92:95], v[184:187], v[52:55]
	v_mfma_f32_16x16x32_bf16 v[40:43], v[84:87], v[230:233], v[40:43]
	v_mfma_f32_16x16x32_bf16 v[36:39], v[92:95], v[230:233], v[36:39]
	v_mfma_f32_16x16x32_bf16 v[72:75], v[92:95], v[238:241], v[4:7]
	s_setprio 0
	s_setprio 1
	v_mfma_f32_16x16x32_bf16 v[4:7], v[96:99], v[108:111], v[48:51]
	v_mfma_f32_16x16x32_bf16 v[48:51], v[100:103], v[176:179], v[4:7]
	v_mfma_f32_16x16x32_bf16 v[4:7], v[104:107], v[108:111], v[44:47]
	v_mfma_f32_16x16x32_bf16 v[44:47], v[172:175], v[176:179], v[4:7]
	v_mfma_f32_16x16x32_bf16 v[4:7], v[96:99], v[180:183], v[32:35]
	v_mfma_f32_16x16x32_bf16 v[32:35], v[100:103], v[184:187], v[4:7]
	v_mfma_f32_16x16x32_bf16 v[4:7], v[104:107], v[180:183], v[28:31]
	v_mfma_f32_16x16x32_bf16 v[28:31], v[172:175], v[184:187], v[4:7]
	v_mfma_f32_16x16x32_bf16 v[4:7], v[96:99], v[188:191], v[24:27]
	v_mfma_f32_16x16x32_bf16 v[24:27], v[100:103], v[230:233], v[4:7]
	v_mfma_f32_16x16x32_bf16 v[4:7], v[104:107], v[188:191], v[20:23]
	v_mfma_f32_16x16x32_bf16 v[20:23], v[172:175], v[230:233], v[4:7]
	v_mfma_f32_16x16x32_bf16 v[4:7], v[96:99], v[234:237], v[16:19]
	v_mfma_f32_16x16x32_bf16 v[16:19], v[100:103], v[238:241], v[4:7]
	v_mfma_f32_16x16x32_bf16 v[4:7], v[104:107], v[234:237], v[12:15]
	v_mfma_f32_16x16x32_bf16 v[12:15], v[172:175], v[238:241], v[4:7]
	s_barrier
	s_setprio 0
	s_add_i32 s54, s54, 2
	s_add_u32 s72, s72, 0x100
	s_addc_u32 s73, s73, 0
	s_cmp_gt_u32 s54, 29
	s_mov_b64 s[44:45], s[76:77]
	s_cbranch_scc0 .LBB0_1106
	s_mov_b32 s100, 0
	s_and_b64 vcc, exec, s[14:15]
	s_cbranch_vccz .LBB0_1109
	s_barrier

; #define PG8_STAGE(bufoff, gbase, voff) do { _Pragma("unroll") for (int _i = 0; _i < 2; ++_i) \
;         __builtin_amdgcn_global_load_lds((const unsigned*)((const char*)(gbase) + (voff)[_i]), (PG8_LAS unsigned*)(lds + (bufoff) + ldsw + _i * 8192), 16, 0, 0); } while (0)
; #define PG8_LDA(dst, b, h) do { _Pragma("unroll") for (int m = 0; m < 4; ++m) _Pragma("unroll") for (int k = 0; k < 2; ++k) dst[m][k] = *(const PG8_LAS bf16x8*)(lds + PG8_SA(b, h) + aoff + m * 2048 + k * 1024); } while (0)
; #define PG8_LDB(dst, b, h) do { _Pragma("unroll") for (int n = 0; n < 2; ++n) _Pragma("unroll") for (int k = 0; k < 2; ++k) dst[n][k] = *(const PG8_LAS bf16x8*)(lds + PG8_SB(b, h) + boff + n * 2048 + k * 1024); } while (0)
; #define PG8_MMA(ai, bj, At, Bt) do { __builtin_amdgcn_s_setprio(1); _Pragma("unroll") for (int m = 0; m < 4; ++m) _Pragma("unroll") for (int n = 0; n < 2; ++n) _Pragma("unroll") for (int k = 0; k < 2; ++k) \
;         acc[ai][bj][m][n] = __builtin_amdgcn_mfma_f32_16x16x32_bf16(Bt[n][k], At[m][k], acc[ai][bj][m][n], 0, 0, 0); __builtin_amdgcn_s_setprio(0); } while (0)
; #define PG8_WAIT_V(n) asm volatile("s_waitcnt vmcnt(" #n ")" ::: "memory")
; #define PG8_WAIT_L(n) asm volatile("s_waitcnt lgkmcnt(" #n ")" ::: "memory")
; #define PG8_BAR __builtin_amdgcn_s_barrier()
; #define PG8_SCHED __builtin_amdgcn_sched_barrier(0)
; template <class Epi>
; __device__ __forceinline__ void gemm_phase(PG8_LAS unsigned char* lds, PG8_LAS unsigned char* xl, const Gemm g, const Sched& S, const Epi& E, const int wid) {
;     ...
;             const char* a1 = cA + (size_t)(t + 1) * kstep + j1;
;             const char* a2 = last ? nA : cA + (size_t)(t + 2) * kstep + ja2; const char* b2 = last ? nB : cB + (size_t)(t + 2) * kstep + jb2;
;             const char* a3 = a2 + kstep; const char* b3 = b2 + kstep;
;             PG8_LDB(B0, 0, 0); PG8_LDB(B1, 0, 1); PG8_SCHED; PG8_LDA(At, 0, 0); PG8_STAGE(PG8_SA(1, 1), a1 + hstepA, voffA);
;             PG8_WAIT_V(8); PG8_WAIT_L(0); PG8_BAR; if (do0) { PG8_MMA(0, 0, At, B0); PG8_MMA(0, 1, At, B1); } PG8_BAR; PG8_SCHED;
;             PG8_LDA(At, 0, 1); PG8_STAGE(PG8_SB(0, 0), b2, voffB); PG8_STAGE(PG8_SB(0, 1), b2 + hstepB, voffB); PG8_STAGE(PG8_SA(0, 0), a2, voffA);
;             PG8_WAIT_V(8); PG8_WAIT_L(0); PG8_BAR; if (do1) { PG8_MMA(1, 0, At, B0); PG8_MMA(1, 1, At, B1); } PG8_BAR; PG8_SCHED;
.LBB0_1304:
	s_add_u32 s4, s36, 0xffea0080
	s_addc_u32 s5, s37, -1
	s_add_i32 s13, 0, 0x10000
	s_cmpk_eq_i32 s9, 0x54
	s_cselect_b32 s11, s21, s5
	s_cselect_b32 s10, s20, s4
	s_cselect_b32 s41, s31, s8
	s_cselect_b32 s40, s30, s1
	s_add_i32 s4, 0, 0x14000
	v_add_u32_e32 v136, s13, v195
	v_add_u32_e32 v156, s4, v195
	ds_read_b128 v[120:123], v136
	ds_read_b128 v[124:127], v136 offset:1024
	ds_read_b128 v[128:131], v136 offset:2048
	ds_read_b128 v[136:139], v136 offset:3072
	ds_read_b128 v[144:147], v156
	ds_read_b128 v[148:151], v156 offset:1024
	ds_read_b128 v[152:155], v156 offset:2048
	ds_read_b128 v[156:159], v156 offset:3072
	s_add_i32 m0, s51, 0xc000
	ds_read_b128 v[160:163], v220
	ds_read_b128 v[164:167], v220 offset:1024
	ds_read_b128 v[168:171], v220 offset:2048
	ds_read_b128 v[172:175], v220 offset:3072
	ds_read_b128 v[176:179], v220 offset:4096
	ds_read_b128 v[180:183], v220 offset:5120
	ds_read_b128 v[184:187], v220 offset:6144
	ds_read_b128 v[222:225], v220 offset:7168
	global_load_lds_dwordx4 v214, s[36:37]
	s_add_i32 m0, s51, 0xe000
	s_nop 0
	global_load_lds_dwordx4 v216, s[36:37]
	s_waitcnt vmcnt(8)
	s_waitcnt lgkmcnt(0)
	s_setprio 1
	s_barrier
	v_mfma_f32_16x16x32_bf16 v[140:143], v[120:123], v[160:163], v[140:143]
	v_mfma_f32_16x16x32_bf16 v[132:135], v[128:131], v[160:163], v[132:135]
	v_mfma_f32_16x16x32_bf16 v[108:111], v[120:123], v[168:171], v[108:111]
	v_mfma_f32_16x16x32_bf16 v[104:107], v[128:131], v[168:171], v[104:107]
	v_mfma_f32_16x16x32_bf16 v[92:95], v[120:123], v[176:179], v[92:95]
	v_mfma_f32_16x16x32_bf16 v[88:91], v[128:131], v[176:179], v[88:91]
	v_mfma_f32_16x16x32_bf16 v[76:79], v[120:123], v[184:187], v[76:79]
	v_mfma_f32_16x16x32_bf16 v[72:75], v[128:131], v[184:187], v[72:75]
	v_mfma_f32_16x16x32_bf16 v[140:143], v[124:127], v[164:167], v[140:143]
	v_mfma_f32_16x16x32_bf16 v[132:135], v[136:139], v[164:167], v[132:135]
	v_mfma_f32_16x16x32_bf16 v[108:111], v[124:127], v[172:175], v[108:111]
	v_mfma_f32_16x16x32_bf16 v[104:107], v[136:139], v[172:175], v[104:107]
	v_mfma_f32_16x16x32_bf16 v[92:95], v[124:127], v[180:183], v[92:95]
	v_mfma_f32_16x16x32_bf16 v[88:91], v[136:139], v[180:183], v[88:91]
	v_mfma_f32_16x16x32_bf16 v[76:79], v[124:127], v[222:225], v[76:79]
	v_mfma_f32_16x16x32_bf16 v[72:75], v[136:139], v[222:225], v[72:75]
	s_setprio 0
	s_setprio 1
	v_mfma_f32_16x16x32_bf16 v[116:119], v[144:147], v[160:163], v[116:119]
	v_mfma_f32_16x16x32_bf16 v[112:115], v[152:155], v[160:163], v[112:115]
	v_mfma_f32_16x16x32_bf16 v[100:103], v[144:147], v[168:171], v[100:103]
	v_mfma_f32_16x16x32_bf16 v[96:99], v[152:155], v[168:171], v[96:99]
	v_mfma_f32_16x16x32_bf16 v[84:87], v[144:147], v[176:179], v[84:87]
	v_mfma_f32_16x16x32_bf16 v[80:83], v[152:155], v[176:179], v[80:83]
	v_mfma_f32_16x16x32_bf16 v[68:71], v[144:147], v[184:187], v[68:71]
	v_mfma_f32_16x16x32_bf16 v[64:67], v[152:155], v[184:187], v[64:67]
	v_mfma_f32_16x16x32_bf16 v[116:119], v[148:151], v[164:167], v[116:119]
	v_mfma_f32_16x16x32_bf16 v[112:115], v[156:159], v[164:167], v[112:115]
	v_mfma_f32_16x16x32_bf16 v[100:103], v[148:151], v[172:175], v[100:103]
	v_mfma_f32_16x16x32_bf16 v[96:99], v[156:159], v[172:175], v[96:99]
	v_mfma_f32_16x16x32_bf16 v[84:87], v[148:151], v[180:183], v[84:87]
	v_mfma_f32_16x16x32_bf16 v[80:83], v[156:159], v[180:183], v[80:83]
	v_mfma_f32_16x16x32_bf16 v[68:71], v[148:151], v[222:225], v[68:71]
	v_mfma_f32_16x16x32_bf16 v[64:67], v[156:159], v[222:225], v[64:67]
	s_barrier
	s_setprio 0
	s_add_i32 s5, s13, s29
	s_mov_b32 m0, s5
	ds_read_b128 v[160:163], v220 offset:16384
	ds_read_b128 v[164:167], v220 offset:17408
	ds_read_b128 v[168:171], v220 offset:18432
	ds_read_b128 v[172:175], v220 offset:19456
	ds_read_b128 v[176:179], v220 offset:20480
	ds_read_b128 v[180:183], v220 offset:21504
	ds_read_b128 v[184:187], v220 offset:22528
	ds_read_b128 v[222:225], v220 offset:23552
	global_load_lds_dwordx4 v190, s[40:41]
	s_add_i32 m0, s5, 0x2000
	s_add_u32 s44, s40, 0x160000
	s_addc_u32 s45, s41, 0
	s_add_i32 s4, s4, s29
	global_load_lds_dwordx4 v212, s[40:41]
	s_mov_b32 m0, s4
	s_nop 0
	global_load_lds_dwordx4 v190, s[44:45]
	s_add_i32 m0, s4, 0x2000
	s_nop 0
	global_load_lds_dwordx4 v212, s[44:45]
	s_mov_b32 m0, s51
	s_nop 0
	global_load_lds_dwordx4 v188, s[10:11]
	s_mov_b32 m0, s52
	s_nop 0
	global_load_lds_dwordx4 v210, s[10:11]
	s_waitcnt vmcnt(8)
	s_waitcnt lgkmcnt(0)
	s_setprio 1
	s_barrier
	v_mfma_f32_16x16x32_bf16 v[60:63], v[120:123], v[160:163], v[60:63]
	v_mfma_f32_16x16x32_bf16 v[56:59], v[128:131], v[160:163], v[56:59]
	v_mfma_f32_16x16x32_bf16 v[44:47], v[120:123], v[168:171], v[44:47]
	v_mfma_f32_16x16x32_bf16 v[40:43], v[128:131], v[168:171], v[40:43]
	v_mfma_f32_16x16x32_bf16 v[28:31], v[120:123], v[176:179], v[28:31]
	v_mfma_f32_16x16x32_bf16 v[24:27], v[128:131], v[176:179], v[24:27]
	v_mfma_f32_16x16x32_bf16 v[12:15], v[120:123], v[184:187], v[12:15]
	v_mfma_f32_16x16x32_bf16 v[8:11], v[128:131], v[184:187], v[8:11]
	v_mfma_f32_16x16x32_bf16 v[60:63], v[124:127], v[164:167], v[60:63]
	v_mfma_f32_16x16x32_bf16 v[56:59], v[136:139], v[164:167], v[56:59]
	v_mfma_f32_16x16x32_bf16 v[44:47], v[124:127], v[172:175], v[44:47]
	v_mfma_f32_16x16x32_bf16 v[40:43], v[136:139], v[172:175], v[40:43]
	v_mfma_f32_16x16x32_bf16 v[28:31], v[124:127], v[180:183], v[28:31]
	v_mfma_f32_16x16x32_bf16 v[24:27], v[136:139], v[180:183], v[24:27]
	v_mfma_f32_16x16x32_bf16 v[12:15], v[124:127], v[222:225], v[12:15]
	v_mfma_f32_16x16x32_bf16 v[8:11], v[136:139], v[222:225], v[8:11]
	s_setprio 0
	s_setprio 1
	v_mfma_f32_16x16x32_bf16 v[52:55], v[144:147], v[160:163], v[52:55]
	v_mfma_f32_16x16x32_bf16 v[48:51], v[152:155], v[160:163], v[48:51]
	v_mfma_f32_16x16x32_bf16 v[36:39], v[144:147], v[168:171], v[36:39]
	v_mfma_f32_16x16x32_bf16 v[32:35], v[152:155], v[168:171], v[32:35]
	v_mfma_f32_16x16x32_bf16 v[20:23], v[144:147], v[176:179], v[20:23]
	v_mfma_f32_16x16x32_bf16 v[16:19], v[152:155], v[176:179], v[16:19]
	v_mfma_f32_16x16x32_bf16 v[4:7], v[144:147], v[184:187], v[4:7]
	v_mfma_f32_16x16x32_bf16 v[0:3], v[152:155], v[184:187], v[0:3]
	v_mfma_f32_16x16x32_bf16 v[52:55], v[148:151], v[164:167], v[52:55]
	v_mfma_f32_16x16x32_bf16 v[48:51], v[156:159], v[164:167], v[48:51]
	v_mfma_f32_16x16x32_bf16 v[36:39], v[148:151], v[172:175], v[36:39]
	v_mfma_f32_16x16x32_bf16 v[32:35], v[156:159], v[172:175], v[32:35]
	v_mfma_f32_16x16x32_bf16 v[20:23], v[148:151], v[180:183], v[20:23]
	v_mfma_f32_16x16x32_bf16 v[16:19], v[156:159], v[180:183], v[16:19]
	v_mfma_f32_16x16x32_bf16 v[4:7], v[148:151], v[222:225], v[4:7]
	v_mfma_f32_16x16x32_bf16 v[0:3], v[156:159], v[222:225], v[0:3]
	s_barrier
; #define PG8_STAGE(bufoff, gbase, voff) do { _Pragma("unroll") for (int _i = 0; _i < 2; ++_i) \
;         __builtin_amdgcn_global_load_lds((const unsigned*)((const char*)(gbase) + (voff)[_i]), (PG8_LAS unsigned*)(lds + (bufoff) + ldsw + _i * 8192), 16, 0, 0); } while (0)
; #define PG8_LDA(dst, b, h) do { _Pragma("unroll") for (int m = 0; m < 4; ++m) _Pragma("unroll") for (int k = 0; k < 2; ++k) dst[m][k] = *(const PG8_LAS bf16x8*)(lds + PG8_SA(b, h) + aoff + m * 2048 + k * 1024); } while (0)
; #define PG8_LDB(dst, b, h) do { _Pragma("unroll") for (int n = 0; n < 2; ++n) _Pragma("unroll") for (int k = 0; k < 2; ++k) dst[n][k] = *(const PG8_LAS bf16x8*)(lds + PG8_SB(b, h) + boff + n * 2048 + k * 1024); } while (0)
; #define PG8_MMA(ai, bj, At, Bt) do { __builtin_amdgcn_s_setprio(1); _Pragma("unroll") for (int m = 0; m < 4; ++m) _Pragma("unroll") for (int n = 0; n < 2; ++n) _Pragma("unroll") for (int k = 0; k < 2; ++k) \
;         acc[ai][bj][m][n] = __builtin_amdgcn_mfma_f32_16x16x32_bf16(Bt[n][k], At[m][k], acc[ai][bj][m][n], 0, 0, 0); __builtin_amdgcn_s_setprio(0); } while (0)
; #define PG8_WAIT_V(n) asm volatile("s_waitcnt vmcnt(" #n ")" ::: "memory")
; #define PG8_WAIT_L(n) asm volatile("s_waitcnt lgkmcnt(" #n ")" ::: "memory")
; #define PG8_BAR __builtin_amdgcn_s_barrier()
; #define PG8_SCHED __builtin_amdgcn_sched_barrier(0)
; template <class Epi>
; __device__ __forceinline__ void gemm_phase(PG8_LAS unsigned char* lds, PG8_LAS unsigned char* xl, const Gemm g, const Sched& S, const Epi& E, const int wid) {
;     ...
;             PG8_LDB(B0, 1, 0); PG8_LDB(B1, 1, 1); PG8_SCHED; PG8_LDA(At, 1, 0); PG8_STAGE(PG8_SA(0, 1), a2 + hstepA, voffA);
;             PG8_WAIT_V(8); PG8_WAIT_L(0); PG8_BAR; if (do0) { PG8_MMA(0, 0, At, B0); PG8_MMA(0, 1, At, B1); } PG8_BAR; PG8_SCHED;
;             PG8_LDA(At, 1, 1); PG8_STAGE(PG8_SB(1, 0), b3, voffB); PG8_STAGE(PG8_SB(1, 1), b3 + hstepB, voffB); PG8_STAGE(PG8_SA(1, 0), a3, voffA);
;             PG8_WAIT_V(8); PG8_WAIT_L(0); PG8_BAR; if (do1) { PG8_MMA(1, 0, At, B0); PG8_MMA(1, 1, At, B1); } PG8_BAR; PG8_SCHED;
;         }
	s_setprio 0
	s_add_i32 s4, 0, 0x18000
	s_add_i32 s5, 0, 0x1c000
	v_add_u32_e32 v136, s4, v195
	v_add_u32_e32 v156, s5, v195
	ds_read_b128 v[120:123], v136
	ds_read_b128 v[124:127], v136 offset:1024
	ds_read_b128 v[128:131], v136 offset:2048
	ds_read_b128 v[136:139], v136 offset:3072
	ds_read_b128 v[144:147], v156
	ds_read_b128 v[148:151], v156 offset:1024
	ds_read_b128 v[152:155], v156 offset:2048
	ds_read_b128 v[156:159], v156 offset:3072
	s_add_u32 s100, s10, 0x160000
	s_addc_u32 s101, s11, 0
	s_mov_b32 m0, s53
	ds_read_b128 v[160:163], v220 offset:32768
	ds_read_b128 v[164:167], v220 offset:33792
	ds_read_b128 v[168:171], v220 offset:34816
	ds_read_b128 v[172:175], v220 offset:35840
	ds_read_b128 v[176:179], v220 offset:36864
	ds_read_b128 v[180:183], v220 offset:37888
	ds_read_b128 v[184:187], v220 offset:38912
	ds_read_b128 v[222:225], v220 offset:39936
	global_load_lds_dwordx4 v188, s[100:101]
	s_mov_b32 m0, s56
	s_nop 0
	global_load_lds_dwordx4 v210, s[100:101]
	s_waitcnt vmcnt(8)
	s_waitcnt lgkmcnt(0)
	s_setprio 1
	s_barrier
	v_mfma_f32_16x16x32_bf16 v[140:143], v[120:123], v[160:163], v[140:143]
	v_mfma_f32_16x16x32_bf16 v[132:135], v[128:131], v[160:163], v[132:135]
	v_mfma_f32_16x16x32_bf16 v[108:111], v[120:123], v[168:171], v[108:111]
	v_mfma_f32_16x16x32_bf16 v[104:107], v[128:131], v[168:171], v[104:107]
	v_mfma_f32_16x16x32_bf16 v[92:95], v[120:123], v[176:179], v[92:95]
	v_mfma_f32_16x16x32_bf16 v[88:91], v[128:131], v[176:179], v[88:91]
	v_mfma_f32_16x16x32_bf16 v[76:79], v[120:123], v[184:187], v[76:79]
	v_mfma_f32_16x16x32_bf16 v[72:75], v[128:131], v[184:187], v[72:75]
	v_mfma_f32_16x16x32_bf16 v[140:143], v[124:127], v[164:167], v[140:143]
	v_mfma_f32_16x16x32_bf16 v[132:135], v[136:139], v[164:167], v[132:135]
	v_mfma_f32_16x16x32_bf16 v[108:111], v[124:127], v[172:175], v[108:111]
	v_mfma_f32_16x16x32_bf16 v[104:107], v[136:139], v[172:175], v[104:107]
	v_mfma_f32_16x16x32_bf16 v[92:95], v[124:127], v[180:183], v[92:95]
	v_mfma_f32_16x16x32_bf16 v[88:91], v[136:139], v[180:183], v[88:91]
	v_mfma_f32_16x16x32_bf16 v[76:79], v[124:127], v[222:225], v[76:79]
	v_mfma_f32_16x16x32_bf16 v[72:75], v[136:139], v[222:225], v[72:75]
	s_setprio 0
	s_setprio 1
	v_mfma_f32_16x16x32_bf16 v[116:119], v[144:147], v[160:163], v[116:119]
	v_mfma_f32_16x16x32_bf16 v[112:115], v[152:155], v[160:163], v[112:115]
	v_mfma_f32_16x16x32_bf16 v[100:103], v[144:147], v[168:171], v[100:103]
	v_mfma_f32_16x16x32_bf16 v[96:99], v[152:155], v[168:171], v[96:99]
	v_mfma_f32_16x16x32_bf16 v[84:87], v[144:147], v[176:179], v[84:87]
	v_mfma_f32_16x16x32_bf16 v[80:83], v[152:155], v[176:179], v[80:83]
	v_mfma_f32_16x16x32_bf16 v[68:71], v[144:147], v[184:187], v[68:71]
	v_mfma_f32_16x16x32_bf16 v[64:67], v[152:155], v[184:187], v[64:67]
	v_mfma_f32_16x16x32_bf16 v[116:119], v[148:151], v[164:167], v[116:119]
	v_mfma_f32_16x16x32_bf16 v[112:115], v[156:159], v[164:167], v[112:115]
	v_mfma_f32_16x16x32_bf16 v[100:103], v[148:151], v[172:175], v[100:103]
	v_mfma_f32_16x16x32_bf16 v[96:99], v[156:159], v[172:175], v[96:99]
	v_mfma_f32_16x16x32_bf16 v[84:87], v[148:151], v[180:183], v[84:87]
	v_mfma_f32_16x16x32_bf16 v[80:83], v[156:159], v[180:183], v[80:83]
	v_mfma_f32_16x16x32_bf16 v[68:71], v[148:151], v[222:225], v[68:71]
	v_mfma_f32_16x16x32_bf16 v[64:67], v[156:159], v[222:225], v[64:67]
	s_barrier
	s_setprio 0
	s_add_i32 s4, s4, s29
	s_mov_b32 m0, s4
	ds_read_b128 v[160:163], v220 offset:49152
	ds_read_b128 v[164:167], v220 offset:50176
	ds_read_b128 v[168:171], v220 offset:51200
	ds_read_b128 v[172:175], v220 offset:52224
	ds_read_b128 v[176:179], v220 offset:53248
	ds_read_b128 v[180:183], v220 offset:54272
	ds_read_b128 v[184:187], v220 offset:55296
	ds_read_b128 v[222:225], v220 offset:56320
	global_load_lds_dwordx4 v205, s[40:41]
	s_add_i32 m0, s4, 0x2000
	s_add_u32 s100, s40, 0x160080
	global_load_lds_dwordx4 v219, s[40:41]
	s_addc_u32 s101, s41, 0
	s_add_i32 s4, s5, s29
	s_mov_b32 m0, s4
	s_nop 0
	global_load_lds_dwordx4 v190, s[100:101]
	s_add_i32 m0, s4, 0x2000
	s_nop 0
	global_load_lds_dwordx4 v212, s[100:101]
	s_mov_b32 m0, s61
	s_nop 0
	global_load_lds_dwordx4 v204, s[10:11]
	s_mov_b32 m0, s62
	s_nop 0
	global_load_lds_dwordx4 v218, s[10:11]
	s_waitcnt vmcnt(8)
	s_waitcnt lgkmcnt(0)
	s_setprio 1
	s_barrier
	v_mfma_f32_16x16x32_bf16 v[60:63], v[120:123], v[160:163], v[60:63]
	v_mfma_f32_16x16x32_bf16 v[56:59], v[128:131], v[160:163], v[56:59]
	v_mfma_f32_16x16x32_bf16 v[44:47], v[120:123], v[168:171], v[44:47]
	v_mfma_f32_16x16x32_bf16 v[40:43], v[128:131], v[168:171], v[40:43]
	v_mfma_f32_16x16x32_bf16 v[28:31], v[120:123], v[176:179], v[28:31]
	v_mfma_f32_16x16x32_bf16 v[24:27], v[128:131], v[176:179], v[24:27]
	v_mfma_f32_16x16x32_bf16 v[12:15], v[120:123], v[184:187], v[12:15]
	v_mfma_f32_16x16x32_bf16 v[8:11], v[128:131], v[184:187], v[8:11]
	v_mfma_f32_16x16x32_bf16 v[60:63], v[124:127], v[164:167], v[60:63]
	v_mfma_f32_16x16x32_bf16 v[56:59], v[136:139], v[164:167], v[56:59]
	v_mfma_f32_16x16x32_bf16 v[44:47], v[124:127], v[172:175], v[44:47]
	v_mfma_f32_16x16x32_bf16 v[40:43], v[136:139], v[172:175], v[40:43]
	v_mfma_f32_16x16x32_bf16 v[28:31], v[124:127], v[180:183], v[28:31]
	v_mfma_f32_16x16x32_bf16 v[24:27], v[136:139], v[180:183], v[24:27]
	v_mfma_f32_16x16x32_bf16 v[12:15], v[124:127], v[222:225], v[12:15]
	v_mfma_f32_16x16x32_bf16 v[8:11], v[136:139], v[222:225], v[8:11]
	s_setprio 0
	s_setprio 1
	v_mfma_f32_16x16x32_bf16 v[52:55], v[144:147], v[160:163], v[52:55]
	v_mfma_f32_16x16x32_bf16 v[48:51], v[152:155], v[160:163], v[48:51]
	v_mfma_f32_16x16x32_bf16 v[36:39], v[144:147], v[168:171], v[36:39]
	v_mfma_f32_16x16x32_bf16 v[32:35], v[152:155], v[168:171], v[32:35]
	v_mfma_f32_16x16x32_bf16 v[20:23], v[144:147], v[176:179], v[20:23]
	v_mfma_f32_16x16x32_bf16 v[16:19], v[152:155], v[176:179], v[16:19]
	v_mfma_f32_16x16x32_bf16 v[4:7], v[144:147], v[184:187], v[4:7]
	v_mfma_f32_16x16x32_bf16 v[0:3], v[152:155], v[184:187], v[0:3]
	v_mfma_f32_16x16x32_bf16 v[52:55], v[148:151], v[164:167], v[52:55]
	v_mfma_f32_16x16x32_bf16 v[48:51], v[156:159], v[164:167], v[48:51]
	v_mfma_f32_16x16x32_bf16 v[36:39], v[148:151], v[172:175], v[36:39]
	v_mfma_f32_16x16x32_bf16 v[32:35], v[156:159], v[172:175], v[32:35]
	v_mfma_f32_16x16x32_bf16 v[20:23], v[148:151], v[180:183], v[20:23]
	v_mfma_f32_16x16x32_bf16 v[16:19], v[156:159], v[180:183], v[16:19]
	v_mfma_f32_16x16x32_bf16 v[4:7], v[148:151], v[222:225], v[4:7]
	v_mfma_f32_16x16x32_bf16 v[0:3], v[156:159], v[222:225], v[0:3]
	s_barrier
	s_setprio 0
	s_add_i32 s9, s9, 2
	s_add_u32 s36, s36, 0x100
	s_addc_u32 s37, s37, 0
	s_add_u32 s1, s1, 0x100
	s_addc_u32 s8, s8, 0
	s_cmpk_gt_u32 s9, 0x55
	s_cbranch_scc0 .LBB0_1304
	s_mov_b32 s100, 0
	s_and_b64 vcc, exec, s[14:15]
	s_cbranch_vccz .LBB0_1307
	s_barrier
